# stack: GEMM M0 folding + s_xor stage toggles + dead LDS-offset captures removed from tile prologue; RWKV step loop with row-paired state registers
# speedup vs baseline: 1.0040x; 1.0040x over previous
.LBB0_258:
	s_mul_hi_i32 s4, s44, 0x2aaaaaab
	s_lshr_b32 s5, s4, 31
	s_ashr_i32 s4, s4, 1
	s_add_i32 s4, s4, s5
	s_mul_i32 s5, s4, -12
	s_add_i32 s5, s5, s44
	s_lshl_b32 s6, s5, 7
	v_add_u32_e32 v0, s6, v112
	v_ashrrev_i32_e32 v1, 31, v0
	v_add_u32_e32 v2, 0x4000, v113
	v_lshlrev_b64 v[0:1], 11, v[0:1]
	v_readfirstlane_b32 s5, v2
	s_lshl_b32 s30, s4, 7
	v_lshl_add_u64 v[0:1], v[66:67], 0, v[0:1]
	s_mov_b32 m0, s5
	v_readfirstlane_b32 s5, v113
	global_load_lds_dwordx4 v[0:1], off
	v_add_u32_e32 v0, s30, v112
	v_ashrrev_i32_e32 v1, 31, v0
	v_lshlrev_b64 v[0:1], 11, v[0:1]
	v_lshl_add_u64 v[2:3], v[72:73], 0, v[0:1]
	s_mov_b32 m0, s5
	v_readfirstlane_b32 s5, v137
	global_load_lds_dwordx4 v[2:3], off
	v_add_u32_e32 v2, s6, v114
	v_ashrrev_i32_e32 v3, 31, v2
	v_lshlrev_b64 v[2:3], 11, v[2:3]
	v_lshl_add_u64 v[2:3], v[68:69], 0, v[2:3]
	s_mov_b32 m0, s5
	v_add_u32_e32 v4, 0x400, v113
	global_load_lds_dwordx4 v[2:3], off
	v_add_u32_e32 v2, s30, v114
	v_ashrrev_i32_e32 v3, 31, v2
	v_lshlrev_b64 v[2:3], 11, v[2:3]
	v_readfirstlane_b32 s5, v4
	v_lshl_add_u64 v[2:3], v[74:75], 0, v[2:3]
	s_mov_b32 m0, s5
	v_readfirstlane_b32 s5, v138
	global_load_lds_dwordx4 v[2:3], off
	v_add_u32_e32 v2, s6, v116
	v_ashrrev_i32_e32 v3, 31, v2
	v_lshlrev_b64 v[2:3], 11, v[2:3]
	v_lshl_add_u64 v[2:3], v[66:67], 0, v[2:3]
	s_mov_b32 m0, s5
	v_add_u32_e32 v4, 0x800, v113
	global_load_lds_dwordx4 v[2:3], off
	v_add_u32_e32 v2, s30, v116
	v_ashrrev_i32_e32 v3, 31, v2
	v_lshlrev_b64 v[2:3], 11, v[2:3]
	v_readfirstlane_b32 s5, v4
	v_lshl_add_u64 v[2:3], v[72:73], 0, v[2:3]
	s_mov_b32 m0, s5
	v_readfirstlane_b32 s5, v139
	global_load_lds_dwordx4 v[2:3], off
	v_add_u32_e32 v2, s6, v118
	v_ashrrev_i32_e32 v3, 31, v2
	v_lshlrev_b64 v[2:3], 11, v[2:3]
	v_lshl_add_u64 v[2:3], v[70:71], 0, v[2:3]
	s_mov_b32 m0, s5
	v_add_u32_e32 v4, 0xc00, v113
	global_load_lds_dwordx4 v[2:3], off
	v_add_u32_e32 v2, s30, v118
	v_ashrrev_i32_e32 v3, 31, v2
	v_lshlrev_b64 v[2:3], 11, v[2:3]
	v_readfirstlane_b32 s5, v4
	v_lshl_add_u64 v[2:3], v[76:77], 0, v[2:3]
	s_mov_b32 m0, s5
	s_mulk_i32 s4, 0x600
	global_load_lds_dwordx4 v[2:3], off
	v_lshl_add_u64 v[98:99], v[84:85], 0, v[0:1]
	v_subrev_u32_e32 v0, s4, v129
	v_ashrrev_i32_e32 v1, 31, v0
	v_lshlrev_b64 v[0:1], 11, v[0:1]
	v_lshl_add_u64 v[100:101], v[86:87], 0, v[0:1]
	v_add_u32_e32 v0, s30, v130
	v_ashrrev_i32_e32 v1, 31, v0
	v_lshlrev_b64 v[0:1], 11, v[0:1]
	v_lshl_add_u64 v[102:103], v[88:89], 0, v[0:1]
	v_subrev_u32_e32 v0, s4, v131
	v_ashrrev_i32_e32 v1, 31, v0
	v_lshlrev_b64 v[0:1], 11, v[0:1]
	v_lshl_add_u64 v[104:105], v[82:83], 0, v[0:1]
	v_add_u32_e32 v0, s30, v132
	v_ashrrev_i32_e32 v1, 31, v0
	v_lshlrev_b64 v[0:1], 11, v[0:1]
	v_lshl_add_u64 v[106:107], v[84:85], 0, v[0:1]
	v_subrev_u32_e32 v0, s4, v133
	v_ashrrev_i32_e32 v1, 31, v0
	v_lshlrev_b64 v[0:1], 11, v[0:1]
	v_subrev_u32_e32 v2, s4, v128
	v_lshl_add_u64 v[108:109], v[90:91], 0, v[0:1]
	v_add_u32_e32 v0, s30, v134
	v_ashrrev_i32_e32 v3, 31, v2
	v_ashrrev_i32_e32 v1, 31, v0
	v_lshlrev_b64 v[2:3], 11, v[2:3]
	v_lshlrev_b64 v[0:1], 11, v[0:1]
	v_lshl_add_u64 v[96:97], v[82:83], 0, v[2:3]
	v_lshl_add_u64 v[110:111], v[92:93], 0, v[0:1]
	s_mov_b64 s[4:5], 0
	s_mov_b32 s7, 0
	v_mov_b32_e32 v0, v65
	v_mov_b32_e32 v1, v65
	v_mov_b32_e32 v2, v65
	v_mov_b32_e32 v3, v65
	v_mov_b32_e32 v4, v65
	v_mov_b32_e32 v5, v65
	v_mov_b32_e32 v6, v65
	v_mov_b32_e32 v7, v65
	v_mov_b32_e32 v8, v65
	v_mov_b32_e32 v9, v65
	v_mov_b32_e32 v10, v65
	v_mov_b32_e32 v11, v65
	v_mov_b32_e32 v12, v65
	v_mov_b32_e32 v13, v65
	v_mov_b32_e32 v14, v65
	v_mov_b32_e32 v15, v65
	v_mov_b32_e32 v16, v65
	v_mov_b32_e32 v17, v65
	v_mov_b32_e32 v18, v65
	v_mov_b32_e32 v19, v65
	v_mov_b32_e32 v20, v65
	v_mov_b32_e32 v21, v65
	v_mov_b32_e32 v22, v65
	v_mov_b32_e32 v23, v65
	v_mov_b32_e32 v24, v65
	v_mov_b32_e32 v25, v65
	v_mov_b32_e32 v26, v65
	v_mov_b32_e32 v27, v65
	v_mov_b32_e32 v28, v65
	v_mov_b32_e32 v29, v65
	v_mov_b32_e32 v30, v65
	v_mov_b32_e32 v31, v65
	v_mov_b32_e32 v32, v65
	v_mov_b32_e32 v33, v65
	v_mov_b32_e32 v34, v65
	v_mov_b32_e32 v35, v65
	v_mov_b32_e32 v36, v65
	v_mov_b32_e32 v37, v65
	v_mov_b32_e32 v38, v65
	v_mov_b32_e32 v39, v65
	v_mov_b32_e32 v40, v65
	v_mov_b32_e32 v41, v65
	v_mov_b32_e32 v42, v65
	v_mov_b32_e32 v43, v65
	v_mov_b32_e32 v44, v65
	v_mov_b32_e32 v45, v65
	v_mov_b32_e32 v46, v65
	v_mov_b32_e32 v47, v65
	v_mov_b32_e32 v48, v65
	v_mov_b32_e32 v49, v65
	v_mov_b32_e32 v50, v65
	v_mov_b32_e32 v51, v65
	v_mov_b32_e32 v52, v65
	v_mov_b32_e32 v53, v65
	v_mov_b32_e32 v54, v65
	v_mov_b32_e32 v55, v65
	v_mov_b32_e32 v56, v65
	v_mov_b32_e32 v57, v65
	v_mov_b32_e32 v58, v65
	v_mov_b32_e32 v59, v65
	v_mov_b32_e32 v60, v65
	v_mov_b32_e32 v61, v65
	v_mov_b32_e32 v62, v65
	v_mov_b32_e32 v63, v65
	s_waitcnt vmcnt(0) lgkmcnt(0)
	s_barrier
	v_add3_u32 v182, 0, v140, v141
	v_add_u32_e32 v183, 0x4000, v182
	s_nop 0
	v_readfirstlane_b32 s82, v183
	s_nop 0
	v_readfirstlane_b32 s83, v182
	v_subrev_u32_e32 v184, s52, v96
	v_subrev_u32_e32 v185, s52, v98
	v_subrev_u32_e32 v186, s52, v100
	v_subrev_u32_e32 v187, s52, v102
	v_subrev_u32_e32 v188, s52, v104
	v_subrev_u32_e32 v189, s52, v106
	v_subrev_u32_e32 v190, s52, v108
	v_subrev_u32_e32 v191, s52, v110
	v_subrev_u32_e32 v187, 0x400, v187
	v_subrev_u32_e32 v186, 0x400, v186
	v_subrev_u32_e32 v189, 0x800, v189
	v_subrev_u32_e32 v188, 0x800, v188
	v_subrev_u32_e32 v191, 0xc00, v191
	v_subrev_u32_e32 v190, 0xc00, v190
	s_and_b32 s9, s7, 0x4000
	s_xor_b32 s8, s9, 0x4000
	s_lshl_b32 s8, s8, 1
	s_add_i32 s8, s8, 32
	s_lshl_b32 s9, s9, 1
	s_add_i32 s9, s9, 32

.LBB0_277:
	s_add_i32 s4, s30, 0xffffff70
	s_cmpk_lt_i32 s30, 0x90
	s_cselect_b32 s5, 8, 4
	v_cvt_f32_ubyte0_e32 v0, s5
	v_rcp_iflag_f32_e32 v0, v0
	s_cselect_b32 s7, 0, 0x400
	s_cselect_b32 s4, s30, s4
	s_cselect_b32 s6, 3, 2
	v_mul_f32_e32 v0, 0x4f7ffffe, v0
	v_cvt_u32_f32_e32 v0, v0
	s_sub_i32 s20, 0, s5
	s_abs_i32 s9, s4
	s_ashr_i32 s8, s4, 31
	v_readfirstlane_b32 s21, v0
	s_mul_i32 s20, s20, s21
	s_mul_hi_u32 s20, s21, s20
	s_add_i32 s21, s21, s20
	s_mul_hi_u32 s20, s9, s21
	s_mul_i32 s21, s20, s5
	s_sub_i32 s9, s9, s21
	s_add_i32 s21, s20, 1
	s_sub_i32 s22, s9, s5
	s_cmp_ge_u32 s9, s5
	s_cselect_b32 s20, s21, s20
	s_cselect_b32 s9, s22, s9
	s_add_i32 s21, s20, 1
	s_cmp_ge_u32 s9, s5
	s_cselect_b32 s5, s21, s20
	s_xor_b32 s5, s5, s8
	s_sub_i32 s5, s5, s8
	s_lshl_b32 s8, s5, s6
	s_sub_i32 s6, s4, s8
	s_lshl_b32 s6, s6, 7
	v_add_u32_e32 v0, s5, v112
	s_add_i32 s6, s6, s7
	v_lshlrev_b32_e32 v143, 7, v0
	v_add_u32_e32 v0, s6, v113
	v_ashrrev_i32_e32 v1, 31, v0
	v_add_u32_e32 v2, 0x4000, v114
	v_lshlrev_b64 v[0:1], 11, v[0:1]
	v_readfirstlane_b32 s5, v2
	v_lshl_add_u64 v[0:1], v[66:67], 0, v[0:1]
	s_mov_b32 m0, s5
	v_readfirstlane_b32 s5, v114
	global_load_lds_dwordx4 v[0:1], off
	v_add_u32_e32 v0, v143, v113
	v_ashrrev_i32_e32 v1, 31, v0
	v_lshlrev_b64 v[0:1], 11, v[0:1]
	v_lshl_add_u64 v[2:3], v[72:73], 0, v[0:1]
	s_mov_b32 m0, s5
	v_readfirstlane_b32 s5, v134
	global_load_lds_dwordx4 v[2:3], off
	v_add_u32_e32 v2, s6, v115
	v_ashrrev_i32_e32 v3, 31, v2
	v_lshlrev_b64 v[2:3], 11, v[2:3]
	v_lshl_add_u64 v[2:3], v[68:69], 0, v[2:3]
	s_mov_b32 m0, s5
	v_add_u32_e32 v4, 0x400, v114
	global_load_lds_dwordx4 v[2:3], off
	v_add_u32_e32 v2, v143, v115
	v_ashrrev_i32_e32 v3, 31, v2
	v_lshlrev_b64 v[2:3], 11, v[2:3]
	v_readfirstlane_b32 s5, v4
	v_lshl_add_u64 v[2:3], v[74:75], 0, v[2:3]
	s_mov_b32 m0, s5
	v_readfirstlane_b32 s5, v135
	global_load_lds_dwordx4 v[2:3], off
	v_add_u32_e32 v2, s6, v117
	v_ashrrev_i32_e32 v3, 31, v2
	v_lshlrev_b64 v[2:3], 11, v[2:3]
	v_lshl_add_u64 v[2:3], v[66:67], 0, v[2:3]
	s_mov_b32 m0, s5
	v_add_u32_e32 v4, 0x800, v114
	global_load_lds_dwordx4 v[2:3], off
	v_add_u32_e32 v2, v143, v117
	v_ashrrev_i32_e32 v3, 31, v2
	v_lshlrev_b64 v[2:3], 11, v[2:3]
	v_readfirstlane_b32 s5, v4
	v_lshl_add_u64 v[2:3], v[72:73], 0, v[2:3]
	s_mov_b32 m0, s5
	v_readfirstlane_b32 s5, v136
	global_load_lds_dwordx4 v[2:3], off
	v_add_u32_e32 v2, s6, v119
	v_ashrrev_i32_e32 v3, 31, v2
	v_lshlrev_b64 v[2:3], 11, v[2:3]
	v_lshl_add_u64 v[2:3], v[70:71], 0, v[2:3]
	s_mov_b32 m0, s5
	v_add_u32_e32 v4, 0xc00, v114
	global_load_lds_dwordx4 v[2:3], off
	v_add_u32_e32 v2, v143, v119
	v_ashrrev_i32_e32 v3, 31, v2
	v_lshlrev_b64 v[2:3], 11, v[2:3]
	v_readfirstlane_b32 s5, v4
	v_lshl_add_u64 v[2:3], v[76:77], 0, v[2:3]
	s_mov_b32 m0, s5
	s_lshl_b32 s4, s4, 7
	global_load_lds_dwordx4 v[2:3], off
	s_add_i32 s4, s4, s7
	s_lshl_b32 s5, s8, 7
	v_lshl_add_u64 v[98:99], v[84:85], 0, v[0:1]
	v_add_u32_e32 v0, s4, v129
	v_subrev_u32_e32 v0, s5, v0
	v_ashrrev_i32_e32 v1, 31, v0
	v_lshlrev_b64 v[0:1], 11, v[0:1]
	v_lshl_add_u64 v[100:101], v[86:87], 0, v[0:1]
	v_add_u32_e32 v0, v129, v143
	v_ashrrev_i32_e32 v1, 31, v0
	v_lshlrev_b64 v[0:1], 11, v[0:1]
	v_lshl_add_u64 v[102:103], v[88:89], 0, v[0:1]
	v_add_u32_e32 v0, s4, v130
	v_subrev_u32_e32 v0, s5, v0
	v_ashrrev_i32_e32 v1, 31, v0
	v_lshlrev_b64 v[0:1], 11, v[0:1]
	v_lshl_add_u64 v[104:105], v[82:83], 0, v[0:1]
	v_add_u32_e32 v0, v130, v143
	v_ashrrev_i32_e32 v1, 31, v0
	v_lshlrev_b64 v[0:1], 11, v[0:1]
	v_lshl_add_u64 v[106:107], v[84:85], 0, v[0:1]
	v_add_u32_e32 v0, s4, v131
	v_subrev_u32_e32 v0, s5, v0
	v_ashrrev_i32_e32 v1, 31, v0
	v_lshlrev_b64 v[0:1], 11, v[0:1]
	v_add_u32_e32 v2, s4, v113
	v_lshl_add_u64 v[108:109], v[90:91], 0, v[0:1]
	v_add_u32_e32 v0, v131, v143
	v_subrev_u32_e32 v2, s5, v2
	v_ashrrev_i32_e32 v1, 31, v0
	v_ashrrev_i32_e32 v3, 31, v2
	v_lshlrev_b64 v[0:1], 11, v[0:1]
	v_lshlrev_b64 v[2:3], 11, v[2:3]
	v_lshl_add_u64 v[110:111], v[92:93], 0, v[0:1]
	v_mov_b32_e32 v0, 0
	v_lshl_add_u64 v[96:97], v[82:83], 0, v[2:3]
	s_mov_b64 s[4:5], 0
	s_mov_b32 s7, 0
	v_mov_b32_e32 v1, v0
	v_mov_b32_e32 v2, v0
	v_mov_b32_e32 v3, v0
	v_mov_b32_e32 v4, v0
	v_mov_b32_e32 v5, v0
	v_mov_b32_e32 v6, v0
	v_mov_b32_e32 v7, v0
	v_mov_b32_e32 v8, v0
	v_mov_b32_e32 v9, v0
	v_mov_b32_e32 v10, v0
	v_mov_b32_e32 v11, v0
	v_mov_b32_e32 v12, v0
	v_mov_b32_e32 v13, v0
	v_mov_b32_e32 v14, v0
	v_mov_b32_e32 v15, v0
	v_mov_b32_e32 v16, v0
	v_mov_b32_e32 v17, v0
	v_mov_b32_e32 v18, v0
	v_mov_b32_e32 v19, v0
	v_mov_b32_e32 v20, v0
	v_mov_b32_e32 v21, v0
	v_mov_b32_e32 v22, v0
	v_mov_b32_e32 v23, v0
	v_mov_b32_e32 v24, v0
	v_mov_b32_e32 v25, v0
	v_mov_b32_e32 v26, v0
	v_mov_b32_e32 v27, v0
	v_mov_b32_e32 v28, v0
	v_mov_b32_e32 v29, v0
	v_mov_b32_e32 v30, v0
	v_mov_b32_e32 v31, v0
	v_mov_b32_e32 v32, v0
	v_mov_b32_e32 v33, v0
	v_mov_b32_e32 v34, v0
	v_mov_b32_e32 v35, v0
	v_mov_b32_e32 v36, v0
	v_mov_b32_e32 v37, v0
	v_mov_b32_e32 v38, v0
	v_mov_b32_e32 v39, v0
	v_mov_b32_e32 v40, v0
	v_mov_b32_e32 v41, v0
	v_mov_b32_e32 v42, v0
	v_mov_b32_e32 v43, v0
	v_mov_b32_e32 v44, v0
	v_mov_b32_e32 v45, v0
	v_mov_b32_e32 v46, v0
	v_mov_b32_e32 v47, v0
	v_mov_b32_e32 v48, v0
	v_mov_b32_e32 v49, v0
	v_mov_b32_e32 v50, v0
	v_mov_b32_e32 v51, v0
	v_mov_b32_e32 v52, v0
	v_mov_b32_e32 v53, v0
	v_mov_b32_e32 v54, v0
	v_mov_b32_e32 v55, v0
	v_mov_b32_e32 v56, v0
	v_mov_b32_e32 v57, v0
	v_mov_b32_e32 v58, v0
	v_mov_b32_e32 v59, v0
	v_mov_b32_e32 v60, v0
	v_mov_b32_e32 v61, v0
	v_mov_b32_e32 v62, v0
	v_mov_b32_e32 v63, v0
	s_waitcnt vmcnt(0) lgkmcnt(0)
	s_barrier
	v_add3_u32 v182, 0, v137, v138
	v_add_u32_e32 v183, 0x4000, v182
	s_nop 0
	v_readfirstlane_b32 s82, v183
	s_nop 0
	v_readfirstlane_b32 s83, v182
	v_subrev_u32_e32 v184, s52, v96
	v_subrev_u32_e32 v185, s52, v98
	v_subrev_u32_e32 v186, s52, v100
	v_subrev_u32_e32 v187, s52, v102
	v_subrev_u32_e32 v188, s52, v104
	v_subrev_u32_e32 v189, s52, v106
	v_subrev_u32_e32 v190, s52, v108
	v_subrev_u32_e32 v191, s52, v110
	v_subrev_u32_e32 v187, 0x400, v187
	v_subrev_u32_e32 v186, 0x400, v186
	v_subrev_u32_e32 v189, 0x800, v189
	v_subrev_u32_e32 v188, 0x800, v188
	v_subrev_u32_e32 v191, 0xc00, v191
	v_subrev_u32_e32 v190, 0xc00, v190
	s_and_b32 s9, s7, 0x4000
	s_xor_b32 s8, s9, 0x4000
	s_lshl_b32 s8, s8, 1
	s_add_i32 s8, s8, 32
	s_lshl_b32 s9, s9, 1
	s_add_i32 s9, s9, 32

.LBB0_422:
	s_ashr_i32 s14, s21, 31
	s_lshr_b32 s14, s14, 29
	s_add_i32 s14, s21, s14
	s_ashr_i32 s14, s14, 3
	s_lshl_b32 s22, s14, 7
	s_lshl_b32 s14, s14, 10
	s_lshl_b32 s15, s21, 7
	s_sub_i32 s23, s15, s14
	v_add_u32_e32 v0, s23, v106
	v_ashrrev_i32_e32 v1, 31, v0
	v_add_u32_e32 v2, 0x4000, v107
	v_lshlrev_b64 v[0:1], 11, v[0:1]
	v_readfirstlane_b32 s15, v2
	v_lshl_add_u64 v[0:1], v[66:67], 0, v[0:1]
	s_mov_b32 m0, s15
	v_readfirstlane_b32 s15, v107
	global_load_lds_dwordx4 v[0:1], off
	v_add_u32_e32 v0, s22, v106
	v_ashrrev_i32_e32 v1, 31, v0
	v_lshlrev_b64 v[0:1], 11, v[0:1]
	v_lshl_add_u64 v[2:3], v[72:73], 0, v[0:1]
	s_mov_b32 m0, s15
	v_readfirstlane_b32 s15, v130
	global_load_lds_dwordx4 v[2:3], off
	v_add_u32_e32 v2, s23, v108
	v_ashrrev_i32_e32 v3, 31, v2
	v_lshlrev_b64 v[2:3], 11, v[2:3]
	v_lshl_add_u64 v[2:3], v[68:69], 0, v[2:3]
	s_mov_b32 m0, s15
	v_add_u32_e32 v4, 0x400, v107
	global_load_lds_dwordx4 v[2:3], off
	v_add_u32_e32 v2, s22, v108
	v_ashrrev_i32_e32 v3, 31, v2
	v_lshlrev_b64 v[2:3], 11, v[2:3]
	v_readfirstlane_b32 s15, v4
	v_lshl_add_u64 v[2:3], v[74:75], 0, v[2:3]
	s_mov_b32 m0, s15
	v_readfirstlane_b32 s15, v131
	global_load_lds_dwordx4 v[2:3], off
	v_add_u32_e32 v2, s23, v110
	v_ashrrev_i32_e32 v3, 31, v2
	v_lshlrev_b64 v[2:3], 11, v[2:3]
	v_lshl_add_u64 v[2:3], v[66:67], 0, v[2:3]
	s_mov_b32 m0, s15
	v_add_u32_e32 v4, 0x800, v107
	global_load_lds_dwordx4 v[2:3], off
	v_add_u32_e32 v2, s22, v110
	v_ashrrev_i32_e32 v3, 31, v2
	v_lshlrev_b64 v[2:3], 11, v[2:3]
	v_readfirstlane_b32 s15, v4
	v_lshl_add_u64 v[2:3], v[72:73], 0, v[2:3]
	s_mov_b32 m0, s15
	v_readfirstlane_b32 s15, v132
	global_load_lds_dwordx4 v[2:3], off
	v_add_u32_e32 v2, s23, v112
	v_ashrrev_i32_e32 v3, 31, v2
	v_lshlrev_b64 v[2:3], 11, v[2:3]
	v_lshl_add_u64 v[2:3], v[70:71], 0, v[2:3]
	s_mov_b32 m0, s15
	v_add_u32_e32 v4, 0xc00, v107
	global_load_lds_dwordx4 v[2:3], off
	v_add_u32_e32 v2, s22, v112
	v_ashrrev_i32_e32 v3, 31, v2
	v_lshlrev_b64 v[2:3], 11, v[2:3]
	v_readfirstlane_b32 s15, v4
	v_lshl_add_u64 v[2:3], v[76:77], 0, v[2:3]
	s_mov_b32 m0, s15
	v_lshl_add_u64 v[92:93], v[80:81], 0, v[0:1]
	global_load_lds_dwordx4 v[2:3], off
	v_subrev_u32_e32 v0, s14, v123
	v_ashrrev_i32_e32 v1, 31, v0
	v_lshlrev_b64 v[0:1], 11, v[0:1]
	v_lshl_add_u64 v[94:95], v[82:83], 0, v[0:1]
	v_add_u32_e32 v0, s22, v124
	v_ashrrev_i32_e32 v1, 31, v0
	v_lshlrev_b64 v[0:1], 11, v[0:1]
	v_lshl_add_u64 v[96:97], v[84:85], 0, v[0:1]
	v_subrev_u32_e32 v0, s14, v125
	v_ashrrev_i32_e32 v1, 31, v0
	v_lshlrev_b64 v[0:1], 11, v[0:1]
	v_lshl_add_u64 v[98:99], v[78:79], 0, v[0:1]
	v_add_u32_e32 v0, s22, v126
	v_ashrrev_i32_e32 v1, 31, v0
	v_lshlrev_b64 v[0:1], 11, v[0:1]
	v_lshl_add_u64 v[100:101], v[80:81], 0, v[0:1]
	v_subrev_u32_e32 v0, s14, v64
	v_ashrrev_i32_e32 v1, 31, v0
	v_lshlrev_b64 v[0:1], 11, v[0:1]
	v_subrev_u32_e32 v2, s14, v122
	v_lshl_add_u64 v[102:103], v[86:87], 0, v[0:1]
	v_add_u32_e32 v0, s22, v127
	v_ashrrev_i32_e32 v3, 31, v2
	v_ashrrev_i32_e32 v1, 31, v0
	v_lshlrev_b64 v[2:3], 11, v[2:3]
	v_lshlrev_b64 v[0:1], 11, v[0:1]
	v_lshl_add_u64 v[90:91], v[78:79], 0, v[2:3]
	v_lshl_add_u64 v[104:105], v[88:89], 0, v[0:1]
	s_mov_b32 s24, 0
	s_mov_b64 s[14:15], 0
	v_mov_b32_e32 v0, 0
	v_mov_b32_e32 v1, v65
	v_mov_b32_e32 v2, v65
	v_mov_b32_e32 v3, v65
	v_mov_b32_e32 v4, 0
	v_mov_b32_e32 v5, v65
	v_mov_b32_e32 v6, v65
	v_mov_b32_e32 v7, v65
	v_mov_b32_e32 v8, 0
	v_mov_b32_e32 v9, v65
	v_mov_b32_e32 v10, v65
	v_mov_b32_e32 v11, v65
	v_mov_b32_e32 v12, 0
	v_mov_b32_e32 v13, v65
	v_mov_b32_e32 v14, v65
	v_mov_b32_e32 v15, v65
	v_mov_b32_e32 v16, 0
	v_mov_b32_e32 v17, v65
	v_mov_b32_e32 v18, v65
	v_mov_b32_e32 v19, v65
	v_mov_b32_e32 v20, 0
	v_mov_b32_e32 v21, v65
	v_mov_b32_e32 v22, v65
	v_mov_b32_e32 v23, v65
	v_mov_b32_e32 v24, 0
	v_mov_b32_e32 v25, v65
	v_mov_b32_e32 v26, v65
	v_mov_b32_e32 v27, v65
	v_mov_b32_e32 v28, 0
	v_mov_b32_e32 v29, v65
	v_mov_b32_e32 v30, v65
	v_mov_b32_e32 v31, v65
	v_mov_b32_e32 v32, 0
	v_mov_b32_e32 v33, v65
	v_mov_b32_e32 v34, v65
	v_mov_b32_e32 v35, v65
	v_mov_b32_e32 v36, 0
	v_mov_b32_e32 v37, v65
	v_mov_b32_e32 v38, v65
	v_mov_b32_e32 v39, v65
	v_mov_b32_e32 v40, 0
	v_mov_b32_e32 v41, v65
	v_mov_b32_e32 v42, v65
	v_mov_b32_e32 v43, v65
	v_mov_b32_e32 v44, 0
	v_mov_b32_e32 v45, v65
	v_mov_b32_e32 v46, v65
	v_mov_b32_e32 v47, v65
	v_mov_b32_e32 v48, 0
	v_mov_b32_e32 v49, v65
	v_mov_b32_e32 v50, v65
	v_mov_b32_e32 v51, v65
	v_mov_b32_e32 v52, 0
	v_mov_b32_e32 v53, v65
	v_mov_b32_e32 v54, v65
	v_mov_b32_e32 v55, v65
	v_mov_b32_e32 v56, 0
	v_mov_b32_e32 v57, v65
	v_mov_b32_e32 v58, v65
	v_mov_b32_e32 v59, v65
	v_mov_b32_e32 v60, 0
	v_mov_b32_e32 v61, v65
	v_mov_b32_e32 v62, v65
	v_mov_b32_e32 v63, v65
	s_waitcnt vmcnt(0) lgkmcnt(0)
	s_barrier
	v_add3_u32 v186, 0, v133, v134
	v_add_u32_e32 v187, 0x4000, v186
	s_nop 0
	v_readfirstlane_b32 s82, v187
	s_nop 0
	v_readfirstlane_b32 s83, v186
	v_subrev_u32_e32 v188, s52, v90
	v_subrev_u32_e32 v189, s52, v92
	v_subrev_u32_e32 v190, s52, v94
	v_subrev_u32_e32 v191, s52, v96
	v_subrev_u32_e32 v192, s52, v98
	v_subrev_u32_e32 v193, s52, v100
	v_subrev_u32_e32 v194, s52, v102
	v_subrev_u32_e32 v195, s52, v104
	v_subrev_u32_e32 v191, 0x400, v191
	v_subrev_u32_e32 v190, 0x400, v190
	v_subrev_u32_e32 v193, 0x800, v193
	v_subrev_u32_e32 v192, 0x800, v192
	v_subrev_u32_e32 v195, 0xc00, v195
	v_subrev_u32_e32 v194, 0xc00, v194
	s_and_b32 s26, s24, 0x4000
	s_xor_b32 s25, s26, 0x4000
	s_lshl_b32 s25, s25, 1
	s_add_i32 s25, s25, 32
	s_lshl_b32 s26, s26, 1
	s_add_i32 s26, s26, 32

.LBB0_431:
	s_ashr_i32 s14, s16, 31
	s_lshr_b32 s14, s14, 29
	s_add_i32 s14, s16, s14
	s_ashr_i32 s14, s14, 3
	s_lshl_b32 s15, s14, 10
	s_lshl_b32 s23, s16, 7
	v_add_u32_e32 v0, s14, v104
	s_sub_i32 s23, s23, s15
	v_lshlrev_b32_e32 v2, 7, v0
	v_add_u32_e32 v0, s23, v105
	v_ashrrev_i32_e32 v1, 31, v0
	v_add_u32_e32 v3, 0x4000, v106
	v_lshlrev_b64 v[0:1], 11, v[0:1]
	v_readfirstlane_b32 s24, v3
	v_lshl_add_u64 v[0:1], v[64:65], 0, v[0:1]
	s_mov_b32 m0, s24
	v_readfirstlane_b32 s24, v106
	global_load_lds_dwordx4 v[0:1], off
	v_add_u32_e32 v0, v2, v105
	v_ashrrev_i32_e32 v1, 31, v0
	v_lshlrev_b64 v[0:1], 11, v[0:1]
	v_lshl_add_u64 v[0:1], v[70:71], 0, v[0:1]
	s_mov_b32 m0, s24
	v_readfirstlane_b32 s24, v131
	global_load_lds_dwordx4 v[0:1], off
	v_add_u32_e32 v0, s23, v107
	v_ashrrev_i32_e32 v1, 31, v0
	v_lshlrev_b64 v[0:1], 11, v[0:1]
	v_lshl_add_u64 v[0:1], v[66:67], 0, v[0:1]
	s_mov_b32 m0, s24
	v_add_u32_e32 v3, 0x400, v106
	global_load_lds_dwordx4 v[0:1], off
	v_add_u32_e32 v0, v2, v107
	v_ashrrev_i32_e32 v1, 31, v0
	v_lshlrev_b64 v[0:1], 11, v[0:1]
	v_readfirstlane_b32 s24, v3
	v_lshl_add_u64 v[0:1], v[72:73], 0, v[0:1]
	s_mov_b32 m0, s24
	v_readfirstlane_b32 s24, v132
	global_load_lds_dwordx4 v[0:1], off
	v_add_u32_e32 v0, s23, v109
	v_ashrrev_i32_e32 v1, 31, v0
	v_lshlrev_b64 v[0:1], 11, v[0:1]
	v_lshl_add_u64 v[0:1], v[64:65], 0, v[0:1]
	s_mov_b32 m0, s24
	v_add_u32_e32 v3, 0x800, v106
	global_load_lds_dwordx4 v[0:1], off
	v_add_u32_e32 v0, v2, v109
	v_ashrrev_i32_e32 v1, 31, v0
	v_lshlrev_b64 v[0:1], 11, v[0:1]
	v_readfirstlane_b32 s24, v3
	v_lshl_add_u64 v[0:1], v[70:71], 0, v[0:1]
	s_mov_b32 m0, s24
	v_readfirstlane_b32 s24, v133
	global_load_lds_dwordx4 v[0:1], off
	v_add_u32_e32 v0, s23, v111
	v_ashrrev_i32_e32 v1, 31, v0
	v_lshlrev_b64 v[0:1], 11, v[0:1]
	v_lshl_add_u64 v[0:1], v[68:69], 0, v[0:1]
	s_mov_b32 m0, s24
	s_mov_b32 s25, 0
	global_load_lds_dwordx4 v[0:1], off
	v_add_u32_e32 v0, v2, v111
	v_ashrrev_i32_e32 v1, 31, v0
	v_add_u32_e32 v2, 0xc00, v106
	v_lshlrev_b64 v[0:1], 11, v[0:1]
	v_readfirstlane_b32 s24, v2
	v_lshl_add_u64 v[0:1], v[74:75], 0, v[0:1]
	s_mov_b32 m0, s24
	s_lshl_b32 s24, s14, 7
	global_load_lds_dwordx4 v[0:1], off
	v_subrev_u32_e32 v0, s15, v121
	v_ashrrev_i32_e32 v1, 31, v0
	v_lshlrev_b64 v[0:1], 11, v[0:1]
	v_lshl_add_u64 v[88:89], v[76:77], 0, v[0:1]
	v_add_u32_e32 v0, s24, v122
	v_ashrrev_i32_e32 v1, 31, v0
	v_lshlrev_b64 v[0:1], 11, v[0:1]
	v_lshl_add_u64 v[90:91], v[78:79], 0, v[0:1]
	v_subrev_u32_e32 v0, s15, v123
	v_ashrrev_i32_e32 v1, 31, v0
	v_lshlrev_b64 v[0:1], 11, v[0:1]
	v_lshl_add_u64 v[92:93], v[80:81], 0, v[0:1]
	v_add_u32_e32 v0, s24, v124
	v_ashrrev_i32_e32 v1, 31, v0
	v_lshlrev_b64 v[0:1], 11, v[0:1]
	v_lshl_add_u64 v[94:95], v[82:83], 0, v[0:1]
	v_subrev_u32_e32 v0, s15, v125
	v_ashrrev_i32_e32 v1, 31, v0
	v_lshlrev_b64 v[0:1], 11, v[0:1]
	v_lshl_add_u64 v[96:97], v[76:77], 0, v[0:1]
	v_add_u32_e32 v0, s24, v126
	v_ashrrev_i32_e32 v1, 31, v0
	v_lshlrev_b64 v[0:1], 11, v[0:1]
	v_lshl_add_u64 v[98:99], v[78:79], 0, v[0:1]
	v_subrev_u32_e32 v0, s15, v127
	v_ashrrev_i32_e32 v1, 31, v0
	v_lshlrev_b64 v[0:1], 11, v[0:1]
	v_lshl_add_u64 v[100:101], v[84:85], 0, v[0:1]
	v_add_u32_e32 v0, s24, v128
	v_ashrrev_i32_e32 v1, 31, v0
	v_lshlrev_b64 v[0:1], 11, v[0:1]
	v_lshl_add_u64 v[102:103], v[86:87], 0, v[0:1]
	v_mov_b32_e32 v0, 0
	s_mov_b64 s[14:15], 0
	v_mov_b32_e32 v1, v0
	v_mov_b32_e32 v2, v0
	v_mov_b32_e32 v3, v0
	v_mov_b32_e32 v4, v0
	v_mov_b32_e32 v5, v0
	v_mov_b32_e32 v6, v0
	v_mov_b32_e32 v7, v0
	v_mov_b32_e32 v8, v0
	v_mov_b32_e32 v9, v0
	v_mov_b32_e32 v10, v0
	v_mov_b32_e32 v11, v0
	v_mov_b32_e32 v12, v0
	v_mov_b32_e32 v13, v0
	v_mov_b32_e32 v14, v0
	v_mov_b32_e32 v15, v0
	v_mov_b32_e32 v16, v0
	v_mov_b32_e32 v17, v0
	v_mov_b32_e32 v18, v0
	v_mov_b32_e32 v19, v0
	v_mov_b32_e32 v20, v0
	v_mov_b32_e32 v21, v0
	v_mov_b32_e32 v22, v0
	v_mov_b32_e32 v23, v0
	v_mov_b32_e32 v24, v0
	v_mov_b32_e32 v25, v0
	v_mov_b32_e32 v26, v0
	v_mov_b32_e32 v27, v0
	v_mov_b32_e32 v28, v0
	v_mov_b32_e32 v29, v0
	v_mov_b32_e32 v30, v0
	v_mov_b32_e32 v31, v0
	v_mov_b32_e32 v32, v0
	v_mov_b32_e32 v33, v0
	v_mov_b32_e32 v34, v0
	v_mov_b32_e32 v35, v0
	v_mov_b32_e32 v36, v0
	v_mov_b32_e32 v37, v0
	v_mov_b32_e32 v38, v0
	v_mov_b32_e32 v39, v0
	v_mov_b32_e32 v40, v0
	v_mov_b32_e32 v41, v0
	v_mov_b32_e32 v42, v0
	v_mov_b32_e32 v43, v0
	v_mov_b32_e32 v44, v0
	v_mov_b32_e32 v45, v0
	v_mov_b32_e32 v46, v0
	v_mov_b32_e32 v47, v0
	v_mov_b32_e32 v48, v0
	v_mov_b32_e32 v49, v0
	v_mov_b32_e32 v50, v0
	v_mov_b32_e32 v51, v0
	v_mov_b32_e32 v52, v0
	v_mov_b32_e32 v53, v0
	v_mov_b32_e32 v54, v0
	v_mov_b32_e32 v55, v0
	v_mov_b32_e32 v56, v0
	v_mov_b32_e32 v57, v0
	v_mov_b32_e32 v58, v0
	v_mov_b32_e32 v59, v0
	v_mov_b32_e32 v60, v0
	v_mov_b32_e32 v61, v0
	v_mov_b32_e32 v62, v0
	v_mov_b32_e32 v63, v0
	s_waitcnt vmcnt(0) lgkmcnt(0)
	s_barrier
	v_add3_u32 v186, 0, v134, v135
	v_add_u32_e32 v187, 0x4000, v186
	s_nop 0
	v_readfirstlane_b32 s82, v187
	s_nop 0
	v_readfirstlane_b32 s83, v186
	v_subrev_u32_e32 v188, s52, v88
	v_subrev_u32_e32 v189, s52, v90
	v_subrev_u32_e32 v190, s52, v92
	v_subrev_u32_e32 v191, s52, v94
	v_subrev_u32_e32 v192, s52, v96
	v_subrev_u32_e32 v193, s52, v98
	v_subrev_u32_e32 v194, s52, v100
	v_subrev_u32_e32 v195, s52, v102
	v_subrev_u32_e32 v191, 0x400, v191
	v_subrev_u32_e32 v190, 0x400, v190
	v_subrev_u32_e32 v193, 0x800, v193
	v_subrev_u32_e32 v192, 0x800, v192
	v_subrev_u32_e32 v195, 0xc00, v195
	v_subrev_u32_e32 v194, 0xc00, v194
	s_and_b32 s27, s25, 0x4000
	s_xor_b32 s26, s27, 0x4000
	s_lshl_b32 s26, s26, 1
	s_add_i32 s26, s26, 32
	s_lshl_b32 s27, s27, 1
	s_add_i32 s27, s27, 32

.LBB0_442:
	s_and_b32 s10, s16, 0x380
	v_add_lshl_u32 v70, v138, s10, 11
	v_lshl_add_u64 v[96:97], v[84:85], 0, v[70:71]
	v_add_lshl_u32 v70, v140, s10, 11
	v_lshl_add_u64 v[98:99], v[88:89], 0, v[70:71]
	v_add_lshl_u32 v70, v142, s10, 11
	s_lshl_b32 s22, s21, 7
	v_lshl_add_u64 v[100:101], v[84:85], 0, v[70:71]
	v_add_lshl_u32 v70, v144, s10, 11
	s_ashr_i32 s10, s21, 3
	s_and_b32 s22, s22, 0x380
	v_add_u32_e32 v2, 0x4000, v133
	v_lshl_add_u64 v[102:103], v[92:93], 0, v[70:71]
	s_add_i32 s11, s10, s15
	v_add_lshl_u32 v70, s22, v132, 11
	v_readfirstlane_b32 s23, v2
	s_lshl_b32 s11, s11, 7
	v_lshl_add_u64 v[0:1], v[72:73], 0, v[70:71]
	s_mov_b32 m0, s23
	v_readfirstlane_b32 s23, v133
	global_load_lds_dwordx4 v[0:1], off
	v_add_u32_e32 v0, s11, v132
	v_ashrrev_i32_e32 v1, 31, v0
	v_lshlrev_b64 v[0:1], 11, v[0:1]
	v_lshl_add_u64 v[0:1], v[78:79], 0, v[0:1]
	s_mov_b32 m0, s23
	v_add_lshl_u32 v70, s22, v119, 11
	v_readfirstlane_b32 s23, v148
	global_load_lds_dwordx4 v[0:1], off
	v_lshl_add_u64 v[0:1], v[74:75], 0, v[70:71]
	s_mov_b32 m0, s23
	v_add_u32_e32 v2, 0x400, v133
	global_load_lds_dwordx4 v[0:1], off
	v_add_u32_e32 v0, s11, v119
	v_ashrrev_i32_e32 v1, 31, v0
	v_lshlrev_b64 v[0:1], 11, v[0:1]
	v_readfirstlane_b32 s23, v2
	v_lshl_add_u64 v[0:1], v[80:81], 0, v[0:1]
	s_mov_b32 m0, s23
	v_add_lshl_u32 v70, s22, v120, 11
	v_readfirstlane_b32 s23, v149
	global_load_lds_dwordx4 v[0:1], off
	v_lshl_add_u64 v[0:1], v[72:73], 0, v[70:71]
	s_mov_b32 m0, s23
	v_add_u32_e32 v2, 0x800, v133
	global_load_lds_dwordx4 v[0:1], off
	v_add_u32_e32 v0, s11, v120
	v_ashrrev_i32_e32 v1, 31, v0
	v_lshlrev_b64 v[0:1], 11, v[0:1]
	v_readfirstlane_b32 s23, v2
	v_lshl_add_u64 v[0:1], v[78:79], 0, v[0:1]
	s_mov_b32 m0, s23
	v_add_lshl_u32 v70, s22, v118, 11
	v_readfirstlane_b32 s23, v150
	global_load_lds_dwordx4 v[0:1], off
	v_lshl_add_u64 v[0:1], v[76:77], 0, v[70:71]
	s_mov_b32 m0, s23
	v_add_u32_e32 v2, 0xc00, v133
	global_load_lds_dwordx4 v[0:1], off
	v_add_u32_e32 v0, s11, v118
	v_ashrrev_i32_e32 v1, 31, v0
	v_lshlrev_b64 v[0:1], 11, v[0:1]
	v_readfirstlane_b32 s11, v2
	v_lshl_add_u64 v[0:1], v[82:83], 0, v[0:1]
	s_mov_b32 m0, s11
	s_lshl_b32 s23, s10, 7
	global_load_lds_dwordx4 v[0:1], off
	v_add_u32_e32 v0, s23, v139
	v_ashrrev_i32_e32 v1, 31, v0
	v_lshlrev_b64 v[0:1], 11, v[0:1]
	v_lshl_add_u64 v[104:105], v[86:87], 0, v[0:1]
	v_add_u32_e32 v0, s23, v141
	v_ashrrev_i32_e32 v1, 31, v0
	v_lshlrev_b64 v[0:1], 11, v[0:1]
	v_lshl_add_u64 v[106:107], v[90:91], 0, v[0:1]
	v_add_u32_e32 v0, s23, v143
	v_ashrrev_i32_e32 v1, 31, v0
	v_lshlrev_b64 v[0:1], 11, v[0:1]
	v_lshl_add_u64 v[108:109], v[86:87], 0, v[0:1]
	v_add_u32_e32 v0, s23, v145
	v_ashrrev_i32_e32 v1, 31, v0
	v_lshlrev_b64 v[0:1], 11, v[0:1]
	v_lshl_add_u64 v[110:111], v[94:95], 0, v[0:1]
	s_mov_b64 s[10:11], 0
	s_mov_b32 s24, 0
	v_mov_b32_e32 v0, 0
	v_mov_b32_e32 v1, v71
	v_mov_b32_e32 v2, v71
	v_mov_b32_e32 v3, v71
	v_mov_b32_e32 v4, 0
	v_mov_b32_e32 v5, v71
	v_mov_b32_e32 v6, v71
	v_mov_b32_e32 v7, v71
	v_mov_b32_e32 v8, 0
	v_mov_b32_e32 v9, v71
	v_mov_b32_e32 v10, v71
	v_mov_b32_e32 v11, v71
	v_mov_b32_e32 v12, 0
	v_mov_b32_e32 v13, v71
	v_mov_b32_e32 v14, v71
	v_mov_b32_e32 v15, v71
	v_mov_b32_e32 v16, 0
	v_mov_b32_e32 v17, v71
	v_mov_b32_e32 v18, v71
	v_mov_b32_e32 v19, v71
	v_mov_b32_e32 v20, 0
	v_mov_b32_e32 v21, v71
	v_mov_b32_e32 v22, v71
	v_mov_b32_e32 v23, v71
	v_mov_b32_e32 v24, 0
	v_mov_b32_e32 v25, v71
	v_mov_b32_e32 v26, v71
	v_mov_b32_e32 v27, v71
	v_mov_b32_e32 v28, 0
	v_mov_b32_e32 v29, v71
	v_mov_b32_e32 v30, v71
	v_mov_b32_e32 v31, v71
	v_mov_b32_e32 v32, 0
	v_mov_b32_e32 v33, v71
	v_mov_b32_e32 v34, v71
	v_mov_b32_e32 v35, v71
	v_mov_b32_e32 v36, 0
	v_mov_b32_e32 v37, v71
	v_mov_b32_e32 v38, v71
	v_mov_b32_e32 v39, v71
	v_mov_b32_e32 v40, 0
	v_mov_b32_e32 v41, v71
	v_mov_b32_e32 v42, v71
	v_mov_b32_e32 v43, v71
	v_mov_b32_e32 v44, 0
	v_mov_b32_e32 v45, v71
	v_mov_b32_e32 v46, v71
	v_mov_b32_e32 v47, v71
	v_mov_b32_e32 v48, 0
	v_mov_b32_e32 v49, v71
	v_mov_b32_e32 v50, v71
	v_mov_b32_e32 v51, v71
	v_mov_b32_e32 v52, 0
	v_mov_b32_e32 v53, v71
	v_mov_b32_e32 v54, v71
	v_mov_b32_e32 v55, v71
	v_mov_b32_e32 v56, 0
	v_mov_b32_e32 v57, v71
	v_mov_b32_e32 v58, v71
	v_mov_b32_e32 v59, v71
	v_mov_b32_e32 v60, 0
	v_mov_b32_e32 v61, v71
	v_mov_b32_e32 v62, v71
	v_mov_b32_e32 v63, v71
	s_waitcnt vmcnt(0) lgkmcnt(0)
	s_barrier
	v_lshlrev_b32_e32 v186, 1, v130
	v_lshlrev_b32_e32 v187, 1, v131
	v_add3_u32 v186, 0, v186, v187
	v_add_u32_e32 v188, 0x4000, v186
	s_nop 0
	v_readfirstlane_b32 s82, v188
	s_nop 0
	v_readfirstlane_b32 s83, v186
	v_subrev_u32_e32 v189, s52, v96
	v_subrev_u32_e32 v190, s52, v104
	v_subrev_u32_e32 v191, s52, v98
	v_subrev_u32_e32 v192, s52, v106
	v_subrev_u32_e32 v193, s52, v100
	v_subrev_u32_e32 v194, s52, v108
	v_subrev_u32_e32 v195, s52, v102
	v_subrev_u32_e32 v196, s52, v110
	v_subrev_u32_e32 v192, 0x400, v192
	v_subrev_u32_e32 v191, 0x400, v191
	v_subrev_u32_e32 v194, 0x800, v194
	v_subrev_u32_e32 v193, 0x800, v193
	v_subrev_u32_e32 v196, 0xc00, v196
	v_subrev_u32_e32 v195, 0xc00, v195
	s_and_b32 s26, s24, 0x4000
	s_xor_b32 s25, s26, 0x4000
	s_lshl_b32 s25, s25, 1
	s_add_i32 s25, s25, 32
	s_lshl_b32 s26, s26, 1
	s_add_i32 s26, s26, 32

.LBB0_604:
	s_ashr_i32 s10, s14, 31
	s_lshr_b32 s10, s10, 27
	s_add_i32 s10, s14, s10
	s_ashr_i32 s10, s10, 5
	s_lshl_b32 s15, s10, 7
	s_lshl_b32 s10, s10, 12
	s_lshl_b32 s11, s14, 7
	s_sub_i32 s16, s11, s10
	v_add_u32_e32 v0, s16, v106
	v_ashrrev_i32_e32 v1, 31, v0
	v_add_u32_e32 v2, 0x4000, v107
	v_lshlrev_b64 v[0:1], 11, v[0:1]
	v_readfirstlane_b32 s11, v2
	v_lshl_add_u64 v[0:1], v[66:67], 0, v[0:1]
	s_mov_b32 m0, s11
	v_readfirstlane_b32 s11, v107
	global_load_lds_dwordx4 v[0:1], off
	v_add_u32_e32 v0, s15, v106
	v_ashrrev_i32_e32 v1, 31, v0
	v_lshlrev_b64 v[0:1], 11, v[0:1]
	v_lshl_add_u64 v[2:3], v[72:73], 0, v[0:1]
	s_mov_b32 m0, s11
	v_readfirstlane_b32 s11, v130
	global_load_lds_dwordx4 v[2:3], off
	v_add_u32_e32 v2, s16, v108
	v_ashrrev_i32_e32 v3, 31, v2
	v_lshlrev_b64 v[2:3], 11, v[2:3]
	v_lshl_add_u64 v[2:3], v[68:69], 0, v[2:3]
	s_mov_b32 m0, s11
	v_add_u32_e32 v4, 0x400, v107
	global_load_lds_dwordx4 v[2:3], off
	v_add_u32_e32 v2, s15, v108
	v_ashrrev_i32_e32 v3, 31, v2
	v_lshlrev_b64 v[2:3], 11, v[2:3]
	v_readfirstlane_b32 s11, v4
	v_lshl_add_u64 v[2:3], v[74:75], 0, v[2:3]
	s_mov_b32 m0, s11
	v_readfirstlane_b32 s11, v131
	global_load_lds_dwordx4 v[2:3], off
	v_add_u32_e32 v2, s16, v110
	v_ashrrev_i32_e32 v3, 31, v2
	v_lshlrev_b64 v[2:3], 11, v[2:3]
	v_lshl_add_u64 v[2:3], v[66:67], 0, v[2:3]
	s_mov_b32 m0, s11
	v_add_u32_e32 v4, 0x800, v107
	global_load_lds_dwordx4 v[2:3], off
	v_add_u32_e32 v2, s15, v110
	v_ashrrev_i32_e32 v3, 31, v2
	v_lshlrev_b64 v[2:3], 11, v[2:3]
	v_readfirstlane_b32 s11, v4
	v_lshl_add_u64 v[2:3], v[72:73], 0, v[2:3]
	s_mov_b32 m0, s11
	v_readfirstlane_b32 s11, v132
	global_load_lds_dwordx4 v[2:3], off
	v_add_u32_e32 v2, s16, v112
	v_ashrrev_i32_e32 v3, 31, v2
	v_lshlrev_b64 v[2:3], 11, v[2:3]
	v_lshl_add_u64 v[2:3], v[70:71], 0, v[2:3]
	s_mov_b32 m0, s11
	v_add_u32_e32 v4, 0xc00, v107
	global_load_lds_dwordx4 v[2:3], off
	v_add_u32_e32 v2, s15, v112
	v_ashrrev_i32_e32 v3, 31, v2
	v_lshlrev_b64 v[2:3], 11, v[2:3]
	v_readfirstlane_b32 s11, v4
	v_lshl_add_u64 v[2:3], v[76:77], 0, v[2:3]
	s_mov_b32 m0, s11
	v_lshl_add_u64 v[92:93], v[80:81], 0, v[0:1]
	global_load_lds_dwordx4 v[2:3], off
	v_subrev_u32_e32 v0, s10, v123
	v_ashrrev_i32_e32 v1, 31, v0
	v_lshlrev_b64 v[0:1], 11, v[0:1]
	v_lshl_add_u64 v[94:95], v[82:83], 0, v[0:1]
	v_add_u32_e32 v0, s15, v124
	v_ashrrev_i32_e32 v1, 31, v0
	v_lshlrev_b64 v[0:1], 11, v[0:1]
	v_lshl_add_u64 v[96:97], v[84:85], 0, v[0:1]
	v_subrev_u32_e32 v0, s10, v125
	v_ashrrev_i32_e32 v1, 31, v0
	v_lshlrev_b64 v[0:1], 11, v[0:1]
	v_lshl_add_u64 v[98:99], v[78:79], 0, v[0:1]
	v_add_u32_e32 v0, s15, v126
	v_ashrrev_i32_e32 v1, 31, v0
	v_lshlrev_b64 v[0:1], 11, v[0:1]
	v_lshl_add_u64 v[100:101], v[80:81], 0, v[0:1]
	v_subrev_u32_e32 v0, s10, v64
	v_ashrrev_i32_e32 v1, 31, v0
	v_lshlrev_b64 v[0:1], 11, v[0:1]
	v_subrev_u32_e32 v2, s10, v122
	v_lshl_add_u64 v[102:103], v[86:87], 0, v[0:1]
	v_add_u32_e32 v0, s15, v127
	v_ashrrev_i32_e32 v3, 31, v2
	v_ashrrev_i32_e32 v1, 31, v0
	v_lshlrev_b64 v[2:3], 11, v[2:3]
	v_lshlrev_b64 v[0:1], 11, v[0:1]
	v_lshl_add_u64 v[90:91], v[78:79], 0, v[2:3]
	v_lshl_add_u64 v[104:105], v[88:89], 0, v[0:1]
	s_mov_b64 s[10:11], 0
	s_mov_b32 s17, 0
	v_mov_b32_e32 v0, 0
	v_mov_b32_e32 v1, v65
	v_mov_b32_e32 v2, v65
	v_mov_b32_e32 v3, v65
	v_mov_b32_e32 v4, 0
	v_mov_b32_e32 v5, v65
	v_mov_b32_e32 v6, v65
	v_mov_b32_e32 v7, v65
	v_mov_b32_e32 v8, 0
	v_mov_b32_e32 v9, v65
	v_mov_b32_e32 v10, v65
	v_mov_b32_e32 v11, v65
	v_mov_b32_e32 v12, 0
	v_mov_b32_e32 v13, v65
	v_mov_b32_e32 v14, v65
	v_mov_b32_e32 v15, v65
	v_mov_b32_e32 v16, 0
	v_mov_b32_e32 v17, v65
	v_mov_b32_e32 v18, v65
	v_mov_b32_e32 v19, v65
	v_mov_b32_e32 v20, 0
	v_mov_b32_e32 v21, v65
	v_mov_b32_e32 v22, v65
	v_mov_b32_e32 v23, v65
	v_mov_b32_e32 v24, 0
	v_mov_b32_e32 v25, v65
	v_mov_b32_e32 v26, v65
	v_mov_b32_e32 v27, v65
	v_mov_b32_e32 v28, 0
	v_mov_b32_e32 v29, v65
	v_mov_b32_e32 v30, v65
	v_mov_b32_e32 v31, v65
	v_mov_b32_e32 v32, 0
	v_mov_b32_e32 v33, v65
	v_mov_b32_e32 v34, v65
	v_mov_b32_e32 v35, v65
	v_mov_b32_e32 v36, 0
	v_mov_b32_e32 v37, v65
	v_mov_b32_e32 v38, v65
	v_mov_b32_e32 v39, v65
	v_mov_b32_e32 v40, 0
	v_mov_b32_e32 v41, v65
	v_mov_b32_e32 v42, v65
	v_mov_b32_e32 v43, v65
	v_mov_b32_e32 v44, 0
	v_mov_b32_e32 v45, v65
	v_mov_b32_e32 v46, v65
	v_mov_b32_e32 v47, v65
	v_mov_b32_e32 v48, 0
	v_mov_b32_e32 v49, v65
	v_mov_b32_e32 v50, v65
	v_mov_b32_e32 v51, v65
	v_mov_b32_e32 v52, 0
	v_mov_b32_e32 v53, v65
	v_mov_b32_e32 v54, v65
	v_mov_b32_e32 v55, v65
	v_mov_b32_e32 v56, 0
	v_mov_b32_e32 v57, v65
	v_mov_b32_e32 v58, v65
	v_mov_b32_e32 v59, v65
	v_mov_b32_e32 v60, 0
	v_mov_b32_e32 v61, v65
	v_mov_b32_e32 v62, v65
	v_mov_b32_e32 v63, v65
	s_waitcnt vmcnt(0) lgkmcnt(0)
	s_barrier
	v_add3_u32 v182, 0, v133, v134
	v_add_u32_e32 v183, 0x4000, v182
	s_nop 0
	v_readfirstlane_b32 s82, v183
	s_nop 0
	v_readfirstlane_b32 s83, v182
	v_subrev_u32_e32 v184, s52, v90
	v_subrev_u32_e32 v185, s52, v92
	v_subrev_u32_e32 v186, s52, v94
	v_subrev_u32_e32 v187, s52, v96
	v_subrev_u32_e32 v188, s52, v98
	v_subrev_u32_e32 v189, s52, v100
	v_subrev_u32_e32 v190, s52, v102
	v_subrev_u32_e32 v191, s52, v104
	v_subrev_u32_e32 v187, 0x400, v187
	v_subrev_u32_e32 v186, 0x400, v186
	v_subrev_u32_e32 v189, 0x800, v189
	v_subrev_u32_e32 v188, 0x800, v188
	v_subrev_u32_e32 v191, 0xc00, v191
	v_subrev_u32_e32 v190, 0xc00, v190
	s_and_b32 s19, s17, 0x4000
	s_xor_b32 s18, s19, 0x4000
	s_lshl_b32 s18, s18, 1
	s_add_i32 s18, s18, 32
	s_lshl_b32 s19, s19, 1
	s_add_i32 s19, s19, 32

.LBB0_615:
	s_ashr_i32 s12, s7, 31
	s_lshr_b32 s12, s12, 29
	s_add_i32 s12, s7, s12
	s_ashr_i32 s13, s12, 3
	s_lshl_b32 s14, s13, 10
	s_lshl_b32 s7, s7, 7
	s_sub_i32 s12, s7, s14
	v_add_u32_e32 v0, s13, v104
	s_add_i32 s12, s12, s6
	v_lshlrev_b32_e32 v2, 7, v0
	v_add_u32_e32 v0, s12, v105
	v_ashrrev_i32_e32 v1, 31, v0
	v_add_u32_e32 v3, 0x4000, v106
	v_lshlrev_b64 v[0:1], 11, v[0:1]
	v_readfirstlane_b32 s15, v3
	v_lshl_add_u64 v[0:1], v[64:65], 0, v[0:1]
	s_mov_b32 m0, s15
	v_readfirstlane_b32 s15, v106
	global_load_lds_dwordx4 v[0:1], off
	v_add_u32_e32 v0, v2, v105
	v_ashrrev_i32_e32 v1, 31, v0
	v_lshlrev_b64 v[0:1], 11, v[0:1]
	v_lshl_add_u64 v[0:1], v[70:71], 0, v[0:1]
	s_mov_b32 m0, s15
	v_readfirstlane_b32 s15, v130
	global_load_lds_dwordx4 v[0:1], off
	v_add_u32_e32 v0, s12, v107
	v_ashrrev_i32_e32 v1, 31, v0
	v_lshlrev_b64 v[0:1], 11, v[0:1]
	v_lshl_add_u64 v[0:1], v[66:67], 0, v[0:1]
	s_mov_b32 m0, s15
	v_add_u32_e32 v3, 0x400, v106
	global_load_lds_dwordx4 v[0:1], off
	v_add_u32_e32 v0, v2, v107
	v_ashrrev_i32_e32 v1, 31, v0
	v_lshlrev_b64 v[0:1], 11, v[0:1]
	v_readfirstlane_b32 s15, v3
	v_lshl_add_u64 v[0:1], v[72:73], 0, v[0:1]
	s_mov_b32 m0, s15
	v_readfirstlane_b32 s15, v131
	global_load_lds_dwordx4 v[0:1], off
	v_add_u32_e32 v0, s12, v109
	v_ashrrev_i32_e32 v1, 31, v0
	v_lshlrev_b64 v[0:1], 11, v[0:1]
	v_lshl_add_u64 v[0:1], v[64:65], 0, v[0:1]
	s_mov_b32 m0, s15
	v_add_u32_e32 v3, 0x800, v106
	global_load_lds_dwordx4 v[0:1], off
	v_add_u32_e32 v0, v2, v109
	v_ashrrev_i32_e32 v1, 31, v0
	v_lshlrev_b64 v[0:1], 11, v[0:1]
	v_readfirstlane_b32 s15, v3
	v_lshl_add_u64 v[0:1], v[70:71], 0, v[0:1]
	s_mov_b32 m0, s15
	v_readfirstlane_b32 s15, v132
	global_load_lds_dwordx4 v[0:1], off
	v_add_u32_e32 v0, s12, v111
	v_ashrrev_i32_e32 v1, 31, v0
	v_lshlrev_b64 v[0:1], 11, v[0:1]
	v_lshl_add_u64 v[0:1], v[68:69], 0, v[0:1]
	s_mov_b32 m0, s15
	s_add_i32 s7, s7, s6
	global_load_lds_dwordx4 v[0:1], off
	v_add_u32_e32 v0, v2, v111
	v_ashrrev_i32_e32 v1, 31, v0
	v_add_u32_e32 v2, 0xc00, v106
	v_lshlrev_b64 v[0:1], 11, v[0:1]
	v_readfirstlane_b32 s15, v2
	v_lshl_add_u64 v[0:1], v[74:75], 0, v[0:1]
	s_mov_b32 m0, s15
	s_lshl_b32 s13, s13, 7
	global_load_lds_dwordx4 v[0:1], off
	v_add_u32_e32 v0, s7, v105
	v_subrev_u32_e32 v0, s14, v0
	v_ashrrev_i32_e32 v1, 31, v0
	v_lshlrev_b64 v[0:1], 11, v[0:1]
	v_lshl_add_u64 v[88:89], v[76:77], 0, v[0:1]
	v_add_u32_e32 v0, s13, v121
	v_ashrrev_i32_e32 v1, 31, v0
	v_lshlrev_b64 v[0:1], 11, v[0:1]
	v_lshl_add_u64 v[90:91], v[78:79], 0, v[0:1]
	v_add_u32_e32 v0, s7, v122
	v_subrev_u32_e32 v0, s14, v0
	v_ashrrev_i32_e32 v1, 31, v0
	v_lshlrev_b64 v[0:1], 11, v[0:1]
	v_lshl_add_u64 v[92:93], v[80:81], 0, v[0:1]
	v_add_u32_e32 v0, s13, v123
	v_ashrrev_i32_e32 v1, 31, v0
	v_lshlrev_b64 v[0:1], 11, v[0:1]
	v_lshl_add_u64 v[94:95], v[82:83], 0, v[0:1]
	v_add_u32_e32 v0, s7, v124
	v_subrev_u32_e32 v0, s14, v0
	v_ashrrev_i32_e32 v1, 31, v0
	v_lshlrev_b64 v[0:1], 11, v[0:1]
	v_lshl_add_u64 v[96:97], v[76:77], 0, v[0:1]
	v_add_u32_e32 v0, s13, v125
	v_ashrrev_i32_e32 v1, 31, v0
	v_lshlrev_b64 v[0:1], 11, v[0:1]
	v_lshl_add_u64 v[98:99], v[78:79], 0, v[0:1]
	v_add_u32_e32 v0, s7, v126
	v_subrev_u32_e32 v0, s14, v0
	v_ashrrev_i32_e32 v1, 31, v0
	v_lshlrev_b64 v[0:1], 11, v[0:1]
	v_lshl_add_u64 v[100:101], v[84:85], 0, v[0:1]
	v_add_u32_e32 v0, s13, v127
	v_ashrrev_i32_e32 v1, 31, v0
	v_lshlrev_b64 v[0:1], 11, v[0:1]
	v_lshl_add_u64 v[102:103], v[86:87], 0, v[0:1]
	v_mov_b32_e32 v0, 0
	s_mov_b32 s14, 0
	s_mov_b64 s[6:7], 0
	v_mov_b32_e32 v1, v0
	v_mov_b32_e32 v2, v0
	v_mov_b32_e32 v3, v0
	v_mov_b32_e32 v4, v0
	v_mov_b32_e32 v5, v0
	v_mov_b32_e32 v6, v0
	v_mov_b32_e32 v7, v0
	v_mov_b32_e32 v8, v0
	v_mov_b32_e32 v9, v0
	v_mov_b32_e32 v10, v0
	v_mov_b32_e32 v11, v0
	v_mov_b32_e32 v12, v0
	v_mov_b32_e32 v13, v0
	v_mov_b32_e32 v14, v0
	v_mov_b32_e32 v15, v0
	v_mov_b32_e32 v16, v0
	v_mov_b32_e32 v17, v0
	v_mov_b32_e32 v18, v0
	v_mov_b32_e32 v19, v0
	v_mov_b32_e32 v20, v0
	v_mov_b32_e32 v21, v0
	v_mov_b32_e32 v22, v0
	v_mov_b32_e32 v23, v0
	v_mov_b32_e32 v24, v0
	v_mov_b32_e32 v25, v0
	v_mov_b32_e32 v26, v0
	v_mov_b32_e32 v27, v0
	v_mov_b32_e32 v28, v0
	v_mov_b32_e32 v29, v0
	v_mov_b32_e32 v30, v0
	v_mov_b32_e32 v31, v0
	v_mov_b32_e32 v32, v0
	v_mov_b32_e32 v33, v0
	v_mov_b32_e32 v34, v0
	v_mov_b32_e32 v35, v0
	v_mov_b32_e32 v36, v0
	v_mov_b32_e32 v37, v0
	v_mov_b32_e32 v38, v0
	v_mov_b32_e32 v39, v0
	v_mov_b32_e32 v40, v0
	v_mov_b32_e32 v41, v0
	v_mov_b32_e32 v42, v0
	v_mov_b32_e32 v43, v0
	v_mov_b32_e32 v44, v0
	v_mov_b32_e32 v45, v0
	v_mov_b32_e32 v46, v0
	v_mov_b32_e32 v47, v0
	v_mov_b32_e32 v48, v0
	v_mov_b32_e32 v49, v0
	v_mov_b32_e32 v50, v0
	v_mov_b32_e32 v51, v0
	v_mov_b32_e32 v52, v0
	v_mov_b32_e32 v53, v0
	v_mov_b32_e32 v54, v0
	v_mov_b32_e32 v55, v0
	v_mov_b32_e32 v56, v0
	v_mov_b32_e32 v57, v0
	v_mov_b32_e32 v58, v0
	v_mov_b32_e32 v59, v0
	v_mov_b32_e32 v60, v0
	v_mov_b32_e32 v61, v0
	v_mov_b32_e32 v62, v0
	v_mov_b32_e32 v63, v0
	s_waitcnt vmcnt(0) lgkmcnt(0)
	s_barrier
	v_add3_u32 v182, 0, v133, v134
	v_add_u32_e32 v183, 0x4000, v182
	s_nop 0
	v_readfirstlane_b32 s82, v183
	s_nop 0
	v_readfirstlane_b32 s83, v182
	v_subrev_u32_e32 v184, s52, v88
	v_subrev_u32_e32 v185, s52, v90
	v_subrev_u32_e32 v186, s52, v92
	v_subrev_u32_e32 v187, s52, v94
	v_subrev_u32_e32 v188, s52, v96
	v_subrev_u32_e32 v189, s52, v98
	v_subrev_u32_e32 v190, s52, v100
	v_subrev_u32_e32 v191, s52, v102
	v_subrev_u32_e32 v187, 0x400, v187
	v_subrev_u32_e32 v186, 0x400, v186
	v_subrev_u32_e32 v189, 0x800, v189
	v_subrev_u32_e32 v188, 0x800, v188
	v_subrev_u32_e32 v191, 0xc00, v191
	v_subrev_u32_e32 v190, 0xc00, v190
	s_and_b32 s16, s14, 0x4000
	s_xor_b32 s15, s16, 0x4000
	s_lshl_b32 s15, s15, 1
	s_add_i32 s15, s15, 32
	s_lshl_b32 s16, s16, 1
	s_add_i32 s16, s16, 32

.LBB0_681:
	s_ashr_i32 s14, s21, 31
	s_lshr_b32 s14, s14, 29
	s_add_i32 s14, s21, s14
	s_ashr_i32 s14, s14, 3
	s_lshl_b32 s22, s14, 7
	s_lshl_b32 s14, s14, 10
	s_lshl_b32 s15, s21, 7
	s_sub_i32 s23, s15, s14
	v_add_u32_e32 v0, s23, v106
	v_ashrrev_i32_e32 v1, 31, v0
	v_add_u32_e32 v2, 0x4000, v107
	v_lshlrev_b64 v[0:1], 13, v[0:1]
	v_readfirstlane_b32 s15, v2
	v_lshl_add_u64 v[0:1], v[66:67], 0, v[0:1]
	s_mov_b32 m0, s15
	v_readfirstlane_b32 s15, v107
	global_load_lds_dwordx4 v[0:1], off
	v_add_u32_e32 v0, s22, v106
	v_ashrrev_i32_e32 v1, 31, v0
	v_lshlrev_b64 v[0:1], 13, v[0:1]
	v_lshl_add_u64 v[2:3], v[72:73], 0, v[0:1]
	s_mov_b32 m0, s15
	v_readfirstlane_b32 s15, v130
	global_load_lds_dwordx4 v[2:3], off
	v_add_u32_e32 v2, s23, v108
	v_ashrrev_i32_e32 v3, 31, v2
	v_lshlrev_b64 v[2:3], 13, v[2:3]
	v_lshl_add_u64 v[2:3], v[68:69], 0, v[2:3]
	s_mov_b32 m0, s15
	v_add_u32_e32 v4, 0x400, v107
	global_load_lds_dwordx4 v[2:3], off
	v_add_u32_e32 v2, s22, v108
	v_ashrrev_i32_e32 v3, 31, v2
	v_lshlrev_b64 v[2:3], 13, v[2:3]
	v_readfirstlane_b32 s15, v4
	v_lshl_add_u64 v[2:3], v[74:75], 0, v[2:3]
	s_mov_b32 m0, s15
	v_readfirstlane_b32 s15, v131
	global_load_lds_dwordx4 v[2:3], off
	v_add_u32_e32 v2, s23, v110
	v_ashrrev_i32_e32 v3, 31, v2
	v_lshlrev_b64 v[2:3], 13, v[2:3]
	v_lshl_add_u64 v[2:3], v[66:67], 0, v[2:3]
	s_mov_b32 m0, s15
	v_add_u32_e32 v4, 0x800, v107
	global_load_lds_dwordx4 v[2:3], off
	v_add_u32_e32 v2, s22, v110
	v_ashrrev_i32_e32 v3, 31, v2
	v_lshlrev_b64 v[2:3], 13, v[2:3]
	v_readfirstlane_b32 s15, v4
	v_lshl_add_u64 v[2:3], v[72:73], 0, v[2:3]
	s_mov_b32 m0, s15
	v_readfirstlane_b32 s15, v132
	global_load_lds_dwordx4 v[2:3], off
	v_add_u32_e32 v2, s23, v112
	v_ashrrev_i32_e32 v3, 31, v2
	v_lshlrev_b64 v[2:3], 13, v[2:3]
	v_lshl_add_u64 v[2:3], v[70:71], 0, v[2:3]
	s_mov_b32 m0, s15
	v_add_u32_e32 v4, 0xc00, v107
	global_load_lds_dwordx4 v[2:3], off
	v_add_u32_e32 v2, s22, v112
	v_ashrrev_i32_e32 v3, 31, v2
	v_lshlrev_b64 v[2:3], 13, v[2:3]
	v_readfirstlane_b32 s15, v4
	v_lshl_add_u64 v[2:3], v[76:77], 0, v[2:3]
	s_mov_b32 m0, s15
	v_lshl_add_u64 v[92:93], v[80:81], 0, v[0:1]
	global_load_lds_dwordx4 v[2:3], off
	v_subrev_u32_e32 v0, s14, v123
	v_ashrrev_i32_e32 v1, 31, v0
	v_lshlrev_b64 v[0:1], 13, v[0:1]
	v_lshl_add_u64 v[94:95], v[82:83], 0, v[0:1]
	v_add_u32_e32 v0, s22, v124
	v_ashrrev_i32_e32 v1, 31, v0
	v_lshlrev_b64 v[0:1], 13, v[0:1]
	v_lshl_add_u64 v[96:97], v[84:85], 0, v[0:1]
	v_subrev_u32_e32 v0, s14, v125
	v_ashrrev_i32_e32 v1, 31, v0
	v_lshlrev_b64 v[0:1], 13, v[0:1]
	v_lshl_add_u64 v[98:99], v[78:79], 0, v[0:1]
	v_add_u32_e32 v0, s22, v126
	v_ashrrev_i32_e32 v1, 31, v0
	v_lshlrev_b64 v[0:1], 13, v[0:1]
	v_lshl_add_u64 v[100:101], v[80:81], 0, v[0:1]
	v_subrev_u32_e32 v0, s14, v64
	v_ashrrev_i32_e32 v1, 31, v0
	v_lshlrev_b64 v[0:1], 13, v[0:1]
	v_subrev_u32_e32 v2, s14, v122
	v_lshl_add_u64 v[102:103], v[86:87], 0, v[0:1]
	v_add_u32_e32 v0, s22, v127
	v_ashrrev_i32_e32 v3, 31, v2
	v_ashrrev_i32_e32 v1, 31, v0
	v_lshlrev_b64 v[2:3], 13, v[2:3]
	v_lshlrev_b64 v[0:1], 13, v[0:1]
	v_lshl_add_u64 v[90:91], v[78:79], 0, v[2:3]
	v_lshl_add_u64 v[104:105], v[88:89], 0, v[0:1]
	s_mov_b32 s24, 0
	s_mov_b64 s[14:15], 0
	v_mov_b32_e32 v0, 0
	v_mov_b32_e32 v1, v65
	v_mov_b32_e32 v2, v65
	v_mov_b32_e32 v3, v65
	v_mov_b32_e32 v4, 0
	v_mov_b32_e32 v5, v65
	v_mov_b32_e32 v6, v65
	v_mov_b32_e32 v7, v65
	v_mov_b32_e32 v8, 0
	v_mov_b32_e32 v9, v65
	v_mov_b32_e32 v10, v65
	v_mov_b32_e32 v11, v65
	v_mov_b32_e32 v12, 0
	v_mov_b32_e32 v13, v65
	v_mov_b32_e32 v14, v65
	v_mov_b32_e32 v15, v65
	v_mov_b32_e32 v16, 0
	v_mov_b32_e32 v17, v65
	v_mov_b32_e32 v18, v65
	v_mov_b32_e32 v19, v65
	v_mov_b32_e32 v20, 0
	v_mov_b32_e32 v21, v65
	v_mov_b32_e32 v22, v65
	v_mov_b32_e32 v23, v65
	v_mov_b32_e32 v24, 0
	v_mov_b32_e32 v25, v65
	v_mov_b32_e32 v26, v65
	v_mov_b32_e32 v27, v65
	v_mov_b32_e32 v28, 0
	v_mov_b32_e32 v29, v65
	v_mov_b32_e32 v30, v65
	v_mov_b32_e32 v31, v65
	v_mov_b32_e32 v32, 0
	v_mov_b32_e32 v33, v65
	v_mov_b32_e32 v34, v65
	v_mov_b32_e32 v35, v65
	v_mov_b32_e32 v36, 0
	v_mov_b32_e32 v37, v65
	v_mov_b32_e32 v38, v65
	v_mov_b32_e32 v39, v65
	v_mov_b32_e32 v40, 0
	v_mov_b32_e32 v41, v65
	v_mov_b32_e32 v42, v65
	v_mov_b32_e32 v43, v65
	v_mov_b32_e32 v44, 0
	v_mov_b32_e32 v45, v65
	v_mov_b32_e32 v46, v65
	v_mov_b32_e32 v47, v65
	v_mov_b32_e32 v48, 0
	v_mov_b32_e32 v49, v65
	v_mov_b32_e32 v50, v65
	v_mov_b32_e32 v51, v65
	v_mov_b32_e32 v52, 0
	v_mov_b32_e32 v53, v65
	v_mov_b32_e32 v54, v65
	v_mov_b32_e32 v55, v65
	v_mov_b32_e32 v56, 0
	v_mov_b32_e32 v57, v65
	v_mov_b32_e32 v58, v65
	v_mov_b32_e32 v59, v65
	v_mov_b32_e32 v60, 0
	v_mov_b32_e32 v61, v65
	v_mov_b32_e32 v62, v65
	v_mov_b32_e32 v63, v65
	s_waitcnt vmcnt(0) lgkmcnt(0)
	s_barrier
	v_add3_u32 v190, 0, v133, v134
	v_add_u32_e32 v191, 0x4000, v190
	s_nop 0
	v_readfirstlane_b32 s82, v191
	s_nop 0
	v_readfirstlane_b32 s83, v190
	v_subrev_u32_e32 v192, s52, v90
	v_subrev_u32_e32 v193, s52, v92
	v_subrev_u32_e32 v194, s52, v94
	v_subrev_u32_e32 v195, s52, v96
	v_subrev_u32_e32 v196, s52, v98
	v_subrev_u32_e32 v197, s52, v100
	v_subrev_u32_e32 v198, s52, v102
	v_subrev_u32_e32 v199, s52, v104
	v_subrev_u32_e32 v195, 0x400, v195
	v_subrev_u32_e32 v194, 0x400, v194
	v_subrev_u32_e32 v197, 0x800, v197
	v_subrev_u32_e32 v196, 0x800, v196
	v_subrev_u32_e32 v199, 0xc00, v199
	v_subrev_u32_e32 v198, 0xc00, v198
	s_and_b32 s26, s24, 0x4000
	s_xor_b32 s25, s26, 0x4000
	s_lshl_b32 s25, s25, 1
	s_add_i32 s25, s25, 32
	s_lshl_b32 s26, s26, 1
	s_add_i32 s26, s26, 32

.LBB0_690:
	s_ashr_i32 s14, s16, 31
	s_lshr_b32 s14, s14, 29
	s_add_i32 s14, s16, s14
	s_ashr_i32 s14, s14, 3
	s_lshl_b32 s15, s14, 10
	s_lshl_b32 s23, s16, 7
	v_add_u32_e32 v0, s14, v104
	s_sub_i32 s23, s23, s15
	v_lshlrev_b32_e32 v2, 7, v0
	v_add_u32_e32 v0, s23, v105
	v_ashrrev_i32_e32 v1, 31, v0
	v_add_u32_e32 v3, 0x4000, v106
	v_lshlrev_b64 v[0:1], 13, v[0:1]
	v_readfirstlane_b32 s24, v3
	v_lshl_add_u64 v[0:1], v[64:65], 0, v[0:1]
	s_mov_b32 m0, s24
	v_readfirstlane_b32 s24, v106
	global_load_lds_dwordx4 v[0:1], off
	v_add_u32_e32 v0, v2, v105
	v_ashrrev_i32_e32 v1, 31, v0
	v_lshlrev_b64 v[0:1], 13, v[0:1]
	v_lshl_add_u64 v[0:1], v[70:71], 0, v[0:1]
	s_mov_b32 m0, s24
	v_readfirstlane_b32 s24, v131
	global_load_lds_dwordx4 v[0:1], off
	v_add_u32_e32 v0, s23, v107
	v_ashrrev_i32_e32 v1, 31, v0
	v_lshlrev_b64 v[0:1], 13, v[0:1]
	v_lshl_add_u64 v[0:1], v[66:67], 0, v[0:1]
	s_mov_b32 m0, s24
	v_add_u32_e32 v3, 0x400, v106
	global_load_lds_dwordx4 v[0:1], off
	v_add_u32_e32 v0, v2, v107
	v_ashrrev_i32_e32 v1, 31, v0
	v_lshlrev_b64 v[0:1], 13, v[0:1]
	v_readfirstlane_b32 s24, v3
	v_lshl_add_u64 v[0:1], v[72:73], 0, v[0:1]
	s_mov_b32 m0, s24
	v_readfirstlane_b32 s24, v132
	global_load_lds_dwordx4 v[0:1], off
	v_add_u32_e32 v0, s23, v109
	v_ashrrev_i32_e32 v1, 31, v0
	v_lshlrev_b64 v[0:1], 13, v[0:1]
	v_lshl_add_u64 v[0:1], v[64:65], 0, v[0:1]
	s_mov_b32 m0, s24
	v_add_u32_e32 v3, 0x800, v106
	global_load_lds_dwordx4 v[0:1], off
	v_add_u32_e32 v0, v2, v109
	v_ashrrev_i32_e32 v1, 31, v0
	v_lshlrev_b64 v[0:1], 13, v[0:1]
	v_readfirstlane_b32 s24, v3
	v_lshl_add_u64 v[0:1], v[70:71], 0, v[0:1]
	s_mov_b32 m0, s24
	v_readfirstlane_b32 s24, v133
	global_load_lds_dwordx4 v[0:1], off
	v_add_u32_e32 v0, s23, v111
	v_ashrrev_i32_e32 v1, 31, v0
	v_lshlrev_b64 v[0:1], 13, v[0:1]
	v_lshl_add_u64 v[0:1], v[68:69], 0, v[0:1]
	s_mov_b32 m0, s24
	s_mov_b32 s25, 0
	global_load_lds_dwordx4 v[0:1], off
	v_add_u32_e32 v0, v2, v111
	v_ashrrev_i32_e32 v1, 31, v0
	v_add_u32_e32 v2, 0xc00, v106
	v_lshlrev_b64 v[0:1], 13, v[0:1]
	v_readfirstlane_b32 s24, v2
	v_lshl_add_u64 v[0:1], v[74:75], 0, v[0:1]
	s_mov_b32 m0, s24
	s_lshl_b32 s24, s14, 7
	global_load_lds_dwordx4 v[0:1], off
	v_subrev_u32_e32 v0, s15, v121
	v_ashrrev_i32_e32 v1, 31, v0
	v_lshlrev_b64 v[0:1], 13, v[0:1]
	v_lshl_add_u64 v[88:89], v[76:77], 0, v[0:1]
	v_add_u32_e32 v0, s24, v122
	v_ashrrev_i32_e32 v1, 31, v0
	v_lshlrev_b64 v[0:1], 13, v[0:1]
	v_lshl_add_u64 v[90:91], v[78:79], 0, v[0:1]
	v_subrev_u32_e32 v0, s15, v123
	v_ashrrev_i32_e32 v1, 31, v0
	v_lshlrev_b64 v[0:1], 13, v[0:1]
	v_lshl_add_u64 v[92:93], v[80:81], 0, v[0:1]
	v_add_u32_e32 v0, s24, v124
	v_ashrrev_i32_e32 v1, 31, v0
	v_lshlrev_b64 v[0:1], 13, v[0:1]
	v_lshl_add_u64 v[94:95], v[82:83], 0, v[0:1]
	v_subrev_u32_e32 v0, s15, v125
	v_ashrrev_i32_e32 v1, 31, v0
	v_lshlrev_b64 v[0:1], 13, v[0:1]
	v_lshl_add_u64 v[96:97], v[76:77], 0, v[0:1]
	v_add_u32_e32 v0, s24, v126
	v_ashrrev_i32_e32 v1, 31, v0
	v_lshlrev_b64 v[0:1], 13, v[0:1]
	v_lshl_add_u64 v[98:99], v[78:79], 0, v[0:1]
	v_subrev_u32_e32 v0, s15, v127
	v_ashrrev_i32_e32 v1, 31, v0
	v_lshlrev_b64 v[0:1], 13, v[0:1]
	v_lshl_add_u64 v[100:101], v[84:85], 0, v[0:1]
	v_add_u32_e32 v0, s24, v128
	v_ashrrev_i32_e32 v1, 31, v0
	v_lshlrev_b64 v[0:1], 13, v[0:1]
	v_lshl_add_u64 v[102:103], v[86:87], 0, v[0:1]
	v_mov_b32_e32 v0, 0
	s_mov_b64 s[14:15], 0
	v_mov_b32_e32 v1, v0
	v_mov_b32_e32 v2, v0
	v_mov_b32_e32 v3, v0
	v_mov_b32_e32 v4, v0
	v_mov_b32_e32 v5, v0
	v_mov_b32_e32 v6, v0
	v_mov_b32_e32 v7, v0
	v_mov_b32_e32 v8, v0
	v_mov_b32_e32 v9, v0
	v_mov_b32_e32 v10, v0
	v_mov_b32_e32 v11, v0
	v_mov_b32_e32 v12, v0
	v_mov_b32_e32 v13, v0
	v_mov_b32_e32 v14, v0
	v_mov_b32_e32 v15, v0
	v_mov_b32_e32 v16, v0
	v_mov_b32_e32 v17, v0
	v_mov_b32_e32 v18, v0
	v_mov_b32_e32 v19, v0
	v_mov_b32_e32 v20, v0
	v_mov_b32_e32 v21, v0
	v_mov_b32_e32 v22, v0
	v_mov_b32_e32 v23, v0
	v_mov_b32_e32 v24, v0
	v_mov_b32_e32 v25, v0
	v_mov_b32_e32 v26, v0
	v_mov_b32_e32 v27, v0
	v_mov_b32_e32 v28, v0
	v_mov_b32_e32 v29, v0
	v_mov_b32_e32 v30, v0
	v_mov_b32_e32 v31, v0
	v_mov_b32_e32 v32, v0
	v_mov_b32_e32 v33, v0
	v_mov_b32_e32 v34, v0
	v_mov_b32_e32 v35, v0
	v_mov_b32_e32 v36, v0
	v_mov_b32_e32 v37, v0
	v_mov_b32_e32 v38, v0
	v_mov_b32_e32 v39, v0
	v_mov_b32_e32 v40, v0
	v_mov_b32_e32 v41, v0
	v_mov_b32_e32 v42, v0
	v_mov_b32_e32 v43, v0
	v_mov_b32_e32 v44, v0
	v_mov_b32_e32 v45, v0
	v_mov_b32_e32 v46, v0
	v_mov_b32_e32 v47, v0
	v_mov_b32_e32 v48, v0
	v_mov_b32_e32 v49, v0
	v_mov_b32_e32 v50, v0
	v_mov_b32_e32 v51, v0
	v_mov_b32_e32 v52, v0
	v_mov_b32_e32 v53, v0
	v_mov_b32_e32 v54, v0
	v_mov_b32_e32 v55, v0
	v_mov_b32_e32 v56, v0
	v_mov_b32_e32 v57, v0
	v_mov_b32_e32 v58, v0
	v_mov_b32_e32 v59, v0
	v_mov_b32_e32 v60, v0
	v_mov_b32_e32 v61, v0
	v_mov_b32_e32 v62, v0
	v_mov_b32_e32 v63, v0
	s_waitcnt vmcnt(0) lgkmcnt(0)
	s_barrier
	v_add3_u32 v190, 0, v134, v135
	v_add_u32_e32 v191, 0x4000, v190
	s_nop 0
	v_readfirstlane_b32 s82, v191
	s_nop 0
	v_readfirstlane_b32 s83, v190
	v_subrev_u32_e32 v192, s52, v88
	v_subrev_u32_e32 v193, s52, v90
	v_subrev_u32_e32 v194, s52, v92
	v_subrev_u32_e32 v195, s52, v94
	v_subrev_u32_e32 v196, s52, v96
	v_subrev_u32_e32 v197, s52, v98
	v_subrev_u32_e32 v198, s52, v100
	v_subrev_u32_e32 v199, s52, v102
	v_subrev_u32_e32 v195, 0x400, v195
	v_subrev_u32_e32 v194, 0x400, v194
	v_subrev_u32_e32 v197, 0x800, v197
	v_subrev_u32_e32 v196, 0x800, v196
	v_subrev_u32_e32 v199, 0xc00, v199
	v_subrev_u32_e32 v198, 0xc00, v198
	s_and_b32 s27, s25, 0x4000
	s_xor_b32 s26, s27, 0x4000
	s_lshl_b32 s26, s26, 1
	s_add_i32 s26, s26, 32
	s_lshl_b32 s27, s27, 1
	s_add_i32 s27, s27, 32

.LBB0_701:
	s_and_b32 s14, s18, 0x380
	v_add_lshl_u32 v72, v141, s14, 13
	v_lshl_add_u64 v[98:99], v[86:87], 0, v[72:73]
	v_add_lshl_u32 v72, v143, s14, 13
	v_lshl_add_u64 v[100:101], v[90:91], 0, v[72:73]
	v_add_lshl_u32 v72, v145, s14, 13
	s_lshl_b32 s24, s23, 7
	v_lshl_add_u64 v[102:103], v[86:87], 0, v[72:73]
	v_add_lshl_u32 v72, v147, s14, 13
	s_ashr_i32 s14, s23, 3
	s_and_b32 s24, s24, 0x380
	v_add_u32_e32 v2, 0x4000, v135
	v_lshl_add_u64 v[104:105], v[94:95], 0, v[72:73]
	s_add_i32 s15, s14, s17
	v_add_lshl_u32 v72, s24, v134, 13
	v_readfirstlane_b32 s25, v2
	s_lshl_b32 s15, s15, 7
	v_lshl_add_u64 v[0:1], v[74:75], 0, v[72:73]
	s_mov_b32 m0, s25
	v_readfirstlane_b32 s25, v135
	global_load_lds_dwordx4 v[0:1], off
	v_add_u32_e32 v0, s15, v134
	v_ashrrev_i32_e32 v1, 31, v0
	v_lshlrev_b64 v[0:1], 13, v[0:1]
	v_lshl_add_u64 v[0:1], v[80:81], 0, v[0:1]
	s_mov_b32 m0, s25
	v_add_lshl_u32 v72, s24, v126, 13
	v_readfirstlane_b32 s25, v151
	global_load_lds_dwordx4 v[0:1], off
	v_lshl_add_u64 v[0:1], v[76:77], 0, v[72:73]
	s_mov_b32 m0, s25
	v_add_u32_e32 v2, 0x400, v135
	global_load_lds_dwordx4 v[0:1], off
	v_add_u32_e32 v0, s15, v126
	v_ashrrev_i32_e32 v1, 31, v0
	v_lshlrev_b64 v[0:1], 13, v[0:1]
	v_readfirstlane_b32 s25, v2
	v_lshl_add_u64 v[0:1], v[82:83], 0, v[0:1]
	s_mov_b32 m0, s25
	v_add_lshl_u32 v72, s24, v127, 13
	v_readfirstlane_b32 s25, v152
	global_load_lds_dwordx4 v[0:1], off
	v_lshl_add_u64 v[0:1], v[74:75], 0, v[72:73]
	s_mov_b32 m0, s25
	v_add_u32_e32 v2, 0x800, v135
	global_load_lds_dwordx4 v[0:1], off
	v_add_u32_e32 v0, s15, v127
	v_ashrrev_i32_e32 v1, 31, v0
	v_lshlrev_b64 v[0:1], 13, v[0:1]
	v_readfirstlane_b32 s25, v2
	v_lshl_add_u64 v[0:1], v[80:81], 0, v[0:1]
	s_mov_b32 m0, s25
	v_add_lshl_u32 v72, s24, v125, 13
	v_readfirstlane_b32 s25, v153
	global_load_lds_dwordx4 v[0:1], off
	v_lshl_add_u64 v[0:1], v[78:79], 0, v[72:73]
	s_mov_b32 m0, s25
	v_add_u32_e32 v2, 0xc00, v135
	global_load_lds_dwordx4 v[0:1], off
	v_add_u32_e32 v0, s15, v125
	v_ashrrev_i32_e32 v1, 31, v0
	v_lshlrev_b64 v[0:1], 13, v[0:1]
	v_readfirstlane_b32 s15, v2
	v_lshl_add_u64 v[0:1], v[84:85], 0, v[0:1]
	s_mov_b32 m0, s15
	s_lshl_b32 s25, s14, 7
	global_load_lds_dwordx4 v[0:1], off
	v_add_u32_e32 v0, s25, v142
	v_ashrrev_i32_e32 v1, 31, v0
	v_lshlrev_b64 v[0:1], 13, v[0:1]
	v_lshl_add_u64 v[106:107], v[88:89], 0, v[0:1]
	v_add_u32_e32 v0, s25, v144
	v_ashrrev_i32_e32 v1, 31, v0
	v_lshlrev_b64 v[0:1], 13, v[0:1]
	v_lshl_add_u64 v[108:109], v[92:93], 0, v[0:1]
	v_add_u32_e32 v0, s25, v146
	v_ashrrev_i32_e32 v1, 31, v0
	v_lshlrev_b64 v[0:1], 13, v[0:1]
	v_lshl_add_u64 v[110:111], v[88:89], 0, v[0:1]
	v_add_u32_e32 v0, s25, v148
	v_ashrrev_i32_e32 v1, 31, v0
	v_lshlrev_b64 v[0:1], 13, v[0:1]
	v_lshl_add_u64 v[112:113], v[96:97], 0, v[0:1]
	s_mov_b64 s[14:15], 0
	s_mov_b32 s26, 0
	v_mov_b32_e32 v0, 0
	v_mov_b32_e32 v1, v73
	v_mov_b32_e32 v2, v73
	v_mov_b32_e32 v3, v73
	v_mov_b32_e32 v4, 0
	v_mov_b32_e32 v5, v73
	v_mov_b32_e32 v6, v73
	v_mov_b32_e32 v7, v73
	v_mov_b32_e32 v8, 0
	v_mov_b32_e32 v9, v73
	v_mov_b32_e32 v10, v73
	v_mov_b32_e32 v11, v73
	v_mov_b32_e32 v12, 0
	v_mov_b32_e32 v13, v73
	v_mov_b32_e32 v14, v73
	v_mov_b32_e32 v15, v73
	v_mov_b32_e32 v16, 0
	v_mov_b32_e32 v17, v73
	v_mov_b32_e32 v18, v73
	v_mov_b32_e32 v19, v73
	v_mov_b32_e32 v20, 0
	v_mov_b32_e32 v21, v73
	v_mov_b32_e32 v22, v73
	v_mov_b32_e32 v23, v73
	v_mov_b32_e32 v24, 0
	v_mov_b32_e32 v25, v73
	v_mov_b32_e32 v26, v73
	v_mov_b32_e32 v27, v73
	v_mov_b32_e32 v28, 0
	v_mov_b32_e32 v29, v73
	v_mov_b32_e32 v30, v73
	v_mov_b32_e32 v31, v73
	v_mov_b32_e32 v32, 0
	v_mov_b32_e32 v33, v73
	v_mov_b32_e32 v34, v73
	v_mov_b32_e32 v35, v73
	v_mov_b32_e32 v36, 0
	v_mov_b32_e32 v37, v73
	v_mov_b32_e32 v38, v73
	v_mov_b32_e32 v39, v73
	v_mov_b32_e32 v40, 0
	v_mov_b32_e32 v41, v73
	v_mov_b32_e32 v42, v73
	v_mov_b32_e32 v43, v73
	v_mov_b32_e32 v44, 0
	v_mov_b32_e32 v45, v73
	v_mov_b32_e32 v46, v73
	v_mov_b32_e32 v47, v73
	v_mov_b32_e32 v48, 0
	v_mov_b32_e32 v49, v73
	v_mov_b32_e32 v50, v73
	v_mov_b32_e32 v51, v73
	v_mov_b32_e32 v52, 0
	v_mov_b32_e32 v53, v73
	v_mov_b32_e32 v54, v73
	v_mov_b32_e32 v55, v73
	v_mov_b32_e32 v56, 0
	v_mov_b32_e32 v57, v73
	v_mov_b32_e32 v58, v73
	v_mov_b32_e32 v59, v73
	v_mov_b32_e32 v60, 0
	v_mov_b32_e32 v61, v73
	v_mov_b32_e32 v62, v73
	v_mov_b32_e32 v63, v73
	s_waitcnt vmcnt(0) lgkmcnt(0)
	s_barrier
	v_lshlrev_b32_e32 v190, 1, v132
	v_lshlrev_b32_e32 v191, 1, v133
	v_add3_u32 v190, 0, v190, v191
	v_add_u32_e32 v192, 0x4000, v190
	s_nop 0
	v_readfirstlane_b32 s82, v192
	s_nop 0
	v_readfirstlane_b32 s83, v190
	v_subrev_u32_e32 v193, s52, v98
	v_subrev_u32_e32 v194, s52, v106
	v_subrev_u32_e32 v195, s52, v100
	v_subrev_u32_e32 v196, s52, v108
	v_subrev_u32_e32 v197, s52, v102
	v_subrev_u32_e32 v198, s52, v110
	v_subrev_u32_e32 v199, s52, v104
	v_subrev_u32_e32 v200, s52, v112
	v_subrev_u32_e32 v196, 0x400, v196
	v_subrev_u32_e32 v195, 0x400, v195
	v_subrev_u32_e32 v198, 0x800, v198
	v_subrev_u32_e32 v197, 0x800, v197
	v_subrev_u32_e32 v200, 0xc00, v200
	v_subrev_u32_e32 v199, 0xc00, v199
	s_and_b32 s28, s26, 0x4000
	s_xor_b32 s27, s28, 0x4000
	s_lshl_b32 s27, s27, 1
	s_add_i32 s27, s27, 32
	s_lshl_b32 s28, s28, 1
	s_add_i32 s28, s28, 32

.LBB0_707:
	s_ashr_i32 s15, s16, 2
	s_add_i32 s10, s15, 0x80
	s_and_b32 s14, s16, 3
	s_ashr_i32 s18, s10, 3
	s_add_i32 s19, s18, s17
	s_lshl_b32 s10, s14, 11
	s_add_u32 s6, s6, s10
	s_addc_u32 s7, s7, 0
	s_add_u32 s16, s8, s10
	s_addc_u32 s17, s9, 0
	s_lshl_b32 s9, s15, 7
	s_lshl_b32 s8, s19, 7
	s_and_b32 s9, s9, 0x380
	v_lshlrev_b32_e32 v83, 1, v2
	v_lshlrev_b32_e32 v84, 1, v3
	v_add_lshl_u32 v0, s9, v134, 13
	v_mov_b32_e32 v1, 0
	v_add3_u32 v20, 32, v83, v84
	v_add_u32_e32 v2, s8, v134
	v_lshl_add_u64 v[4:5], s[16:17], 0, v[0:1]
	v_add_u32_e32 v0, 0x4000, v20
	v_ashrrev_i32_e32 v3, 31, v2
	v_mov_b32_e32 v71, v1
	v_readfirstlane_b32 s19, v0
	v_lshlrev_b64 v[2:3], 13, v[2:3]
	v_lshl_add_u64 v[4:5], v[4:5], 0, v[70:71]
	s_mov_b32 m0, s19
	v_lshl_add_u64 v[2:3], s[6:7], 0, v[2:3]
	v_readfirstlane_b32 s19, v20
	global_load_lds_dwordx4 v[4:5], off
	v_lshl_add_u64 v[2:3], v[2:3], 0, v[70:71]
	s_mov_b32 m0, s19
	v_add_lshl_u32 v0, v126, s9, 12
	s_movk_i32 s15, 0x4000
	global_load_lds_dwordx4 v[2:3], off
	v_lshlrev_b64 v[2:3], 1, v[0:1]
	v_lshl_add_u32 v0, v118, 1, 32
	v_add3_u32 v0, v0, v84, s15
	v_lshl_add_u64 v[4:5], s[16:17], 0, v[2:3]
	v_lshlrev_b64 v[6:7], 1, v[66:67]
	v_readfirstlane_b32 s19, v0
	v_lshl_add_u64 v[4:5], v[4:5], 0, v[6:7]
	s_mov_b32 m0, s19
	v_add_u32_e32 v0, 0x400, v20
	global_load_lds_dwordx4 v[4:5], off
	v_add_u32_e32 v4, s8, v126
	v_ashrrev_i32_e32 v5, 31, v4
	v_lshlrev_b64 v[4:5], 13, v[4:5]
	v_lshl_add_u64 v[8:9], s[6:7], 0, v[4:5]
	v_readfirstlane_b32 s19, v0
	v_lshl_add_u64 v[8:9], v[8:9], 0, v[6:7]
	s_mov_b32 m0, s19
	v_add_lshl_u32 v0, v127, s9, 12
	global_load_lds_dwordx4 v[8:9], off
	v_lshlrev_b64 v[8:9], 1, v[0:1]
	v_lshl_add_u32 v0, v119, 1, 32
	v_add3_u32 v0, v0, v84, s15
	v_lshl_add_u64 v[10:11], s[16:17], 0, v[8:9]
	v_readfirstlane_b32 s19, v0
	v_lshl_add_u64 v[10:11], v[10:11], 0, v[70:71]
	s_mov_b32 m0, s19
	v_add_u32_e32 v0, 0x800, v20
	global_load_lds_dwordx4 v[10:11], off
	v_add_u32_e32 v10, s8, v127
	v_ashrrev_i32_e32 v11, 31, v10
	v_lshlrev_b64 v[10:11], 13, v[10:11]
	v_lshl_add_u64 v[12:13], s[6:7], 0, v[10:11]
	v_readfirstlane_b32 s19, v0
	v_lshl_add_u64 v[12:13], v[12:13], 0, v[70:71]
	s_mov_b32 m0, s19
	v_add_lshl_u32 v0, v125, s9, 12
	global_load_lds_dwordx4 v[12:13], off
	v_lshlrev_b64 v[12:13], 1, v[0:1]
	v_lshl_add_u32 v0, v120, 1, 32
	v_add3_u32 v0, v0, v84, s15
	v_lshl_add_u64 v[14:15], s[16:17], 0, v[12:13]
	v_lshlrev_b64 v[16:17], 1, v[68:69]
	v_readfirstlane_b32 s16, v0
	v_lshl_add_u64 v[14:15], v[14:15], 0, v[16:17]
	s_mov_b32 m0, s16
	v_add_u32_e32 v0, 0xc00, v20
	global_load_lds_dwordx4 v[14:15], off
	v_add_u32_e32 v14, s8, v125
	v_ashrrev_i32_e32 v15, 31, v14
	v_lshlrev_b64 v[14:15], 13, v[14:15]
	v_lshl_add_u64 v[18:19], s[6:7], 0, v[14:15]
	v_readfirstlane_b32 s6, v0
	v_lshl_add_u64 v[18:19], v[18:19], 0, v[16:17]
	s_mov_b32 m0, s6
	s_mov_b32 s11, 0
	global_load_lds_dwordx4 v[18:19], off
	v_or_b32_e32 v0, s9, v124
	v_lshl_add_u64 v[6:7], s[10:11], 0, v[6:7]
	v_add_lshl_u32 v0, v0, v123, 13
	v_lshl_add_u64 v[18:19], s[10:11], 0, v[64:65]
	v_lshl_add_u64 v[2:3], v[6:7], 0, v[2:3]
	v_lshl_add_u64 v[20:21], v[18:19], 0, v[0:1]
	s_mov_b64 s[6:7], 0x800080
	v_lshl_add_u64 v[2:3], s[4:5], 0, v[2:3]
	v_lshl_add_u64 v[20:21], s[4:5], 0, v[20:21]
	s_lshl_b32 s16, s18, 7
	v_lshl_add_u64 v[68:69], v[2:3], 0, s[6:7]
	v_lshl_add_u64 v[2:3], v[6:7], 0, v[4:5]
	v_lshl_add_u64 v[64:65], v[20:21], 0, s[6:7]
	v_add3_u32 v20, v128, s16, v123
	s_mov_b64 s[16:17], 0x8600080
	v_lshl_add_u64 v[2:3], s[4:5], 0, v[2:3]
	v_lshl_add_u64 v[70:71], v[2:3], 0, s[16:17]
	v_lshl_add_u64 v[2:3], v[18:19], 0, v[8:9]
	v_lshl_add_u64 v[2:3], s[4:5], 0, v[2:3]
	v_lshl_add_u64 v[72:73], v[2:3], 0, s[6:7]
	v_lshl_add_u64 v[2:3], v[18:19], 0, v[10:11]
	v_ashrrev_i32_e32 v21, 31, v20
	v_lshl_add_u64 v[2:3], s[4:5], 0, v[2:3]
	v_lshlrev_b64 v[20:21], 13, v[20:21]
	v_lshl_add_u64 v[74:75], v[2:3], 0, s[16:17]
	v_lshl_add_u64 v[2:3], s[10:11], 0, v[16:17]
	v_lshl_add_u64 v[20:21], v[18:19], 0, v[20:21]
	v_lshl_add_u64 v[4:5], v[2:3], 0, v[12:13]
	v_lshl_add_u64 v[2:3], v[2:3], 0, v[14:15]
	v_lshl_add_u64 v[20:21], s[4:5], 0, v[20:21]
	v_lshl_add_u64 v[4:5], s[4:5], 0, v[4:5]
	v_lshl_add_u64 v[2:3], s[4:5], 0, v[2:3]
	v_lshl_add_u64 v[66:67], v[20:21], 0, s[16:17]
	v_lshl_add_u64 v[76:77], v[4:5], 0, s[6:7]
	v_lshl_add_u64 v[78:79], v[2:3], 0, s[16:17]
	s_mov_b64 s[4:5], 0
	v_mov_b32_e32 v0, v1
	v_mov_b32_e32 v2, v1
	v_mov_b32_e32 v3, v1
	v_mov_b32_e32 v4, v1
	v_mov_b32_e32 v5, v1
	v_mov_b32_e32 v6, v1
	v_mov_b32_e32 v7, v1
	v_mov_b32_e32 v8, v1
	v_mov_b32_e32 v9, v1
	v_mov_b32_e32 v10, v1
	v_mov_b32_e32 v11, v1
	v_mov_b32_e32 v12, v1
	v_mov_b32_e32 v13, v1
	v_mov_b32_e32 v14, v1
	v_mov_b32_e32 v15, v1
	v_mov_b32_e32 v16, v1
	v_mov_b32_e32 v17, v1
	v_mov_b32_e32 v18, v1
	v_mov_b32_e32 v19, v1
	v_mov_b32_e32 v20, v1
	v_mov_b32_e32 v21, v1
	v_mov_b32_e32 v22, v1
	v_mov_b32_e32 v23, v1
	v_mov_b32_e32 v24, v1
	v_mov_b32_e32 v25, v1
	v_mov_b32_e32 v26, v1
	v_mov_b32_e32 v27, v1
	v_mov_b32_e32 v28, v1
	v_mov_b32_e32 v29, v1
	v_mov_b32_e32 v30, v1
	v_mov_b32_e32 v31, v1
	v_mov_b32_e32 v32, v1
	v_mov_b32_e32 v33, v1
	v_mov_b32_e32 v34, v1
	v_mov_b32_e32 v35, v1
	v_mov_b32_e32 v36, v1
	v_mov_b32_e32 v37, v1
	v_mov_b32_e32 v38, v1
	v_mov_b32_e32 v39, v1
	v_mov_b32_e32 v40, v1
	v_mov_b32_e32 v41, v1
	v_mov_b32_e32 v42, v1
	v_mov_b32_e32 v43, v1
	v_mov_b32_e32 v44, v1
	v_mov_b32_e32 v45, v1
	v_mov_b32_e32 v46, v1
	v_mov_b32_e32 v47, v1
	v_mov_b32_e32 v48, v1
	v_mov_b32_e32 v49, v1
	v_mov_b32_e32 v50, v1
	v_mov_b32_e32 v51, v1
	v_mov_b32_e32 v52, v1
	v_mov_b32_e32 v53, v1
	v_mov_b32_e32 v54, v1
	v_mov_b32_e32 v55, v1
	v_mov_b32_e32 v56, v1
	v_mov_b32_e32 v57, v1
	v_mov_b32_e32 v58, v1
	v_mov_b32_e32 v59, v1
	v_mov_b32_e32 v60, v1
	v_mov_b32_e32 v61, v1
	v_mov_b32_e32 v62, v1
	v_mov_b32_e32 v63, v1
	s_waitcnt vmcnt(0) lgkmcnt(0)
	s_barrier
	v_add3_u32 v190, 0, v83, v84
	v_add_u32_e32 v191, 0x4000, v190
	s_nop 0
	v_readfirstlane_b32 s82, v191
	s_nop 0
	v_readfirstlane_b32 s83, v190
	v_subrev_u32_e32 v192, s52, v64
	v_subrev_u32_e32 v193, s52, v66
	v_subrev_u32_e32 v194, s52, v68
	v_subrev_u32_e32 v195, s52, v70
	v_subrev_u32_e32 v196, s52, v72
	v_subrev_u32_e32 v197, s52, v74
	v_subrev_u32_e32 v198, s52, v76
	v_subrev_u32_e32 v199, s52, v78
	v_subrev_u32_e32 v195, 0x400, v195
	v_subrev_u32_e32 v194, 0x400, v194
	v_subrev_u32_e32 v197, 0x800, v197
	v_subrev_u32_e32 v196, 0x800, v196
	v_subrev_u32_e32 v199, 0xc00, v199
	v_subrev_u32_e32 v198, 0xc00, v198
	s_and_b32 s7, s11, 0x4000
	s_xor_b32 s6, s7, 0x4000
	s_lshl_b32 s6, s6, 1
	s_add_i32 s6, s6, 32
	s_lshl_b32 s7, s7, 1
	s_add_i32 s7, s7, 32

.LBB0_1813:
	s_ashr_i32 s16, s23, 31
	s_lshr_b32 s16, s16, 29
	s_add_i32 s16, s23, s16
	s_ashr_i32 s16, s16, 3
	s_lshl_b32 s24, s16, 7
	s_lshl_b32 s16, s16, 10
	s_lshl_b32 s17, s23, 7
	s_sub_i32 s25, s17, s16
	v_add_u32_e32 v0, s25, v106
	v_ashrrev_i32_e32 v1, 31, v0
	v_add_u32_e32 v2, 0x4000, v107
	v_lshlrev_b64 v[0:1], 11, v[0:1]
	v_readfirstlane_b32 s17, v2
	v_lshl_add_u64 v[0:1], v[66:67], 0, v[0:1]
	s_mov_b32 m0, s17
	v_readfirstlane_b32 s17, v107
	global_load_lds_dwordx4 v[0:1], off
	v_add_u32_e32 v0, s24, v106
	v_ashrrev_i32_e32 v1, 31, v0
	v_lshlrev_b64 v[0:1], 11, v[0:1]
	v_lshl_add_u64 v[2:3], v[72:73], 0, v[0:1]
	s_mov_b32 m0, s17
	v_readfirstlane_b32 s17, v130
	global_load_lds_dwordx4 v[2:3], off
	v_add_u32_e32 v2, s25, v108
	v_ashrrev_i32_e32 v3, 31, v2
	v_lshlrev_b64 v[2:3], 11, v[2:3]
	v_lshl_add_u64 v[2:3], v[68:69], 0, v[2:3]
	s_mov_b32 m0, s17
	v_add_u32_e32 v4, 0x400, v107
	global_load_lds_dwordx4 v[2:3], off
	v_add_u32_e32 v2, s24, v108
	v_ashrrev_i32_e32 v3, 31, v2
	v_lshlrev_b64 v[2:3], 11, v[2:3]
	v_readfirstlane_b32 s17, v4
	v_lshl_add_u64 v[2:3], v[74:75], 0, v[2:3]
	s_mov_b32 m0, s17
	v_readfirstlane_b32 s17, v131
	global_load_lds_dwordx4 v[2:3], off
	v_add_u32_e32 v2, s25, v110
	v_ashrrev_i32_e32 v3, 31, v2
	v_lshlrev_b64 v[2:3], 11, v[2:3]
	v_lshl_add_u64 v[2:3], v[66:67], 0, v[2:3]
	s_mov_b32 m0, s17
	v_add_u32_e32 v4, 0x800, v107
	global_load_lds_dwordx4 v[2:3], off
	v_add_u32_e32 v2, s24, v110
	v_ashrrev_i32_e32 v3, 31, v2
	v_lshlrev_b64 v[2:3], 11, v[2:3]
	v_readfirstlane_b32 s17, v4
	v_lshl_add_u64 v[2:3], v[72:73], 0, v[2:3]
	s_mov_b32 m0, s17
	v_readfirstlane_b32 s17, v132
	global_load_lds_dwordx4 v[2:3], off
	v_add_u32_e32 v2, s25, v112
	v_ashrrev_i32_e32 v3, 31, v2
	v_lshlrev_b64 v[2:3], 11, v[2:3]
	v_lshl_add_u64 v[2:3], v[70:71], 0, v[2:3]
	s_mov_b32 m0, s17
	v_add_u32_e32 v4, 0xc00, v107
	global_load_lds_dwordx4 v[2:3], off
	v_add_u32_e32 v2, s24, v112
	v_ashrrev_i32_e32 v3, 31, v2
	v_lshlrev_b64 v[2:3], 11, v[2:3]
	v_readfirstlane_b32 s17, v4
	v_lshl_add_u64 v[2:3], v[76:77], 0, v[2:3]
	s_mov_b32 m0, s17
	v_lshl_add_u64 v[92:93], v[80:81], 0, v[0:1]
	global_load_lds_dwordx4 v[2:3], off
	v_subrev_u32_e32 v0, s16, v123
	v_ashrrev_i32_e32 v1, 31, v0
	v_lshlrev_b64 v[0:1], 11, v[0:1]
	v_lshl_add_u64 v[94:95], v[82:83], 0, v[0:1]
	v_add_u32_e32 v0, s24, v124
	v_ashrrev_i32_e32 v1, 31, v0
	v_lshlrev_b64 v[0:1], 11, v[0:1]
	v_lshl_add_u64 v[96:97], v[84:85], 0, v[0:1]
	v_subrev_u32_e32 v0, s16, v125
	v_ashrrev_i32_e32 v1, 31, v0
	v_lshlrev_b64 v[0:1], 11, v[0:1]
	v_lshl_add_u64 v[98:99], v[78:79], 0, v[0:1]
	v_add_u32_e32 v0, s24, v126
	v_ashrrev_i32_e32 v1, 31, v0
	v_lshlrev_b64 v[0:1], 11, v[0:1]
	v_lshl_add_u64 v[100:101], v[80:81], 0, v[0:1]
	v_subrev_u32_e32 v0, s16, v64
	v_ashrrev_i32_e32 v1, 31, v0
	v_lshlrev_b64 v[0:1], 11, v[0:1]
	v_subrev_u32_e32 v2, s16, v122
	v_lshl_add_u64 v[102:103], v[86:87], 0, v[0:1]
	v_add_u32_e32 v0, s24, v127
	v_ashrrev_i32_e32 v3, 31, v2
	v_ashrrev_i32_e32 v1, 31, v0
	v_lshlrev_b64 v[2:3], 11, v[2:3]
	v_lshlrev_b64 v[0:1], 11, v[0:1]
	v_lshl_add_u64 v[90:91], v[78:79], 0, v[2:3]
	v_lshl_add_u64 v[104:105], v[88:89], 0, v[0:1]
	s_mov_b32 s26, 0
	s_mov_b64 s[16:17], 0
	v_mov_b32_e32 v0, 0
	v_mov_b32_e32 v1, v65
	v_mov_b32_e32 v2, v65
	v_mov_b32_e32 v3, v65
	v_mov_b32_e32 v4, 0
	v_mov_b32_e32 v5, v65
	v_mov_b32_e32 v6, v65
	v_mov_b32_e32 v7, v65
	v_mov_b32_e32 v8, 0
	v_mov_b32_e32 v9, v65
	v_mov_b32_e32 v10, v65
	v_mov_b32_e32 v11, v65
	v_mov_b32_e32 v12, 0
	v_mov_b32_e32 v13, v65
	v_mov_b32_e32 v14, v65
	v_mov_b32_e32 v15, v65
	v_mov_b32_e32 v16, 0
	v_mov_b32_e32 v17, v65
	v_mov_b32_e32 v18, v65
	v_mov_b32_e32 v19, v65
	v_mov_b32_e32 v20, 0
	v_mov_b32_e32 v21, v65
	v_mov_b32_e32 v22, v65
	v_mov_b32_e32 v23, v65
	v_mov_b32_e32 v24, 0
	v_mov_b32_e32 v25, v65
	v_mov_b32_e32 v26, v65
	v_mov_b32_e32 v27, v65
	v_mov_b32_e32 v28, 0
	v_mov_b32_e32 v29, v65
	v_mov_b32_e32 v30, v65
	v_mov_b32_e32 v31, v65
	s_waitcnt vmcnt(0)
	v_mov_b32_e32 v32, 0
	v_mov_b32_e32 v33, v65
	v_mov_b32_e32 v34, v65
	v_mov_b32_e32 v35, v65
	v_mov_b32_e32 v36, 0
	v_mov_b32_e32 v37, v65
	v_mov_b32_e32 v38, v65
	v_mov_b32_e32 v39, v65
	v_mov_b32_e32 v40, 0
	v_mov_b32_e32 v41, v65
	v_mov_b32_e32 v42, v65
	v_mov_b32_e32 v43, v65
	v_mov_b32_e32 v44, 0
	v_mov_b32_e32 v45, v65
	v_mov_b32_e32 v46, v65
	v_mov_b32_e32 v47, v65
	v_mov_b32_e32 v48, 0
	v_mov_b32_e32 v49, v65
	v_mov_b32_e32 v50, v65
	v_mov_b32_e32 v51, v65
	v_mov_b32_e32 v52, 0
	v_mov_b32_e32 v53, v65
	v_mov_b32_e32 v54, v65
	v_mov_b32_e32 v55, v65
	v_mov_b32_e32 v56, 0
	v_mov_b32_e32 v57, v65
	v_mov_b32_e32 v58, v65
	v_mov_b32_e32 v59, v65
	v_mov_b32_e32 v60, 0
	v_mov_b32_e32 v61, v65
	v_mov_b32_e32 v62, v65
	v_mov_b32_e32 v63, v65
	s_waitcnt lgkmcnt(0)
	s_barrier
	v_add3_u32 v186, 0, v133, v134
	v_add_u32_e32 v187, 0x4000, v186
	s_nop 0
	v_readfirstlane_b32 s82, v187
	s_nop 0
	v_readfirstlane_b32 s83, v186
	v_subrev_u32_e32 v188, s52, v90
	v_subrev_u32_e32 v189, s52, v92
	v_subrev_u32_e32 v190, s52, v94
	v_subrev_u32_e32 v191, s52, v96
	v_subrev_u32_e32 v192, s52, v98
	v_subrev_u32_e32 v193, s52, v100
	v_subrev_u32_e32 v194, s52, v102
	v_subrev_u32_e32 v195, s52, v104
	v_subrev_u32_e32 v191, 0x400, v191
	v_subrev_u32_e32 v190, 0x400, v190
	v_subrev_u32_e32 v193, 0x800, v193
	v_subrev_u32_e32 v192, 0x800, v192
	v_subrev_u32_e32 v195, 0xc00, v195
	v_subrev_u32_e32 v194, 0xc00, v194
	s_and_b32 s28, s26, 0x4000
	s_xor_b32 s27, s28, 0x4000
	s_lshl_b32 s27, s27, 1
	s_add_i32 s27, s27, 32
	s_lshl_b32 s28, s28, 1
	s_add_i32 s28, s28, 32

.LBB0_1822:
	s_ashr_i32 s16, s18, 31
	s_lshr_b32 s16, s16, 29
	s_add_i32 s16, s18, s16
	s_ashr_i32 s16, s16, 3
	s_lshl_b32 s17, s16, 10
	s_lshl_b32 s25, s18, 7
	v_add_u32_e32 v0, s16, v104
	s_sub_i32 s25, s25, s17
	v_lshlrev_b32_e32 v2, 7, v0
	v_add_u32_e32 v0, s25, v105
	v_ashrrev_i32_e32 v1, 31, v0
	v_add_u32_e32 v3, 0x4000, v106
	v_lshlrev_b64 v[0:1], 11, v[0:1]
	v_readfirstlane_b32 s26, v3
	v_lshl_add_u64 v[0:1], v[64:65], 0, v[0:1]
	s_mov_b32 m0, s26
	v_readfirstlane_b32 s26, v106
	global_load_lds_dwordx4 v[0:1], off
	v_add_u32_e32 v0, v2, v105
	v_ashrrev_i32_e32 v1, 31, v0
	v_lshlrev_b64 v[0:1], 11, v[0:1]
	v_lshl_add_u64 v[0:1], v[70:71], 0, v[0:1]
	s_mov_b32 m0, s26
	v_readfirstlane_b32 s26, v131
	global_load_lds_dwordx4 v[0:1], off
	v_add_u32_e32 v0, s25, v107
	v_ashrrev_i32_e32 v1, 31, v0
	v_lshlrev_b64 v[0:1], 11, v[0:1]
	v_lshl_add_u64 v[0:1], v[66:67], 0, v[0:1]
	s_mov_b32 m0, s26
	v_add_u32_e32 v3, 0x400, v106
	global_load_lds_dwordx4 v[0:1], off
	v_add_u32_e32 v0, v2, v107
	v_ashrrev_i32_e32 v1, 31, v0
	v_lshlrev_b64 v[0:1], 11, v[0:1]
	v_readfirstlane_b32 s26, v3
	v_lshl_add_u64 v[0:1], v[72:73], 0, v[0:1]
	s_mov_b32 m0, s26
	v_readfirstlane_b32 s26, v132
	global_load_lds_dwordx4 v[0:1], off
	v_add_u32_e32 v0, s25, v109
	v_ashrrev_i32_e32 v1, 31, v0
	v_lshlrev_b64 v[0:1], 11, v[0:1]
	v_lshl_add_u64 v[0:1], v[64:65], 0, v[0:1]
	s_mov_b32 m0, s26
	v_add_u32_e32 v3, 0x800, v106
	global_load_lds_dwordx4 v[0:1], off
	v_add_u32_e32 v0, v2, v109
	v_ashrrev_i32_e32 v1, 31, v0
	v_lshlrev_b64 v[0:1], 11, v[0:1]
	v_readfirstlane_b32 s26, v3
	v_lshl_add_u64 v[0:1], v[70:71], 0, v[0:1]
	s_mov_b32 m0, s26
	v_readfirstlane_b32 s26, v133
	global_load_lds_dwordx4 v[0:1], off
	v_add_u32_e32 v0, s25, v111
	v_ashrrev_i32_e32 v1, 31, v0
	v_lshlrev_b64 v[0:1], 11, v[0:1]
	v_lshl_add_u64 v[0:1], v[68:69], 0, v[0:1]
	s_mov_b32 m0, s26
	s_mov_b32 s27, 0
	global_load_lds_dwordx4 v[0:1], off
	v_add_u32_e32 v0, v2, v111
	v_ashrrev_i32_e32 v1, 31, v0
	v_add_u32_e32 v2, 0xc00, v106
	v_lshlrev_b64 v[0:1], 11, v[0:1]
	v_readfirstlane_b32 s26, v2
	v_lshl_add_u64 v[0:1], v[74:75], 0, v[0:1]
	s_mov_b32 m0, s26
	s_lshl_b32 s26, s16, 7
	global_load_lds_dwordx4 v[0:1], off
	v_subrev_u32_e32 v0, s17, v121
	v_ashrrev_i32_e32 v1, 31, v0
	v_lshlrev_b64 v[0:1], 11, v[0:1]
	v_lshl_add_u64 v[88:89], v[76:77], 0, v[0:1]
	v_add_u32_e32 v0, s26, v122
	v_ashrrev_i32_e32 v1, 31, v0
	v_lshlrev_b64 v[0:1], 11, v[0:1]
	v_lshl_add_u64 v[90:91], v[78:79], 0, v[0:1]
	v_subrev_u32_e32 v0, s17, v123
	v_ashrrev_i32_e32 v1, 31, v0
	v_lshlrev_b64 v[0:1], 11, v[0:1]
	v_lshl_add_u64 v[92:93], v[80:81], 0, v[0:1]
	v_add_u32_e32 v0, s26, v124
	v_ashrrev_i32_e32 v1, 31, v0
	v_lshlrev_b64 v[0:1], 11, v[0:1]
	v_lshl_add_u64 v[94:95], v[82:83], 0, v[0:1]
	v_subrev_u32_e32 v0, s17, v125
	v_ashrrev_i32_e32 v1, 31, v0
	v_lshlrev_b64 v[0:1], 11, v[0:1]
	v_lshl_add_u64 v[96:97], v[76:77], 0, v[0:1]
	v_add_u32_e32 v0, s26, v126
	v_ashrrev_i32_e32 v1, 31, v0
	v_lshlrev_b64 v[0:1], 11, v[0:1]
	v_lshl_add_u64 v[98:99], v[78:79], 0, v[0:1]
	v_subrev_u32_e32 v0, s17, v127
	v_ashrrev_i32_e32 v1, 31, v0
	v_lshlrev_b64 v[0:1], 11, v[0:1]
	v_lshl_add_u64 v[100:101], v[84:85], 0, v[0:1]
	v_add_u32_e32 v0, s26, v128
	v_ashrrev_i32_e32 v1, 31, v0
	v_lshlrev_b64 v[0:1], 11, v[0:1]
	v_lshl_add_u64 v[102:103], v[86:87], 0, v[0:1]
	v_mov_b32_e32 v0, 0
	s_mov_b64 s[16:17], 0
	v_mov_b32_e32 v1, v0
	v_mov_b32_e32 v2, v0
	v_mov_b32_e32 v3, v0
	v_mov_b32_e32 v4, v0
	v_mov_b32_e32 v5, v0
	v_mov_b32_e32 v6, v0
	v_mov_b32_e32 v7, v0
	v_mov_b32_e32 v8, v0
	v_mov_b32_e32 v9, v0
	v_mov_b32_e32 v10, v0
	v_mov_b32_e32 v11, v0
	v_mov_b32_e32 v12, v0
	v_mov_b32_e32 v13, v0
	v_mov_b32_e32 v14, v0
	v_mov_b32_e32 v15, v0
	v_mov_b32_e32 v16, v0
	v_mov_b32_e32 v17, v0
	v_mov_b32_e32 v18, v0
	v_mov_b32_e32 v19, v0
	v_mov_b32_e32 v20, v0
	v_mov_b32_e32 v21, v0
	v_mov_b32_e32 v22, v0
	v_mov_b32_e32 v23, v0
	v_mov_b32_e32 v24, v0
	v_mov_b32_e32 v25, v0
	v_mov_b32_e32 v26, v0
	v_mov_b32_e32 v27, v0
	v_mov_b32_e32 v28, v0
	v_mov_b32_e32 v29, v0
	v_mov_b32_e32 v30, v0
	v_mov_b32_e32 v31, v0
	s_waitcnt vmcnt(0)
	v_mov_b32_e32 v32, v0
	v_mov_b32_e32 v33, v0
	v_mov_b32_e32 v34, v0
	v_mov_b32_e32 v35, v0
	v_mov_b32_e32 v36, v0
	v_mov_b32_e32 v37, v0
	v_mov_b32_e32 v38, v0
	v_mov_b32_e32 v39, v0
	v_mov_b32_e32 v40, v0
	v_mov_b32_e32 v41, v0
	v_mov_b32_e32 v42, v0
	v_mov_b32_e32 v43, v0
	v_mov_b32_e32 v44, v0
	v_mov_b32_e32 v45, v0
	v_mov_b32_e32 v46, v0
	v_mov_b32_e32 v47, v0
	v_mov_b32_e32 v48, v0
	v_mov_b32_e32 v49, v0
	v_mov_b32_e32 v50, v0
	v_mov_b32_e32 v51, v0
	v_mov_b32_e32 v52, v0
	v_mov_b32_e32 v53, v0
	v_mov_b32_e32 v54, v0
	v_mov_b32_e32 v55, v0
	v_mov_b32_e32 v56, v0
	v_mov_b32_e32 v57, v0
	v_mov_b32_e32 v58, v0
	v_mov_b32_e32 v59, v0
	v_mov_b32_e32 v60, v0
	v_mov_b32_e32 v61, v0
	v_mov_b32_e32 v62, v0
	v_mov_b32_e32 v63, v0
	s_waitcnt lgkmcnt(0)
	s_barrier
	v_add3_u32 v186, 0, v134, v135
	v_add_u32_e32 v187, 0x4000, v186
	s_nop 0
	v_readfirstlane_b32 s82, v187
	s_nop 0
	v_readfirstlane_b32 s83, v186
	v_subrev_u32_e32 v188, s52, v88
	v_subrev_u32_e32 v189, s52, v90
	v_subrev_u32_e32 v190, s52, v92
	v_subrev_u32_e32 v191, s52, v94
	v_subrev_u32_e32 v192, s52, v96
	v_subrev_u32_e32 v193, s52, v98
	v_subrev_u32_e32 v194, s52, v100
	v_subrev_u32_e32 v195, s52, v102
	v_subrev_u32_e32 v191, 0x400, v191
	v_subrev_u32_e32 v190, 0x400, v190
	v_subrev_u32_e32 v193, 0x800, v193
	v_subrev_u32_e32 v192, 0x800, v192
	v_subrev_u32_e32 v195, 0xc00, v195
	v_subrev_u32_e32 v194, 0xc00, v194
	s_and_b32 s29, s27, 0x4000
	s_xor_b32 s28, s29, 0x4000
	s_lshl_b32 s28, s28, 1
	s_add_i32 s28, s28, 32
	s_lshl_b32 s29, s29, 1
	s_add_i32 s29, s29, 32

.LBB0_1833:
	s_and_b32 s12, s18, 0x380
	v_add_lshl_u32 v70, v138, s12, 11
	v_lshl_add_u64 v[96:97], v[84:85], 0, v[70:71]
	v_add_lshl_u32 v70, v140, s12, 11
	v_lshl_add_u64 v[98:99], v[88:89], 0, v[70:71]
	v_add_lshl_u32 v70, v142, s12, 11
	s_lshl_b32 s24, s23, 7
	v_lshl_add_u64 v[100:101], v[84:85], 0, v[70:71]
	v_add_lshl_u32 v70, v144, s12, 11
	s_ashr_i32 s12, s23, 3
	s_and_b32 s24, s24, 0x380
	v_add_u32_e32 v2, 0x4000, v133
	v_lshl_add_u64 v[102:103], v[92:93], 0, v[70:71]
	s_add_i32 s13, s12, s17
	v_add_lshl_u32 v70, s24, v132, 11
	v_readfirstlane_b32 s25, v2
	s_lshl_b32 s13, s13, 7
	v_lshl_add_u64 v[0:1], v[72:73], 0, v[70:71]
	s_mov_b32 m0, s25
	v_readfirstlane_b32 s25, v133
	global_load_lds_dwordx4 v[0:1], off
	v_add_u32_e32 v0, s13, v132
	v_ashrrev_i32_e32 v1, 31, v0
	v_lshlrev_b64 v[0:1], 11, v[0:1]
	v_lshl_add_u64 v[0:1], v[78:79], 0, v[0:1]
	s_mov_b32 m0, s25
	v_add_lshl_u32 v70, s24, v119, 11
	v_readfirstlane_b32 s25, v148
	global_load_lds_dwordx4 v[0:1], off
	v_lshl_add_u64 v[0:1], v[74:75], 0, v[70:71]
	s_mov_b32 m0, s25
	v_add_u32_e32 v2, 0x400, v133
	global_load_lds_dwordx4 v[0:1], off
	v_add_u32_e32 v0, s13, v119
	v_ashrrev_i32_e32 v1, 31, v0
	v_lshlrev_b64 v[0:1], 11, v[0:1]
	v_readfirstlane_b32 s25, v2
	v_lshl_add_u64 v[0:1], v[80:81], 0, v[0:1]
	s_mov_b32 m0, s25
	v_add_lshl_u32 v70, s24, v120, 11
	v_readfirstlane_b32 s25, v149
	global_load_lds_dwordx4 v[0:1], off
	v_lshl_add_u64 v[0:1], v[72:73], 0, v[70:71]
	s_mov_b32 m0, s25
	v_add_u32_e32 v2, 0x800, v133
	global_load_lds_dwordx4 v[0:1], off
	v_add_u32_e32 v0, s13, v120
	v_ashrrev_i32_e32 v1, 31, v0
	v_lshlrev_b64 v[0:1], 11, v[0:1]
	v_readfirstlane_b32 s25, v2
	v_lshl_add_u64 v[0:1], v[78:79], 0, v[0:1]
	s_mov_b32 m0, s25
	v_add_lshl_u32 v70, s24, v118, 11
	v_readfirstlane_b32 s25, v150
	global_load_lds_dwordx4 v[0:1], off
	v_lshl_add_u64 v[0:1], v[76:77], 0, v[70:71]
	s_mov_b32 m0, s25
	v_add_u32_e32 v2, 0xc00, v133
	global_load_lds_dwordx4 v[0:1], off
	v_add_u32_e32 v0, s13, v118
	v_ashrrev_i32_e32 v1, 31, v0
	v_lshlrev_b64 v[0:1], 11, v[0:1]
	v_readfirstlane_b32 s13, v2
	v_lshl_add_u64 v[0:1], v[82:83], 0, v[0:1]
	s_mov_b32 m0, s13
	s_lshl_b32 s25, s12, 7
	global_load_lds_dwordx4 v[0:1], off
	v_add_u32_e32 v0, s25, v139
	v_ashrrev_i32_e32 v1, 31, v0
	v_lshlrev_b64 v[0:1], 11, v[0:1]
	v_lshl_add_u64 v[104:105], v[86:87], 0, v[0:1]
	v_add_u32_e32 v0, s25, v141
	v_ashrrev_i32_e32 v1, 31, v0
	v_lshlrev_b64 v[0:1], 11, v[0:1]
	v_lshl_add_u64 v[106:107], v[90:91], 0, v[0:1]
	v_add_u32_e32 v0, s25, v143
	v_ashrrev_i32_e32 v1, 31, v0
	v_lshlrev_b64 v[0:1], 11, v[0:1]
	v_lshl_add_u64 v[108:109], v[86:87], 0, v[0:1]
	v_add_u32_e32 v0, s25, v145
	v_ashrrev_i32_e32 v1, 31, v0
	v_lshlrev_b64 v[0:1], 11, v[0:1]
	v_lshl_add_u64 v[110:111], v[94:95], 0, v[0:1]
	s_mov_b64 s[12:13], 0
	s_mov_b32 s26, 0
	v_mov_b32_e32 v0, 0
	v_mov_b32_e32 v1, v71
	v_mov_b32_e32 v2, v71
	v_mov_b32_e32 v3, v71
	v_mov_b32_e32 v4, 0
	v_mov_b32_e32 v5, v71
	v_mov_b32_e32 v6, v71
	v_mov_b32_e32 v7, v71
	v_mov_b32_e32 v8, 0
	v_mov_b32_e32 v9, v71
	v_mov_b32_e32 v10, v71
	v_mov_b32_e32 v11, v71
	v_mov_b32_e32 v12, 0
	v_mov_b32_e32 v13, v71
	v_mov_b32_e32 v14, v71
	v_mov_b32_e32 v15, v71
	v_mov_b32_e32 v16, 0
	v_mov_b32_e32 v17, v71
	v_mov_b32_e32 v18, v71
	v_mov_b32_e32 v19, v71
	v_mov_b32_e32 v20, 0
	v_mov_b32_e32 v21, v71
	v_mov_b32_e32 v22, v71
	v_mov_b32_e32 v23, v71
	v_mov_b32_e32 v24, 0
	v_mov_b32_e32 v25, v71
	v_mov_b32_e32 v26, v71
	v_mov_b32_e32 v27, v71
	v_mov_b32_e32 v28, 0
	v_mov_b32_e32 v29, v71
	v_mov_b32_e32 v30, v71
	v_mov_b32_e32 v31, v71
	s_waitcnt vmcnt(0)
	v_mov_b32_e32 v32, 0
	v_mov_b32_e32 v33, v71
	v_mov_b32_e32 v34, v71
	v_mov_b32_e32 v35, v71
	v_mov_b32_e32 v36, 0
	v_mov_b32_e32 v37, v71
	v_mov_b32_e32 v38, v71
	v_mov_b32_e32 v39, v71
	v_mov_b32_e32 v40, 0
	v_mov_b32_e32 v41, v71
	v_mov_b32_e32 v42, v71
	v_mov_b32_e32 v43, v71
	v_mov_b32_e32 v44, 0
	v_mov_b32_e32 v45, v71
	v_mov_b32_e32 v46, v71
	v_mov_b32_e32 v47, v71
	v_mov_b32_e32 v48, 0
	v_mov_b32_e32 v49, v71
	v_mov_b32_e32 v50, v71
	v_mov_b32_e32 v51, v71
	v_mov_b32_e32 v52, 0
	v_mov_b32_e32 v53, v71
	v_mov_b32_e32 v54, v71
	v_mov_b32_e32 v55, v71
	v_mov_b32_e32 v56, 0
	v_mov_b32_e32 v57, v71
	v_mov_b32_e32 v58, v71
	v_mov_b32_e32 v59, v71
	v_mov_b32_e32 v60, 0
	v_mov_b32_e32 v61, v71
	v_mov_b32_e32 v62, v71
	v_mov_b32_e32 v63, v71
	s_waitcnt lgkmcnt(0)
	s_barrier
	v_lshlrev_b32_e32 v186, 1, v130
	v_lshlrev_b32_e32 v187, 1, v131
	v_add3_u32 v186, 0, v186, v187
	v_add_u32_e32 v188, 0x4000, v186
	s_nop 0
	v_readfirstlane_b32 s82, v188
	s_nop 0
	v_readfirstlane_b32 s83, v186
	v_subrev_u32_e32 v189, s52, v96
	v_subrev_u32_e32 v190, s52, v104
	v_subrev_u32_e32 v191, s52, v98
	v_subrev_u32_e32 v192, s52, v106
	v_subrev_u32_e32 v193, s52, v100
	v_subrev_u32_e32 v194, s52, v108
	v_subrev_u32_e32 v195, s52, v102
	v_subrev_u32_e32 v196, s52, v110
	v_subrev_u32_e32 v192, 0x400, v192
	v_subrev_u32_e32 v191, 0x400, v191
	v_subrev_u32_e32 v194, 0x800, v194
	v_subrev_u32_e32 v193, 0x800, v193
	v_subrev_u32_e32 v196, 0xc00, v196
	v_subrev_u32_e32 v195, 0xc00, v195
	s_and_b32 s28, s26, 0x4000
	s_xor_b32 s27, s28, 0x4000
	s_lshl_b32 s27, s27, 1
	s_add_i32 s27, s27, 32
	s_lshl_b32 s28, s28, 1
	s_add_i32 s28, s28, 32

.LBB0_1997:
	s_ashr_i32 s12, s16, 31
	s_lshr_b32 s12, s12, 27
	s_add_i32 s12, s16, s12
	s_ashr_i32 s12, s12, 5
	s_lshl_b32 s17, s12, 7
	s_lshl_b32 s12, s12, 12
	s_lshl_b32 s13, s16, 7
	s_sub_i32 s18, s13, s12
	v_add_u32_e32 v0, s18, v106
	v_ashrrev_i32_e32 v1, 31, v0
	v_add_u32_e32 v2, 0x4000, v107
	v_lshlrev_b64 v[0:1], 11, v[0:1]
	v_readfirstlane_b32 s13, v2
	v_lshl_add_u64 v[0:1], v[66:67], 0, v[0:1]
	s_mov_b32 m0, s13
	v_readfirstlane_b32 s13, v107
	global_load_lds_dwordx4 v[0:1], off
	v_add_u32_e32 v0, s17, v106
	v_ashrrev_i32_e32 v1, 31, v0
	v_lshlrev_b64 v[0:1], 11, v[0:1]
	v_lshl_add_u64 v[2:3], v[72:73], 0, v[0:1]
	s_mov_b32 m0, s13
	v_readfirstlane_b32 s13, v130
	global_load_lds_dwordx4 v[2:3], off
	v_add_u32_e32 v2, s18, v108
	v_ashrrev_i32_e32 v3, 31, v2
	v_lshlrev_b64 v[2:3], 11, v[2:3]
	v_lshl_add_u64 v[2:3], v[68:69], 0, v[2:3]
	s_mov_b32 m0, s13
	v_add_u32_e32 v4, 0x400, v107
	global_load_lds_dwordx4 v[2:3], off
	v_add_u32_e32 v2, s17, v108
	v_ashrrev_i32_e32 v3, 31, v2
	v_lshlrev_b64 v[2:3], 11, v[2:3]
	v_readfirstlane_b32 s13, v4
	v_lshl_add_u64 v[2:3], v[74:75], 0, v[2:3]
	s_mov_b32 m0, s13
	v_readfirstlane_b32 s13, v131
	global_load_lds_dwordx4 v[2:3], off
	v_add_u32_e32 v2, s18, v110
	v_ashrrev_i32_e32 v3, 31, v2
	v_lshlrev_b64 v[2:3], 11, v[2:3]
	v_lshl_add_u64 v[2:3], v[66:67], 0, v[2:3]
	s_mov_b32 m0, s13
	v_add_u32_e32 v4, 0x800, v107
	global_load_lds_dwordx4 v[2:3], off
	v_add_u32_e32 v2, s17, v110
	v_ashrrev_i32_e32 v3, 31, v2
	v_lshlrev_b64 v[2:3], 11, v[2:3]
	v_readfirstlane_b32 s13, v4
	v_lshl_add_u64 v[2:3], v[72:73], 0, v[2:3]
	s_mov_b32 m0, s13
	v_readfirstlane_b32 s13, v132
	global_load_lds_dwordx4 v[2:3], off
	v_add_u32_e32 v2, s18, v112
	v_ashrrev_i32_e32 v3, 31, v2
	v_lshlrev_b64 v[2:3], 11, v[2:3]
	v_lshl_add_u64 v[2:3], v[70:71], 0, v[2:3]
	s_mov_b32 m0, s13
	v_add_u32_e32 v4, 0xc00, v107
	global_load_lds_dwordx4 v[2:3], off
	v_add_u32_e32 v2, s17, v112
	v_ashrrev_i32_e32 v3, 31, v2
	v_lshlrev_b64 v[2:3], 11, v[2:3]
	v_readfirstlane_b32 s13, v4
	v_lshl_add_u64 v[2:3], v[76:77], 0, v[2:3]
	s_mov_b32 m0, s13
	v_lshl_add_u64 v[92:93], v[80:81], 0, v[0:1]
	global_load_lds_dwordx4 v[2:3], off
	v_subrev_u32_e32 v0, s12, v123
	v_ashrrev_i32_e32 v1, 31, v0
	v_lshlrev_b64 v[0:1], 11, v[0:1]
	v_lshl_add_u64 v[94:95], v[82:83], 0, v[0:1]
	v_add_u32_e32 v0, s17, v124
	v_ashrrev_i32_e32 v1, 31, v0
	v_lshlrev_b64 v[0:1], 11, v[0:1]
	v_lshl_add_u64 v[96:97], v[84:85], 0, v[0:1]
	v_subrev_u32_e32 v0, s12, v125
	v_ashrrev_i32_e32 v1, 31, v0
	v_lshlrev_b64 v[0:1], 11, v[0:1]
	v_lshl_add_u64 v[98:99], v[78:79], 0, v[0:1]
	v_add_u32_e32 v0, s17, v126
	v_ashrrev_i32_e32 v1, 31, v0
	v_lshlrev_b64 v[0:1], 11, v[0:1]
	v_lshl_add_u64 v[100:101], v[80:81], 0, v[0:1]
	v_subrev_u32_e32 v0, s12, v64
	v_ashrrev_i32_e32 v1, 31, v0
	v_lshlrev_b64 v[0:1], 11, v[0:1]
	v_subrev_u32_e32 v2, s12, v122
	v_lshl_add_u64 v[102:103], v[86:87], 0, v[0:1]
	v_add_u32_e32 v0, s17, v127
	v_ashrrev_i32_e32 v3, 31, v2
	v_ashrrev_i32_e32 v1, 31, v0
	v_lshlrev_b64 v[2:3], 11, v[2:3]
	v_lshlrev_b64 v[0:1], 11, v[0:1]
	v_lshl_add_u64 v[90:91], v[78:79], 0, v[2:3]
	v_lshl_add_u64 v[104:105], v[88:89], 0, v[0:1]
	s_mov_b64 s[12:13], 0
	s_mov_b32 s19, 0
	v_mov_b32_e32 v0, 0
	v_mov_b32_e32 v1, v65
	v_mov_b32_e32 v2, v65
	v_mov_b32_e32 v3, v65
	v_mov_b32_e32 v4, 0
	v_mov_b32_e32 v5, v65
	v_mov_b32_e32 v6, v65
	v_mov_b32_e32 v7, v65
	v_mov_b32_e32 v8, 0
	v_mov_b32_e32 v9, v65
	v_mov_b32_e32 v10, v65
	v_mov_b32_e32 v11, v65
	v_mov_b32_e32 v12, 0
	v_mov_b32_e32 v13, v65
	v_mov_b32_e32 v14, v65
	v_mov_b32_e32 v15, v65
	v_mov_b32_e32 v16, 0
	v_mov_b32_e32 v17, v65
	v_mov_b32_e32 v18, v65
	v_mov_b32_e32 v19, v65
	v_mov_b32_e32 v20, 0
	v_mov_b32_e32 v21, v65
	v_mov_b32_e32 v22, v65
	v_mov_b32_e32 v23, v65
	v_mov_b32_e32 v24, 0
	v_mov_b32_e32 v25, v65
	v_mov_b32_e32 v26, v65
	v_mov_b32_e32 v27, v65
	v_mov_b32_e32 v28, 0
	v_mov_b32_e32 v29, v65
	v_mov_b32_e32 v30, v65
	v_mov_b32_e32 v31, v65
	v_mov_b32_e32 v32, 0
	v_mov_b32_e32 v33, v65
	v_mov_b32_e32 v34, v65
	v_mov_b32_e32 v35, v65
	v_mov_b32_e32 v36, 0
	v_mov_b32_e32 v37, v65
	v_mov_b32_e32 v38, v65
	v_mov_b32_e32 v39, v65
	v_mov_b32_e32 v40, 0
	v_mov_b32_e32 v41, v65
	v_mov_b32_e32 v42, v65
	v_mov_b32_e32 v43, v65
	v_mov_b32_e32 v44, 0
	v_mov_b32_e32 v45, v65
	v_mov_b32_e32 v46, v65
	v_mov_b32_e32 v47, v65
	v_mov_b32_e32 v48, 0
	v_mov_b32_e32 v49, v65
	v_mov_b32_e32 v50, v65
	v_mov_b32_e32 v51, v65
	v_mov_b32_e32 v52, 0
	v_mov_b32_e32 v53, v65
	v_mov_b32_e32 v54, v65
	v_mov_b32_e32 v55, v65
	v_mov_b32_e32 v56, 0
	v_mov_b32_e32 v57, v65
	v_mov_b32_e32 v58, v65
	v_mov_b32_e32 v59, v65
	v_mov_b32_e32 v60, 0
	v_mov_b32_e32 v61, v65
	v_mov_b32_e32 v62, v65
	v_mov_b32_e32 v63, v65
	s_waitcnt vmcnt(0) lgkmcnt(0)
	s_barrier
	v_add3_u32 v182, 0, v133, v134
	v_add_u32_e32 v183, 0x4000, v182
	s_nop 0
	v_readfirstlane_b32 s82, v183
	s_nop 0
	v_readfirstlane_b32 s83, v182
	v_subrev_u32_e32 v184, s52, v90
	v_subrev_u32_e32 v185, s52, v92
	v_subrev_u32_e32 v186, s52, v94
	v_subrev_u32_e32 v187, s52, v96
	v_subrev_u32_e32 v188, s52, v98
	v_subrev_u32_e32 v189, s52, v100
	v_subrev_u32_e32 v190, s52, v102
	v_subrev_u32_e32 v191, s52, v104
	v_subrev_u32_e32 v187, 0x400, v187
	v_subrev_u32_e32 v186, 0x400, v186
	v_subrev_u32_e32 v189, 0x800, v189
	v_subrev_u32_e32 v188, 0x800, v188
	v_subrev_u32_e32 v191, 0xc00, v191
	v_subrev_u32_e32 v190, 0xc00, v190
	s_and_b32 s21, s19, 0x4000
	s_xor_b32 s20, s21, 0x4000
	s_lshl_b32 s20, s20, 1
	s_add_i32 s20, s20, 32
	s_lshl_b32 s21, s21, 1
	s_add_i32 s21, s21, 32

.LBB0_2008:
	s_ashr_i32 s14, s9, 31
	s_lshr_b32 s14, s14, 29
	s_add_i32 s14, s9, s14
	s_ashr_i32 s15, s14, 3
	s_lshl_b32 s16, s15, 10
	s_lshl_b32 s9, s9, 7
	s_sub_i32 s14, s9, s16
	v_add_u32_e32 v0, s15, v104
	s_add_i32 s14, s14, s8
	v_lshlrev_b32_e32 v2, 7, v0
	v_add_u32_e32 v0, s14, v105
	v_ashrrev_i32_e32 v1, 31, v0
	v_add_u32_e32 v3, 0x4000, v106
	v_lshlrev_b64 v[0:1], 11, v[0:1]
	v_readfirstlane_b32 s17, v3
	v_lshl_add_u64 v[0:1], v[64:65], 0, v[0:1]
	s_mov_b32 m0, s17
	v_readfirstlane_b32 s17, v106
	global_load_lds_dwordx4 v[0:1], off
	v_add_u32_e32 v0, v2, v105
	v_ashrrev_i32_e32 v1, 31, v0
	v_lshlrev_b64 v[0:1], 11, v[0:1]
	v_lshl_add_u64 v[0:1], v[70:71], 0, v[0:1]
	s_mov_b32 m0, s17
	v_readfirstlane_b32 s17, v130
	global_load_lds_dwordx4 v[0:1], off
	v_add_u32_e32 v0, s14, v107
	v_ashrrev_i32_e32 v1, 31, v0
	v_lshlrev_b64 v[0:1], 11, v[0:1]
	v_lshl_add_u64 v[0:1], v[66:67], 0, v[0:1]
	s_mov_b32 m0, s17
	v_add_u32_e32 v3, 0x400, v106
	global_load_lds_dwordx4 v[0:1], off
	v_add_u32_e32 v0, v2, v107
	v_ashrrev_i32_e32 v1, 31, v0
	v_lshlrev_b64 v[0:1], 11, v[0:1]
	v_readfirstlane_b32 s17, v3
	v_lshl_add_u64 v[0:1], v[72:73], 0, v[0:1]
	s_mov_b32 m0, s17
	v_readfirstlane_b32 s17, v131
	global_load_lds_dwordx4 v[0:1], off
	v_add_u32_e32 v0, s14, v109
	v_ashrrev_i32_e32 v1, 31, v0
	v_lshlrev_b64 v[0:1], 11, v[0:1]
	v_lshl_add_u64 v[0:1], v[64:65], 0, v[0:1]
	s_mov_b32 m0, s17
	v_add_u32_e32 v3, 0x800, v106
	global_load_lds_dwordx4 v[0:1], off
	v_add_u32_e32 v0, v2, v109
	v_ashrrev_i32_e32 v1, 31, v0
	v_lshlrev_b64 v[0:1], 11, v[0:1]
	v_readfirstlane_b32 s17, v3
	v_lshl_add_u64 v[0:1], v[70:71], 0, v[0:1]
	s_mov_b32 m0, s17
	v_readfirstlane_b32 s17, v132
	global_load_lds_dwordx4 v[0:1], off
	v_add_u32_e32 v0, s14, v111
	v_ashrrev_i32_e32 v1, 31, v0
	v_lshlrev_b64 v[0:1], 11, v[0:1]
	v_lshl_add_u64 v[0:1], v[68:69], 0, v[0:1]
	s_mov_b32 m0, s17
	s_add_i32 s9, s9, s8
	global_load_lds_dwordx4 v[0:1], off
	v_add_u32_e32 v0, v2, v111
	v_ashrrev_i32_e32 v1, 31, v0
	v_add_u32_e32 v2, 0xc00, v106
	v_lshlrev_b64 v[0:1], 11, v[0:1]
	v_readfirstlane_b32 s17, v2
	v_lshl_add_u64 v[0:1], v[74:75], 0, v[0:1]
	s_mov_b32 m0, s17
	s_lshl_b32 s15, s15, 7
	global_load_lds_dwordx4 v[0:1], off
	v_add_u32_e32 v0, s9, v105
	v_subrev_u32_e32 v0, s16, v0
	v_ashrrev_i32_e32 v1, 31, v0
	v_lshlrev_b64 v[0:1], 11, v[0:1]
	v_lshl_add_u64 v[88:89], v[76:77], 0, v[0:1]
	v_add_u32_e32 v0, s15, v121
	v_ashrrev_i32_e32 v1, 31, v0
	v_lshlrev_b64 v[0:1], 11, v[0:1]
	v_lshl_add_u64 v[90:91], v[78:79], 0, v[0:1]
	v_add_u32_e32 v0, s9, v122
	v_subrev_u32_e32 v0, s16, v0
	v_ashrrev_i32_e32 v1, 31, v0
	v_lshlrev_b64 v[0:1], 11, v[0:1]
	v_lshl_add_u64 v[92:93], v[80:81], 0, v[0:1]
	v_add_u32_e32 v0, s15, v123
	v_ashrrev_i32_e32 v1, 31, v0
	v_lshlrev_b64 v[0:1], 11, v[0:1]
	v_lshl_add_u64 v[94:95], v[82:83], 0, v[0:1]
	v_add_u32_e32 v0, s9, v124
	v_subrev_u32_e32 v0, s16, v0
	v_ashrrev_i32_e32 v1, 31, v0
	v_lshlrev_b64 v[0:1], 11, v[0:1]
	v_lshl_add_u64 v[96:97], v[76:77], 0, v[0:1]
	v_add_u32_e32 v0, s15, v125
	v_ashrrev_i32_e32 v1, 31, v0
	v_lshlrev_b64 v[0:1], 11, v[0:1]
	v_lshl_add_u64 v[98:99], v[78:79], 0, v[0:1]
	v_add_u32_e32 v0, s9, v126
	v_subrev_u32_e32 v0, s16, v0
	v_ashrrev_i32_e32 v1, 31, v0
	v_lshlrev_b64 v[0:1], 11, v[0:1]
	v_lshl_add_u64 v[100:101], v[84:85], 0, v[0:1]
	v_add_u32_e32 v0, s15, v127
	v_ashrrev_i32_e32 v1, 31, v0
	v_lshlrev_b64 v[0:1], 11, v[0:1]
	v_lshl_add_u64 v[102:103], v[86:87], 0, v[0:1]
	v_mov_b32_e32 v0, 0
	s_mov_b32 s16, 0
	s_mov_b64 s[8:9], 0
	v_mov_b32_e32 v1, v0
	v_mov_b32_e32 v2, v0
	v_mov_b32_e32 v3, v0
	v_mov_b32_e32 v4, v0
	v_mov_b32_e32 v5, v0
	v_mov_b32_e32 v6, v0
	v_mov_b32_e32 v7, v0
	v_mov_b32_e32 v8, v0
	v_mov_b32_e32 v9, v0
	v_mov_b32_e32 v10, v0
	v_mov_b32_e32 v11, v0
	v_mov_b32_e32 v12, v0
	v_mov_b32_e32 v13, v0
	v_mov_b32_e32 v14, v0
	v_mov_b32_e32 v15, v0
	v_mov_b32_e32 v16, v0
	v_mov_b32_e32 v17, v0
	v_mov_b32_e32 v18, v0
	v_mov_b32_e32 v19, v0
	v_mov_b32_e32 v20, v0
	v_mov_b32_e32 v21, v0
	v_mov_b32_e32 v22, v0
	v_mov_b32_e32 v23, v0
	v_mov_b32_e32 v24, v0
	v_mov_b32_e32 v25, v0
	v_mov_b32_e32 v26, v0
	v_mov_b32_e32 v27, v0
	v_mov_b32_e32 v28, v0
	v_mov_b32_e32 v29, v0
	v_mov_b32_e32 v30, v0
	v_mov_b32_e32 v31, v0
	v_mov_b32_e32 v32, v0
	v_mov_b32_e32 v33, v0
	v_mov_b32_e32 v34, v0
	v_mov_b32_e32 v35, v0
	v_mov_b32_e32 v36, v0
	v_mov_b32_e32 v37, v0
	v_mov_b32_e32 v38, v0
	v_mov_b32_e32 v39, v0
	v_mov_b32_e32 v40, v0
	v_mov_b32_e32 v41, v0
	v_mov_b32_e32 v42, v0
	v_mov_b32_e32 v43, v0
	v_mov_b32_e32 v44, v0
	v_mov_b32_e32 v45, v0
	v_mov_b32_e32 v46, v0
	v_mov_b32_e32 v47, v0
	v_mov_b32_e32 v48, v0
	v_mov_b32_e32 v49, v0
	v_mov_b32_e32 v50, v0
	v_mov_b32_e32 v51, v0
	v_mov_b32_e32 v52, v0
	v_mov_b32_e32 v53, v0
	v_mov_b32_e32 v54, v0
	v_mov_b32_e32 v55, v0
	v_mov_b32_e32 v56, v0
	v_mov_b32_e32 v57, v0
	v_mov_b32_e32 v58, v0
	v_mov_b32_e32 v59, v0
	v_mov_b32_e32 v60, v0
	v_mov_b32_e32 v61, v0
	v_mov_b32_e32 v62, v0
	v_mov_b32_e32 v63, v0
	s_waitcnt vmcnt(0) lgkmcnt(0)
	s_barrier
	v_add3_u32 v182, 0, v133, v134
	v_add_u32_e32 v183, 0x4000, v182
	s_nop 0
	v_readfirstlane_b32 s82, v183
	s_nop 0
	v_readfirstlane_b32 s83, v182
	v_subrev_u32_e32 v184, s52, v88
	v_subrev_u32_e32 v185, s52, v90
	v_subrev_u32_e32 v186, s52, v92
	v_subrev_u32_e32 v187, s52, v94
	v_subrev_u32_e32 v188, s52, v96
	v_subrev_u32_e32 v189, s52, v98
	v_subrev_u32_e32 v190, s52, v100
	v_subrev_u32_e32 v191, s52, v102
	v_subrev_u32_e32 v187, 0x400, v187
	v_subrev_u32_e32 v186, 0x400, v186
	v_subrev_u32_e32 v189, 0x800, v189
	v_subrev_u32_e32 v188, 0x800, v188
	v_subrev_u32_e32 v191, 0xc00, v191
	v_subrev_u32_e32 v190, 0xc00, v190
	s_and_b32 s18, s16, 0x4000
	s_xor_b32 s17, s18, 0x4000
	s_lshl_b32 s17, s17, 1
	s_add_i32 s17, s17, 32
	s_lshl_b32 s18, s18, 1
	s_add_i32 s18, s18, 32

.LBB0_2075:
	s_ashr_i32 s16, s23, 31
	s_lshr_b32 s16, s16, 29
	s_add_i32 s16, s23, s16
	s_ashr_i32 s16, s16, 3
	s_lshl_b32 s24, s16, 7
	s_lshl_b32 s16, s16, 10
	s_lshl_b32 s17, s23, 7
	s_sub_i32 s25, s17, s16
	v_add_u32_e32 v0, s25, v106
	v_ashrrev_i32_e32 v1, 31, v0
	v_add_u32_e32 v2, 0x4000, v107
	v_lshlrev_b64 v[0:1], 13, v[0:1]
	v_readfirstlane_b32 s17, v2
	v_lshl_add_u64 v[0:1], v[66:67], 0, v[0:1]
	s_mov_b32 m0, s17
	v_readfirstlane_b32 s17, v107
	global_load_lds_dwordx4 v[0:1], off
	v_add_u32_e32 v0, s24, v106
	v_ashrrev_i32_e32 v1, 31, v0
	v_lshlrev_b64 v[0:1], 13, v[0:1]
	v_lshl_add_u64 v[2:3], v[72:73], 0, v[0:1]
	s_mov_b32 m0, s17
	v_readfirstlane_b32 s17, v130
	global_load_lds_dwordx4 v[2:3], off
	v_add_u32_e32 v2, s25, v108
	v_ashrrev_i32_e32 v3, 31, v2
	v_lshlrev_b64 v[2:3], 13, v[2:3]
	v_lshl_add_u64 v[2:3], v[68:69], 0, v[2:3]
	s_mov_b32 m0, s17
	v_add_u32_e32 v4, 0x400, v107
	global_load_lds_dwordx4 v[2:3], off
	v_add_u32_e32 v2, s24, v108
	v_ashrrev_i32_e32 v3, 31, v2
	v_lshlrev_b64 v[2:3], 13, v[2:3]
	v_readfirstlane_b32 s17, v4
	v_lshl_add_u64 v[2:3], v[74:75], 0, v[2:3]
	s_mov_b32 m0, s17
	v_readfirstlane_b32 s17, v131
	global_load_lds_dwordx4 v[2:3], off
	v_add_u32_e32 v2, s25, v110
	v_ashrrev_i32_e32 v3, 31, v2
	v_lshlrev_b64 v[2:3], 13, v[2:3]
	v_lshl_add_u64 v[2:3], v[66:67], 0, v[2:3]
	s_mov_b32 m0, s17
	v_add_u32_e32 v4, 0x800, v107
	global_load_lds_dwordx4 v[2:3], off
	v_add_u32_e32 v2, s24, v110
	v_ashrrev_i32_e32 v3, 31, v2
	v_lshlrev_b64 v[2:3], 13, v[2:3]
	v_readfirstlane_b32 s17, v4
	v_lshl_add_u64 v[2:3], v[72:73], 0, v[2:3]
	s_mov_b32 m0, s17
	v_readfirstlane_b32 s17, v132
	global_load_lds_dwordx4 v[2:3], off
	v_add_u32_e32 v2, s25, v112
	v_ashrrev_i32_e32 v3, 31, v2
	v_lshlrev_b64 v[2:3], 13, v[2:3]
	v_lshl_add_u64 v[2:3], v[70:71], 0, v[2:3]
	s_mov_b32 m0, s17
	v_add_u32_e32 v4, 0xc00, v107
	global_load_lds_dwordx4 v[2:3], off
	v_add_u32_e32 v2, s24, v112
	v_ashrrev_i32_e32 v3, 31, v2
	v_lshlrev_b64 v[2:3], 13, v[2:3]
	v_readfirstlane_b32 s17, v4
	v_lshl_add_u64 v[2:3], v[76:77], 0, v[2:3]
	s_mov_b32 m0, s17
	v_lshl_add_u64 v[92:93], v[80:81], 0, v[0:1]
	global_load_lds_dwordx4 v[2:3], off
	v_subrev_u32_e32 v0, s16, v123
	v_ashrrev_i32_e32 v1, 31, v0
	v_lshlrev_b64 v[0:1], 13, v[0:1]
	v_lshl_add_u64 v[94:95], v[82:83], 0, v[0:1]
	v_add_u32_e32 v0, s24, v124
	v_ashrrev_i32_e32 v1, 31, v0
	v_lshlrev_b64 v[0:1], 13, v[0:1]
	v_lshl_add_u64 v[96:97], v[84:85], 0, v[0:1]
	v_subrev_u32_e32 v0, s16, v125
	v_ashrrev_i32_e32 v1, 31, v0
	v_lshlrev_b64 v[0:1], 13, v[0:1]
	v_lshl_add_u64 v[98:99], v[78:79], 0, v[0:1]
	v_add_u32_e32 v0, s24, v126
	v_ashrrev_i32_e32 v1, 31, v0
	v_lshlrev_b64 v[0:1], 13, v[0:1]
	v_lshl_add_u64 v[100:101], v[80:81], 0, v[0:1]
	v_subrev_u32_e32 v0, s16, v64
	v_ashrrev_i32_e32 v1, 31, v0
	v_lshlrev_b64 v[0:1], 13, v[0:1]
	v_subrev_u32_e32 v2, s16, v122
	v_lshl_add_u64 v[102:103], v[86:87], 0, v[0:1]
	v_add_u32_e32 v0, s24, v127
	v_ashrrev_i32_e32 v3, 31, v2
	v_ashrrev_i32_e32 v1, 31, v0
	v_lshlrev_b64 v[2:3], 13, v[2:3]
	v_lshlrev_b64 v[0:1], 13, v[0:1]
	v_lshl_add_u64 v[90:91], v[78:79], 0, v[2:3]
	v_lshl_add_u64 v[104:105], v[88:89], 0, v[0:1]
	s_mov_b32 s26, 0
	s_mov_b64 s[16:17], 0
	v_mov_b32_e32 v0, 0
	v_mov_b32_e32 v1, v65
	v_mov_b32_e32 v2, v65
	v_mov_b32_e32 v3, v65
	v_mov_b32_e32 v4, 0
	v_mov_b32_e32 v5, v65
	v_mov_b32_e32 v6, v65
	v_mov_b32_e32 v7, v65
	v_mov_b32_e32 v8, 0
	v_mov_b32_e32 v9, v65
	v_mov_b32_e32 v10, v65
	v_mov_b32_e32 v11, v65
	v_mov_b32_e32 v12, 0
	v_mov_b32_e32 v13, v65
	v_mov_b32_e32 v14, v65
	v_mov_b32_e32 v15, v65
	v_mov_b32_e32 v16, 0
	v_mov_b32_e32 v17, v65
	v_mov_b32_e32 v18, v65
	v_mov_b32_e32 v19, v65
	v_mov_b32_e32 v20, 0
	v_mov_b32_e32 v21, v65
	v_mov_b32_e32 v22, v65
	v_mov_b32_e32 v23, v65
	v_mov_b32_e32 v24, 0
	v_mov_b32_e32 v25, v65
	v_mov_b32_e32 v26, v65
	v_mov_b32_e32 v27, v65
	v_mov_b32_e32 v28, 0
	v_mov_b32_e32 v29, v65
	v_mov_b32_e32 v30, v65
	v_mov_b32_e32 v31, v65
	s_waitcnt vmcnt(0)
	v_mov_b32_e32 v32, 0
	v_mov_b32_e32 v33, v65
	v_mov_b32_e32 v34, v65
	v_mov_b32_e32 v35, v65
	v_mov_b32_e32 v36, 0
	v_mov_b32_e32 v37, v65
	v_mov_b32_e32 v38, v65
	v_mov_b32_e32 v39, v65
	v_mov_b32_e32 v40, 0
	v_mov_b32_e32 v41, v65
	v_mov_b32_e32 v42, v65
	v_mov_b32_e32 v43, v65
	v_mov_b32_e32 v44, 0
	v_mov_b32_e32 v45, v65
	v_mov_b32_e32 v46, v65
	v_mov_b32_e32 v47, v65
	v_mov_b32_e32 v48, 0
	v_mov_b32_e32 v49, v65
	v_mov_b32_e32 v50, v65
	v_mov_b32_e32 v51, v65
	v_mov_b32_e32 v52, 0
	v_mov_b32_e32 v53, v65
	v_mov_b32_e32 v54, v65
	v_mov_b32_e32 v55, v65
	v_mov_b32_e32 v56, 0
	v_mov_b32_e32 v57, v65
	v_mov_b32_e32 v58, v65
	v_mov_b32_e32 v59, v65
	v_mov_b32_e32 v60, 0
	v_mov_b32_e32 v61, v65
	v_mov_b32_e32 v62, v65
	v_mov_b32_e32 v63, v65
	s_waitcnt lgkmcnt(0)
	s_barrier
	v_add3_u32 v190, 0, v133, v134
	v_add_u32_e32 v191, 0x4000, v190
	s_nop 0
	v_readfirstlane_b32 s82, v191
	s_nop 0
	v_readfirstlane_b32 s83, v190
	v_subrev_u32_e32 v192, s52, v90
	v_subrev_u32_e32 v193, s52, v92
	v_subrev_u32_e32 v194, s52, v94
	v_subrev_u32_e32 v195, s52, v96
	v_subrev_u32_e32 v196, s52, v98
	v_subrev_u32_e32 v197, s52, v100
	v_subrev_u32_e32 v198, s52, v102
	v_subrev_u32_e32 v199, s52, v104
	v_subrev_u32_e32 v195, 0x400, v195
	v_subrev_u32_e32 v194, 0x400, v194
	v_subrev_u32_e32 v197, 0x800, v197
	v_subrev_u32_e32 v196, 0x800, v196
	v_subrev_u32_e32 v199, 0xc00, v199
	v_subrev_u32_e32 v198, 0xc00, v198
	s_and_b32 s28, s26, 0x4000
	s_xor_b32 s27, s28, 0x4000
	s_lshl_b32 s27, s27, 1
	s_add_i32 s27, s27, 32
	s_lshl_b32 s28, s28, 1
	s_add_i32 s28, s28, 32

.LBB0_2084:
	s_ashr_i32 s16, s18, 31
	s_lshr_b32 s16, s16, 29
	s_add_i32 s16, s18, s16
	s_ashr_i32 s16, s16, 3
	s_lshl_b32 s17, s16, 10
	s_lshl_b32 s25, s18, 7
	v_add_u32_e32 v0, s16, v104
	s_sub_i32 s25, s25, s17
	v_lshlrev_b32_e32 v2, 7, v0
	v_add_u32_e32 v0, s25, v105
	v_ashrrev_i32_e32 v1, 31, v0
	v_add_u32_e32 v3, 0x4000, v106
	v_lshlrev_b64 v[0:1], 13, v[0:1]
	v_readfirstlane_b32 s26, v3
	v_lshl_add_u64 v[0:1], v[64:65], 0, v[0:1]
	s_mov_b32 m0, s26
	v_readfirstlane_b32 s26, v106
	global_load_lds_dwordx4 v[0:1], off
	v_add_u32_e32 v0, v2, v105
	v_ashrrev_i32_e32 v1, 31, v0
	v_lshlrev_b64 v[0:1], 13, v[0:1]
	v_lshl_add_u64 v[0:1], v[70:71], 0, v[0:1]
	s_mov_b32 m0, s26
	v_readfirstlane_b32 s26, v131
	global_load_lds_dwordx4 v[0:1], off
	v_add_u32_e32 v0, s25, v107
	v_ashrrev_i32_e32 v1, 31, v0
	v_lshlrev_b64 v[0:1], 13, v[0:1]
	v_lshl_add_u64 v[0:1], v[66:67], 0, v[0:1]
	s_mov_b32 m0, s26
	v_add_u32_e32 v3, 0x400, v106
	global_load_lds_dwordx4 v[0:1], off
	v_add_u32_e32 v0, v2, v107
	v_ashrrev_i32_e32 v1, 31, v0
	v_lshlrev_b64 v[0:1], 13, v[0:1]
	v_readfirstlane_b32 s26, v3
	v_lshl_add_u64 v[0:1], v[72:73], 0, v[0:1]
	s_mov_b32 m0, s26
	v_readfirstlane_b32 s26, v132
	global_load_lds_dwordx4 v[0:1], off
	v_add_u32_e32 v0, s25, v109
	v_ashrrev_i32_e32 v1, 31, v0
	v_lshlrev_b64 v[0:1], 13, v[0:1]
	v_lshl_add_u64 v[0:1], v[64:65], 0, v[0:1]
	s_mov_b32 m0, s26
	v_add_u32_e32 v3, 0x800, v106
	global_load_lds_dwordx4 v[0:1], off
	v_add_u32_e32 v0, v2, v109
	v_ashrrev_i32_e32 v1, 31, v0
	v_lshlrev_b64 v[0:1], 13, v[0:1]
	v_readfirstlane_b32 s26, v3
	v_lshl_add_u64 v[0:1], v[70:71], 0, v[0:1]
	s_mov_b32 m0, s26
	v_readfirstlane_b32 s26, v133
	global_load_lds_dwordx4 v[0:1], off
	v_add_u32_e32 v0, s25, v111
	v_ashrrev_i32_e32 v1, 31, v0
	v_lshlrev_b64 v[0:1], 13, v[0:1]
	v_lshl_add_u64 v[0:1], v[68:69], 0, v[0:1]
	s_mov_b32 m0, s26
	s_mov_b32 s27, 0
	global_load_lds_dwordx4 v[0:1], off
	v_add_u32_e32 v0, v2, v111
	v_ashrrev_i32_e32 v1, 31, v0
	v_add_u32_e32 v2, 0xc00, v106
	v_lshlrev_b64 v[0:1], 13, v[0:1]
	v_readfirstlane_b32 s26, v2
	v_lshl_add_u64 v[0:1], v[74:75], 0, v[0:1]
	s_mov_b32 m0, s26
	s_lshl_b32 s26, s16, 7
	global_load_lds_dwordx4 v[0:1], off
	v_subrev_u32_e32 v0, s17, v121
	v_ashrrev_i32_e32 v1, 31, v0
	v_lshlrev_b64 v[0:1], 13, v[0:1]
	v_lshl_add_u64 v[88:89], v[76:77], 0, v[0:1]
	v_add_u32_e32 v0, s26, v122
	v_ashrrev_i32_e32 v1, 31, v0
	v_lshlrev_b64 v[0:1], 13, v[0:1]
	v_lshl_add_u64 v[90:91], v[78:79], 0, v[0:1]
	v_subrev_u32_e32 v0, s17, v123
	v_ashrrev_i32_e32 v1, 31, v0
	v_lshlrev_b64 v[0:1], 13, v[0:1]
	v_lshl_add_u64 v[92:93], v[80:81], 0, v[0:1]
	v_add_u32_e32 v0, s26, v124
	v_ashrrev_i32_e32 v1, 31, v0
	v_lshlrev_b64 v[0:1], 13, v[0:1]
	v_lshl_add_u64 v[94:95], v[82:83], 0, v[0:1]
	v_subrev_u32_e32 v0, s17, v125
	v_ashrrev_i32_e32 v1, 31, v0
	v_lshlrev_b64 v[0:1], 13, v[0:1]
	v_lshl_add_u64 v[96:97], v[76:77], 0, v[0:1]
	v_add_u32_e32 v0, s26, v126
	v_ashrrev_i32_e32 v1, 31, v0
	v_lshlrev_b64 v[0:1], 13, v[0:1]
	v_lshl_add_u64 v[98:99], v[78:79], 0, v[0:1]
	v_subrev_u32_e32 v0, s17, v127
	v_ashrrev_i32_e32 v1, 31, v0
	v_lshlrev_b64 v[0:1], 13, v[0:1]
	v_lshl_add_u64 v[100:101], v[84:85], 0, v[0:1]
	v_add_u32_e32 v0, s26, v128
	v_ashrrev_i32_e32 v1, 31, v0
	v_lshlrev_b64 v[0:1], 13, v[0:1]
	v_lshl_add_u64 v[102:103], v[86:87], 0, v[0:1]
	v_mov_b32_e32 v0, 0
	s_mov_b64 s[16:17], 0
	v_mov_b32_e32 v1, v0
	v_mov_b32_e32 v2, v0
	v_mov_b32_e32 v3, v0
	v_mov_b32_e32 v4, v0
	v_mov_b32_e32 v5, v0
	v_mov_b32_e32 v6, v0
	v_mov_b32_e32 v7, v0
	v_mov_b32_e32 v8, v0
	v_mov_b32_e32 v9, v0
	v_mov_b32_e32 v10, v0
	v_mov_b32_e32 v11, v0
	v_mov_b32_e32 v12, v0
	v_mov_b32_e32 v13, v0
	v_mov_b32_e32 v14, v0
	v_mov_b32_e32 v15, v0
	v_mov_b32_e32 v16, v0
	v_mov_b32_e32 v17, v0
	v_mov_b32_e32 v18, v0
	v_mov_b32_e32 v19, v0
	v_mov_b32_e32 v20, v0
	v_mov_b32_e32 v21, v0
	v_mov_b32_e32 v22, v0
	v_mov_b32_e32 v23, v0
	v_mov_b32_e32 v24, v0
	v_mov_b32_e32 v25, v0
	v_mov_b32_e32 v26, v0
	v_mov_b32_e32 v27, v0
	v_mov_b32_e32 v28, v0
	v_mov_b32_e32 v29, v0
	v_mov_b32_e32 v30, v0
	v_mov_b32_e32 v31, v0
	s_waitcnt vmcnt(0)
	v_mov_b32_e32 v32, v0
	v_mov_b32_e32 v33, v0
	v_mov_b32_e32 v34, v0
	v_mov_b32_e32 v35, v0
	v_mov_b32_e32 v36, v0
	v_mov_b32_e32 v37, v0
	v_mov_b32_e32 v38, v0
	v_mov_b32_e32 v39, v0
	v_mov_b32_e32 v40, v0
	v_mov_b32_e32 v41, v0
	v_mov_b32_e32 v42, v0
	v_mov_b32_e32 v43, v0
	v_mov_b32_e32 v44, v0
	v_mov_b32_e32 v45, v0
	v_mov_b32_e32 v46, v0
	v_mov_b32_e32 v47, v0
	v_mov_b32_e32 v48, v0
	v_mov_b32_e32 v49, v0
	v_mov_b32_e32 v50, v0
	v_mov_b32_e32 v51, v0
	v_mov_b32_e32 v52, v0
	v_mov_b32_e32 v53, v0
	v_mov_b32_e32 v54, v0
	v_mov_b32_e32 v55, v0
	v_mov_b32_e32 v56, v0
	v_mov_b32_e32 v57, v0
	v_mov_b32_e32 v58, v0
	v_mov_b32_e32 v59, v0
	v_mov_b32_e32 v60, v0
	v_mov_b32_e32 v61, v0
	v_mov_b32_e32 v62, v0
	v_mov_b32_e32 v63, v0
	s_waitcnt lgkmcnt(0)
	s_barrier
	v_add3_u32 v190, 0, v134, v135
	v_add_u32_e32 v191, 0x4000, v190
	s_nop 0
	v_readfirstlane_b32 s82, v191
	s_nop 0
	v_readfirstlane_b32 s83, v190
	v_subrev_u32_e32 v192, s52, v88
	v_subrev_u32_e32 v193, s52, v90
	v_subrev_u32_e32 v194, s52, v92
	v_subrev_u32_e32 v195, s52, v94
	v_subrev_u32_e32 v196, s52, v96
	v_subrev_u32_e32 v197, s52, v98
	v_subrev_u32_e32 v198, s52, v100
	v_subrev_u32_e32 v199, s52, v102
	v_subrev_u32_e32 v195, 0x400, v195
	v_subrev_u32_e32 v194, 0x400, v194
	v_subrev_u32_e32 v197, 0x800, v197
	v_subrev_u32_e32 v196, 0x800, v196
	v_subrev_u32_e32 v199, 0xc00, v199
	v_subrev_u32_e32 v198, 0xc00, v198
	s_and_b32 s29, s27, 0x4000
	s_xor_b32 s28, s29, 0x4000
	s_lshl_b32 s28, s28, 1
	s_add_i32 s28, s28, 32
	s_lshl_b32 s29, s29, 1
	s_add_i32 s29, s29, 32

.LBB0_2095:
	s_and_b32 s16, s20, 0x380
	v_add_lshl_u32 v72, v141, s16, 13
	v_lshl_add_u64 v[98:99], v[86:87], 0, v[72:73]
	v_add_lshl_u32 v72, v143, s16, 13
	v_lshl_add_u64 v[100:101], v[90:91], 0, v[72:73]
	v_add_lshl_u32 v72, v145, s16, 13
	s_lshl_b32 s26, s25, 7
	v_lshl_add_u64 v[102:103], v[86:87], 0, v[72:73]
	v_add_lshl_u32 v72, v147, s16, 13
	s_ashr_i32 s16, s25, 3
	s_and_b32 s26, s26, 0x380
	v_add_u32_e32 v2, 0x4000, v135
	v_lshl_add_u64 v[104:105], v[94:95], 0, v[72:73]
	s_add_i32 s17, s16, s19
	v_add_lshl_u32 v72, s26, v134, 13
	v_readfirstlane_b32 s27, v2
	s_lshl_b32 s17, s17, 7
	v_lshl_add_u64 v[0:1], v[74:75], 0, v[72:73]
	s_mov_b32 m0, s27
	v_readfirstlane_b32 s27, v135
	global_load_lds_dwordx4 v[0:1], off
	v_add_u32_e32 v0, s17, v134
	v_ashrrev_i32_e32 v1, 31, v0
	v_lshlrev_b64 v[0:1], 13, v[0:1]
	v_lshl_add_u64 v[0:1], v[80:81], 0, v[0:1]
	s_mov_b32 m0, s27
	v_add_lshl_u32 v72, s26, v126, 13
	v_readfirstlane_b32 s27, v151
	global_load_lds_dwordx4 v[0:1], off
	v_lshl_add_u64 v[0:1], v[76:77], 0, v[72:73]
	s_mov_b32 m0, s27
	v_add_u32_e32 v2, 0x400, v135
	global_load_lds_dwordx4 v[0:1], off
	v_add_u32_e32 v0, s17, v126
	v_ashrrev_i32_e32 v1, 31, v0
	v_lshlrev_b64 v[0:1], 13, v[0:1]
	v_readfirstlane_b32 s27, v2
	v_lshl_add_u64 v[0:1], v[82:83], 0, v[0:1]
	s_mov_b32 m0, s27
	v_add_lshl_u32 v72, s26, v127, 13
	v_readfirstlane_b32 s27, v152
	global_load_lds_dwordx4 v[0:1], off
	v_lshl_add_u64 v[0:1], v[74:75], 0, v[72:73]
	s_mov_b32 m0, s27
	v_add_u32_e32 v2, 0x800, v135
	global_load_lds_dwordx4 v[0:1], off
	v_add_u32_e32 v0, s17, v127
	v_ashrrev_i32_e32 v1, 31, v0
	v_lshlrev_b64 v[0:1], 13, v[0:1]
	v_readfirstlane_b32 s27, v2
	v_lshl_add_u64 v[0:1], v[80:81], 0, v[0:1]
	s_mov_b32 m0, s27
	v_add_lshl_u32 v72, s26, v125, 13
	v_readfirstlane_b32 s27, v153
	global_load_lds_dwordx4 v[0:1], off
	v_lshl_add_u64 v[0:1], v[78:79], 0, v[72:73]
	s_mov_b32 m0, s27
	v_add_u32_e32 v2, 0xc00, v135
	global_load_lds_dwordx4 v[0:1], off
	v_add_u32_e32 v0, s17, v125
	v_ashrrev_i32_e32 v1, 31, v0
	v_lshlrev_b64 v[0:1], 13, v[0:1]
	v_readfirstlane_b32 s17, v2
	v_lshl_add_u64 v[0:1], v[84:85], 0, v[0:1]
	s_mov_b32 m0, s17
	s_lshl_b32 s27, s16, 7
	global_load_lds_dwordx4 v[0:1], off
	v_add_u32_e32 v0, s27, v142
	v_ashrrev_i32_e32 v1, 31, v0
	v_lshlrev_b64 v[0:1], 13, v[0:1]
	v_lshl_add_u64 v[106:107], v[88:89], 0, v[0:1]
	v_add_u32_e32 v0, s27, v144
	v_ashrrev_i32_e32 v1, 31, v0
	v_lshlrev_b64 v[0:1], 13, v[0:1]
	v_lshl_add_u64 v[108:109], v[92:93], 0, v[0:1]
	v_add_u32_e32 v0, s27, v146
	v_ashrrev_i32_e32 v1, 31, v0
	v_lshlrev_b64 v[0:1], 13, v[0:1]
	v_lshl_add_u64 v[110:111], v[88:89], 0, v[0:1]
	v_add_u32_e32 v0, s27, v148
	v_ashrrev_i32_e32 v1, 31, v0
	v_lshlrev_b64 v[0:1], 13, v[0:1]
	v_lshl_add_u64 v[112:113], v[96:97], 0, v[0:1]
	s_mov_b64 s[16:17], 0
	s_mov_b32 s28, 0
	v_mov_b32_e32 v0, 0
	v_mov_b32_e32 v1, v73
	v_mov_b32_e32 v2, v73
	v_mov_b32_e32 v3, v73
	v_mov_b32_e32 v4, 0
	v_mov_b32_e32 v5, v73
	v_mov_b32_e32 v6, v73
	v_mov_b32_e32 v7, v73
	v_mov_b32_e32 v8, 0
	v_mov_b32_e32 v9, v73
	v_mov_b32_e32 v10, v73
	v_mov_b32_e32 v11, v73
	v_mov_b32_e32 v12, 0
	v_mov_b32_e32 v13, v73
	v_mov_b32_e32 v14, v73
	v_mov_b32_e32 v15, v73
	v_mov_b32_e32 v16, 0
	v_mov_b32_e32 v17, v73
	v_mov_b32_e32 v18, v73
	v_mov_b32_e32 v19, v73
	v_mov_b32_e32 v20, 0
	v_mov_b32_e32 v21, v73
	v_mov_b32_e32 v22, v73
	v_mov_b32_e32 v23, v73
	v_mov_b32_e32 v24, 0
	v_mov_b32_e32 v25, v73
	v_mov_b32_e32 v26, v73
	v_mov_b32_e32 v27, v73
	v_mov_b32_e32 v28, 0
	v_mov_b32_e32 v29, v73
	v_mov_b32_e32 v30, v73
	v_mov_b32_e32 v31, v73
	s_waitcnt vmcnt(0)
	v_mov_b32_e32 v32, 0
	v_mov_b32_e32 v33, v73
	v_mov_b32_e32 v34, v73
	v_mov_b32_e32 v35, v73
	v_mov_b32_e32 v36, 0
	v_mov_b32_e32 v37, v73
	v_mov_b32_e32 v38, v73
	v_mov_b32_e32 v39, v73
	v_mov_b32_e32 v40, 0
	v_mov_b32_e32 v41, v73
	v_mov_b32_e32 v42, v73
	v_mov_b32_e32 v43, v73
	v_mov_b32_e32 v44, 0
	v_mov_b32_e32 v45, v73
	v_mov_b32_e32 v46, v73
	v_mov_b32_e32 v47, v73
	v_mov_b32_e32 v48, 0
	v_mov_b32_e32 v49, v73
	v_mov_b32_e32 v50, v73
	v_mov_b32_e32 v51, v73
	v_mov_b32_e32 v52, 0
	v_mov_b32_e32 v53, v73
	v_mov_b32_e32 v54, v73
	v_mov_b32_e32 v55, v73
	v_mov_b32_e32 v56, 0
	v_mov_b32_e32 v57, v73
	v_mov_b32_e32 v58, v73
	v_mov_b32_e32 v59, v73
	v_mov_b32_e32 v60, 0
	v_mov_b32_e32 v61, v73
	v_mov_b32_e32 v62, v73
	v_mov_b32_e32 v63, v73
	s_waitcnt lgkmcnt(0)
	s_barrier
	v_lshlrev_b32_e32 v190, 1, v132
	v_lshlrev_b32_e32 v191, 1, v133
	v_add3_u32 v190, 0, v190, v191
	v_add_u32_e32 v192, 0x4000, v190
	s_nop 0
	v_readfirstlane_b32 s82, v192
	s_nop 0
	v_readfirstlane_b32 s83, v190
	v_subrev_u32_e32 v193, s52, v98
	v_subrev_u32_e32 v194, s52, v106
	v_subrev_u32_e32 v195, s52, v100
	v_subrev_u32_e32 v196, s52, v108
	v_subrev_u32_e32 v197, s52, v102
	v_subrev_u32_e32 v198, s52, v110
	v_subrev_u32_e32 v199, s52, v104
	v_subrev_u32_e32 v200, s52, v112
	v_subrev_u32_e32 v196, 0x400, v196
	v_subrev_u32_e32 v195, 0x400, v195
	v_subrev_u32_e32 v198, 0x800, v198
	v_subrev_u32_e32 v197, 0x800, v197
	v_subrev_u32_e32 v200, 0xc00, v200
	v_subrev_u32_e32 v199, 0xc00, v199
	s_and_b32 s30, s28, 0x4000
	s_xor_b32 s29, s30, 0x4000
	s_lshl_b32 s29, s29, 1
	s_add_i32 s29, s29, 32
	s_lshl_b32 s30, s30, 1
	s_add_i32 s30, s30, 32

.LBB0_2101:
	s_ashr_i32 s17, s18, 2
	s_add_i32 s12, s17, 0x80
	s_and_b32 s16, s18, 3
	s_ashr_i32 s20, s12, 3
	s_add_i32 s21, s20, s19
	s_lshl_b32 s12, s16, 11
	s_add_u32 s8, s8, s12
	s_addc_u32 s9, s9, 0
	s_add_u32 s18, s10, s12
	s_addc_u32 s19, s11, 0
	s_lshl_b32 s11, s17, 7
	s_lshl_b32 s10, s21, 7
	s_and_b32 s11, s11, 0x380
	v_lshlrev_b32_e32 v83, 1, v2
	v_lshlrev_b32_e32 v84, 1, v3
	v_add_lshl_u32 v0, s11, v134, 13
	v_mov_b32_e32 v1, 0
	v_add3_u32 v20, 32, v83, v84
	v_add_u32_e32 v2, s10, v134
	v_lshl_add_u64 v[4:5], s[18:19], 0, v[0:1]
	v_add_u32_e32 v0, 0x4000, v20
	v_ashrrev_i32_e32 v3, 31, v2
	v_mov_b32_e32 v71, v1
	v_readfirstlane_b32 s21, v0
	v_lshlrev_b64 v[2:3], 13, v[2:3]
	v_lshl_add_u64 v[4:5], v[4:5], 0, v[70:71]
	s_mov_b32 m0, s21
	v_lshl_add_u64 v[2:3], s[8:9], 0, v[2:3]
	v_readfirstlane_b32 s21, v20
	global_load_lds_dwordx4 v[4:5], off
	v_lshl_add_u64 v[2:3], v[2:3], 0, v[70:71]
	s_mov_b32 m0, s21
	v_add_lshl_u32 v0, v126, s11, 12
	s_movk_i32 s17, 0x4000
	global_load_lds_dwordx4 v[2:3], off
	v_lshlrev_b64 v[2:3], 1, v[0:1]
	v_lshl_add_u32 v0, v118, 1, 32
	v_add3_u32 v0, v0, v84, s17
	v_lshl_add_u64 v[4:5], s[18:19], 0, v[2:3]
	v_lshlrev_b64 v[6:7], 1, v[66:67]
	v_readfirstlane_b32 s21, v0
	v_lshl_add_u64 v[4:5], v[4:5], 0, v[6:7]
	s_mov_b32 m0, s21
	v_add_u32_e32 v0, 0x400, v20
	global_load_lds_dwordx4 v[4:5], off
	v_add_u32_e32 v4, s10, v126
	v_ashrrev_i32_e32 v5, 31, v4
	v_lshlrev_b64 v[4:5], 13, v[4:5]
	v_lshl_add_u64 v[8:9], s[8:9], 0, v[4:5]
	v_readfirstlane_b32 s21, v0
	v_lshl_add_u64 v[8:9], v[8:9], 0, v[6:7]
	s_mov_b32 m0, s21
	v_add_lshl_u32 v0, v127, s11, 12
	global_load_lds_dwordx4 v[8:9], off
	v_lshlrev_b64 v[8:9], 1, v[0:1]
	v_lshl_add_u32 v0, v119, 1, 32
	v_add3_u32 v0, v0, v84, s17
	v_lshl_add_u64 v[10:11], s[18:19], 0, v[8:9]
	v_readfirstlane_b32 s21, v0
	v_lshl_add_u64 v[10:11], v[10:11], 0, v[70:71]
	s_mov_b32 m0, s21
	v_add_u32_e32 v0, 0x800, v20
	global_load_lds_dwordx4 v[10:11], off
	v_add_u32_e32 v10, s10, v127
	v_ashrrev_i32_e32 v11, 31, v10
	v_lshlrev_b64 v[10:11], 13, v[10:11]
	v_lshl_add_u64 v[12:13], s[8:9], 0, v[10:11]
	v_readfirstlane_b32 s21, v0
	v_lshl_add_u64 v[12:13], v[12:13], 0, v[70:71]
	s_mov_b32 m0, s21
	v_add_lshl_u32 v0, v125, s11, 12
	global_load_lds_dwordx4 v[12:13], off
	v_lshlrev_b64 v[12:13], 1, v[0:1]
	v_lshl_add_u32 v0, v120, 1, 32
	v_add3_u32 v0, v0, v84, s17
	v_lshl_add_u64 v[14:15], s[18:19], 0, v[12:13]
	v_lshlrev_b64 v[16:17], 1, v[68:69]
	v_readfirstlane_b32 s18, v0
	v_lshl_add_u64 v[14:15], v[14:15], 0, v[16:17]
	s_mov_b32 m0, s18
	v_add_u32_e32 v0, 0xc00, v20
	global_load_lds_dwordx4 v[14:15], off
	v_add_u32_e32 v14, s10, v125
	v_ashrrev_i32_e32 v15, 31, v14
	v_lshlrev_b64 v[14:15], 13, v[14:15]
	v_lshl_add_u64 v[18:19], s[8:9], 0, v[14:15]
	v_readfirstlane_b32 s8, v0
	v_lshl_add_u64 v[18:19], v[18:19], 0, v[16:17]
	s_mov_b32 m0, s8
	s_mov_b32 s13, 0
	global_load_lds_dwordx4 v[18:19], off
	v_or_b32_e32 v0, s11, v124
	v_lshl_add_u64 v[6:7], s[12:13], 0, v[6:7]
	v_add_lshl_u32 v0, v0, v123, 13
	v_lshl_add_u64 v[18:19], s[12:13], 0, v[64:65]
	v_lshl_add_u64 v[2:3], v[6:7], 0, v[2:3]
	v_lshl_add_u64 v[20:21], v[18:19], 0, v[0:1]
	s_mov_b64 s[8:9], 0x800080
	v_lshl_add_u64 v[2:3], s[6:7], 0, v[2:3]
	v_lshl_add_u64 v[20:21], s[6:7], 0, v[20:21]
	s_lshl_b32 s18, s20, 7
	v_lshl_add_u64 v[68:69], v[2:3], 0, s[8:9]
	v_lshl_add_u64 v[2:3], v[6:7], 0, v[4:5]
	v_lshl_add_u64 v[64:65], v[20:21], 0, s[8:9]
	v_add3_u32 v20, v128, s18, v123
	s_mov_b64 s[18:19], 0x8600080
	v_lshl_add_u64 v[2:3], s[6:7], 0, v[2:3]
	v_lshl_add_u64 v[70:71], v[2:3], 0, s[18:19]
	v_lshl_add_u64 v[2:3], v[18:19], 0, v[8:9]
	v_lshl_add_u64 v[2:3], s[6:7], 0, v[2:3]
	v_lshl_add_u64 v[72:73], v[2:3], 0, s[8:9]
	v_lshl_add_u64 v[2:3], v[18:19], 0, v[10:11]
	v_ashrrev_i32_e32 v21, 31, v20
	v_lshl_add_u64 v[2:3], s[6:7], 0, v[2:3]
	v_lshlrev_b64 v[20:21], 13, v[20:21]
	v_lshl_add_u64 v[74:75], v[2:3], 0, s[18:19]
	v_lshl_add_u64 v[2:3], s[12:13], 0, v[16:17]
	v_lshl_add_u64 v[20:21], v[18:19], 0, v[20:21]
	v_lshl_add_u64 v[4:5], v[2:3], 0, v[12:13]
	v_lshl_add_u64 v[2:3], v[2:3], 0, v[14:15]
	v_lshl_add_u64 v[20:21], s[6:7], 0, v[20:21]
	v_lshl_add_u64 v[4:5], s[6:7], 0, v[4:5]
	v_lshl_add_u64 v[2:3], s[6:7], 0, v[2:3]
	v_lshl_add_u64 v[66:67], v[20:21], 0, s[18:19]
	v_lshl_add_u64 v[76:77], v[4:5], 0, s[8:9]
	v_lshl_add_u64 v[78:79], v[2:3], 0, s[18:19]
	s_mov_b64 s[6:7], 0
	v_mov_b32_e32 v0, v1
	v_mov_b32_e32 v2, v1
	v_mov_b32_e32 v3, v1
	v_mov_b32_e32 v4, v1
	v_mov_b32_e32 v5, v1
	v_mov_b32_e32 v6, v1
	v_mov_b32_e32 v7, v1
	v_mov_b32_e32 v8, v1
	v_mov_b32_e32 v9, v1
	v_mov_b32_e32 v10, v1
	v_mov_b32_e32 v11, v1
	v_mov_b32_e32 v12, v1
	v_mov_b32_e32 v13, v1
	v_mov_b32_e32 v14, v1
	v_mov_b32_e32 v15, v1
	v_mov_b32_e32 v16, v1
	v_mov_b32_e32 v17, v1
	v_mov_b32_e32 v18, v1
	v_mov_b32_e32 v19, v1
	v_mov_b32_e32 v20, v1
	v_mov_b32_e32 v21, v1
	v_mov_b32_e32 v22, v1
	v_mov_b32_e32 v23, v1
	v_mov_b32_e32 v24, v1
	v_mov_b32_e32 v25, v1
	v_mov_b32_e32 v26, v1
	v_mov_b32_e32 v27, v1
	v_mov_b32_e32 v28, v1
	v_mov_b32_e32 v29, v1
	v_mov_b32_e32 v30, v1
	v_mov_b32_e32 v31, v1
	s_waitcnt vmcnt(0)
	v_mov_b32_e32 v32, v1
	v_mov_b32_e32 v33, v1
	v_mov_b32_e32 v34, v1
	v_mov_b32_e32 v35, v1
	v_mov_b32_e32 v36, v1
	v_mov_b32_e32 v37, v1
	v_mov_b32_e32 v38, v1
	v_mov_b32_e32 v39, v1
	v_mov_b32_e32 v40, v1
	v_mov_b32_e32 v41, v1
	v_mov_b32_e32 v42, v1
	v_mov_b32_e32 v43, v1
	v_mov_b32_e32 v44, v1
	v_mov_b32_e32 v45, v1
	v_mov_b32_e32 v46, v1
	v_mov_b32_e32 v47, v1
	v_mov_b32_e32 v48, v1
	v_mov_b32_e32 v49, v1
	v_mov_b32_e32 v50, v1
	v_mov_b32_e32 v51, v1
	v_mov_b32_e32 v52, v1
	v_mov_b32_e32 v53, v1
	v_mov_b32_e32 v54, v1
	v_mov_b32_e32 v55, v1
	v_mov_b32_e32 v56, v1
	v_mov_b32_e32 v57, v1
	v_mov_b32_e32 v58, v1
	v_mov_b32_e32 v59, v1
	v_mov_b32_e32 v60, v1
	v_mov_b32_e32 v61, v1
	v_mov_b32_e32 v62, v1
	v_mov_b32_e32 v63, v1
	s_waitcnt lgkmcnt(0)
	s_barrier
	v_add3_u32 v190, 0, v83, v84
	v_add_u32_e32 v191, 0x4000, v190
	s_nop 0
	v_readfirstlane_b32 s82, v191
	s_nop 0
	v_readfirstlane_b32 s83, v190
	v_subrev_u32_e32 v192, s52, v64
	v_subrev_u32_e32 v193, s52, v66
	v_subrev_u32_e32 v194, s52, v68
	v_subrev_u32_e32 v195, s52, v70
	v_subrev_u32_e32 v196, s52, v72
	v_subrev_u32_e32 v197, s52, v74
	v_subrev_u32_e32 v198, s52, v76
	v_subrev_u32_e32 v199, s52, v78
	v_subrev_u32_e32 v195, 0x400, v195
	v_subrev_u32_e32 v194, 0x400, v194
	v_subrev_u32_e32 v197, 0x800, v197
	v_subrev_u32_e32 v196, 0x800, v196
	v_subrev_u32_e32 v199, 0xc00, v199
	v_subrev_u32_e32 v198, 0xc00, v198
	s_and_b32 s9, s13, 0x4000
	s_xor_b32 s8, s9, 0x4000
	s_lshl_b32 s8, s8, 1
	s_add_i32 s8, s8, 32
	s_lshl_b32 s9, s9, 1
	s_add_i32 s9, s9, 32

.LBB0_2269:
	s_mul_hi_i32 s8, s49, 0x92492493
	s_add_i32 s8, s8, s49
	s_lshr_b32 s9, s8, 31
	s_ashr_i32 s8, s8, 2
	s_add_i32 s8, s8, s9
	s_mul_i32 s9, s8, -7
	s_add_i32 s28, s9, s49
	s_lshl_b32 s29, s28, 7
	v_add_u32_e32 v0, s29, v106
	v_ashrrev_i32_e32 v1, 31, v0
	v_add_u32_e32 v2, 0x4000, v107
	v_lshlrev_b64 v[0:1], 11, v[0:1]
	v_readfirstlane_b32 s9, v2
	s_lshl_b32 s36, s8, 7
	v_lshl_add_u64 v[0:1], v[66:67], 0, v[0:1]
	s_mov_b32 m0, s9
	v_readfirstlane_b32 s9, v107
	global_load_lds_dwordx4 v[0:1], off
	v_add_u32_e32 v0, s36, v106
	v_ashrrev_i32_e32 v1, 31, v0
	v_lshlrev_b64 v[0:1], 11, v[0:1]
	v_lshl_add_u64 v[2:3], v[72:73], 0, v[0:1]
	s_mov_b32 m0, s9
	v_readfirstlane_b32 s9, v131
	global_load_lds_dwordx4 v[2:3], off
	v_add_u32_e32 v2, s29, v108
	v_ashrrev_i32_e32 v3, 31, v2
	v_lshlrev_b64 v[2:3], 11, v[2:3]
	v_lshl_add_u64 v[2:3], v[68:69], 0, v[2:3]
	s_mov_b32 m0, s9
	v_add_u32_e32 v4, 0x400, v107
	global_load_lds_dwordx4 v[2:3], off
	v_add_u32_e32 v2, s36, v108
	v_ashrrev_i32_e32 v3, 31, v2
	v_lshlrev_b64 v[2:3], 11, v[2:3]
	v_readfirstlane_b32 s9, v4
	v_lshl_add_u64 v[2:3], v[74:75], 0, v[2:3]
	s_mov_b32 m0, s9
	v_readfirstlane_b32 s9, v132
	global_load_lds_dwordx4 v[2:3], off
	v_add_u32_e32 v2, s29, v110
	v_ashrrev_i32_e32 v3, 31, v2
	v_lshlrev_b64 v[2:3], 11, v[2:3]
	v_lshl_add_u64 v[2:3], v[66:67], 0, v[2:3]
	s_mov_b32 m0, s9
	v_add_u32_e32 v4, 0x800, v107
	global_load_lds_dwordx4 v[2:3], off
	v_add_u32_e32 v2, s36, v110
	v_ashrrev_i32_e32 v3, 31, v2
	v_lshlrev_b64 v[2:3], 11, v[2:3]
	v_readfirstlane_b32 s9, v4
	v_lshl_add_u64 v[2:3], v[72:73], 0, v[2:3]
	s_mov_b32 m0, s9
	v_readfirstlane_b32 s9, v133
	global_load_lds_dwordx4 v[2:3], off
	v_add_u32_e32 v2, s29, v112
	v_ashrrev_i32_e32 v3, 31, v2
	v_lshlrev_b64 v[2:3], 11, v[2:3]
	v_lshl_add_u64 v[2:3], v[70:71], 0, v[2:3]
	s_mov_b32 m0, s9
	v_add_u32_e32 v4, 0xc00, v107
	global_load_lds_dwordx4 v[2:3], off
	v_add_u32_e32 v2, s36, v112
	v_ashrrev_i32_e32 v3, 31, v2
	v_lshlrev_b64 v[2:3], 11, v[2:3]
	v_readfirstlane_b32 s9, v4
	v_lshl_add_u64 v[2:3], v[76:77], 0, v[2:3]
	s_mov_b32 m0, s9
	s_mulk_i32 s8, 0x380
	global_load_lds_dwordx4 v[2:3], off
	v_lshl_add_u64 v[92:93], v[80:81], 0, v[0:1]
	v_subrev_u32_e32 v0, s8, v123
	v_ashrrev_i32_e32 v1, 31, v0
	v_lshlrev_b64 v[0:1], 11, v[0:1]
	v_lshl_add_u64 v[94:95], v[82:83], 0, v[0:1]
	v_add_u32_e32 v0, s36, v124
	v_ashrrev_i32_e32 v1, 31, v0
	v_lshlrev_b64 v[0:1], 11, v[0:1]
	v_lshl_add_u64 v[96:97], v[84:85], 0, v[0:1]
	v_subrev_u32_e32 v0, s8, v125
	v_ashrrev_i32_e32 v1, 31, v0
	v_lshlrev_b64 v[0:1], 11, v[0:1]
	v_lshl_add_u64 v[98:99], v[78:79], 0, v[0:1]
	v_add_u32_e32 v0, s36, v126
	v_ashrrev_i32_e32 v1, 31, v0
	v_lshlrev_b64 v[0:1], 11, v[0:1]
	v_lshl_add_u64 v[100:101], v[80:81], 0, v[0:1]
	v_subrev_u32_e32 v0, s8, v127
	v_ashrrev_i32_e32 v1, 31, v0
	v_lshlrev_b64 v[0:1], 11, v[0:1]
	v_subrev_u32_e32 v2, s8, v122
	v_lshl_add_u64 v[102:103], v[86:87], 0, v[0:1]
	v_add_u32_e32 v0, s36, v128
	v_ashrrev_i32_e32 v3, 31, v2
	v_ashrrev_i32_e32 v1, 31, v0
	v_lshlrev_b64 v[2:3], 11, v[2:3]
	v_lshlrev_b64 v[0:1], 11, v[0:1]
	v_lshl_add_u64 v[90:91], v[78:79], 0, v[2:3]
	v_lshl_add_u64 v[104:105], v[88:89], 0, v[0:1]
	s_mov_b64 s[8:9], 0
	s_mov_b32 s30, 0
	v_mov_b32_e32 v0, v65
	v_mov_b32_e32 v1, v65
	v_mov_b32_e32 v2, v65
	v_mov_b32_e32 v3, v65
	v_mov_b32_e32 v4, v65
	v_mov_b32_e32 v5, v65
	v_mov_b32_e32 v6, v65
	v_mov_b32_e32 v7, v65
	v_mov_b32_e32 v8, v65
	v_mov_b32_e32 v9, v65
	v_mov_b32_e32 v10, v65
	v_mov_b32_e32 v11, v65
	v_mov_b32_e32 v12, v65
	v_mov_b32_e32 v13, v65
	v_mov_b32_e32 v14, v65
	v_mov_b32_e32 v15, v65
	v_mov_b32_e32 v16, v65
	v_mov_b32_e32 v17, v65
	v_mov_b32_e32 v18, v65
	v_mov_b32_e32 v19, v65
	v_mov_b32_e32 v20, v65
	v_mov_b32_e32 v21, v65
	v_mov_b32_e32 v22, v65
	v_mov_b32_e32 v23, v65
	v_mov_b32_e32 v24, v65
	v_mov_b32_e32 v25, v65
	v_mov_b32_e32 v26, v65
	v_mov_b32_e32 v27, v65
	v_mov_b32_e32 v28, v65
	v_mov_b32_e32 v29, v65
	v_mov_b32_e32 v30, v65
	v_mov_b32_e32 v31, v65
	s_waitcnt vmcnt(0)
	v_mov_b32_e32 v32, v65
	v_mov_b32_e32 v33, v65
	v_mov_b32_e32 v34, v65
	v_mov_b32_e32 v35, v65
	v_mov_b32_e32 v36, v65
	v_mov_b32_e32 v37, v65
	v_mov_b32_e32 v38, v65
	v_mov_b32_e32 v39, v65
	v_mov_b32_e32 v40, v65
	v_mov_b32_e32 v41, v65
	v_mov_b32_e32 v42, v65
	v_mov_b32_e32 v43, v65
	v_mov_b32_e32 v44, v65
	v_mov_b32_e32 v45, v65
	v_mov_b32_e32 v46, v65
	v_mov_b32_e32 v47, v65
	v_mov_b32_e32 v48, v65
	v_mov_b32_e32 v49, v65
	v_mov_b32_e32 v50, v65
	v_mov_b32_e32 v51, v65
	v_mov_b32_e32 v52, v65
	v_mov_b32_e32 v53, v65
	v_mov_b32_e32 v54, v65
	v_mov_b32_e32 v55, v65
	v_mov_b32_e32 v56, v65
	v_mov_b32_e32 v57, v65
	v_mov_b32_e32 v58, v65
	v_mov_b32_e32 v59, v65
	v_mov_b32_e32 v60, v65
	v_mov_b32_e32 v61, v65
	v_mov_b32_e32 v62, v65
	v_mov_b32_e32 v63, v65
	s_waitcnt lgkmcnt(0)
	s_barrier
	v_add3_u32 v182, 0, v134, v135
	v_add_u32_e32 v183, 0x4000, v182
	s_nop 0
	v_readfirstlane_b32 s82, v183
	s_nop 0
	v_readfirstlane_b32 s83, v182
	v_subrev_u32_e32 v184, s52, v90
	v_subrev_u32_e32 v185, s52, v92
	v_subrev_u32_e32 v186, s52, v94
	v_subrev_u32_e32 v187, s52, v96
	v_subrev_u32_e32 v188, s52, v98
	v_subrev_u32_e32 v189, s52, v100
	v_subrev_u32_e32 v190, s52, v102
	v_subrev_u32_e32 v191, s52, v104
	v_subrev_u32_e32 v187, 0x400, v187
	v_subrev_u32_e32 v186, 0x400, v186
	v_subrev_u32_e32 v189, 0x800, v189
	v_subrev_u32_e32 v188, 0x800, v188
	v_subrev_u32_e32 v191, 0xc00, v191
	v_subrev_u32_e32 v190, 0xc00, v190
	s_and_b32 s34, s30, 0x4000
	s_xor_b32 s31, s34, 0x4000
	s_lshl_b32 s31, s31, 1
	s_add_i32 s31, s31, 32
	s_lshl_b32 s34, s34, 1
	s_add_i32 s34, s34, 32

.LBB0_2291:
	s_mul_hi_i32 s8, s34, 0x92492493
	s_add_i32 s8, s8, s34
	s_lshr_b32 s9, s8, 31
	s_ashr_i32 s8, s8, 2
	s_add_i32 s8, s8, s9
	s_mul_i32 s9, s8, 0x1fffff9
	s_add_i32 s9, s9, s34
	v_add_u32_e32 v0, s8, v106
	s_lshl_b32 s22, s9, 7
	v_lshlrev_b32_e32 v2, 7, v0
	v_add_u32_e32 v0, s22, v107
	v_ashrrev_i32_e32 v1, 31, v0
	v_add_u32_e32 v3, 0x4000, v108
	v_lshlrev_b64 v[0:1], 11, v[0:1]
	v_readfirstlane_b32 s9, v3
	v_lshl_add_u64 v[0:1], v[66:67], 0, v[0:1]
	s_mov_b32 m0, s9
	v_readfirstlane_b32 s9, v108
	global_load_lds_dwordx4 v[0:1], off
	v_add_u32_e32 v0, v2, v107
	v_ashrrev_i32_e32 v1, 31, v0
	v_lshlrev_b64 v[0:1], 11, v[0:1]
	v_lshl_add_u64 v[0:1], v[72:73], 0, v[0:1]
	s_mov_b32 m0, s9
	v_readfirstlane_b32 s9, v133
	global_load_lds_dwordx4 v[0:1], off
	v_add_u32_e32 v0, s22, v109
	v_ashrrev_i32_e32 v1, 31, v0
	v_lshlrev_b64 v[0:1], 11, v[0:1]
	v_lshl_add_u64 v[0:1], v[68:69], 0, v[0:1]
	s_mov_b32 m0, s9
	v_add_u32_e32 v3, 0x400, v108
	global_load_lds_dwordx4 v[0:1], off
	v_add_u32_e32 v0, v2, v109
	v_ashrrev_i32_e32 v1, 31, v0
	v_lshlrev_b64 v[0:1], 11, v[0:1]
	v_readfirstlane_b32 s9, v3
	v_lshl_add_u64 v[0:1], v[74:75], 0, v[0:1]
	s_mov_b32 m0, s9
	v_readfirstlane_b32 s9, v134
	global_load_lds_dwordx4 v[0:1], off
	v_add_u32_e32 v0, s22, v111
	v_ashrrev_i32_e32 v1, 31, v0
	v_lshlrev_b64 v[0:1], 11, v[0:1]
	v_lshl_add_u64 v[0:1], v[66:67], 0, v[0:1]
	s_mov_b32 m0, s9
	v_add_u32_e32 v3, 0x800, v108
	global_load_lds_dwordx4 v[0:1], off
	v_add_u32_e32 v0, v2, v111
	v_ashrrev_i32_e32 v1, 31, v0
	v_lshlrev_b64 v[0:1], 11, v[0:1]
	v_readfirstlane_b32 s9, v3
	v_lshl_add_u64 v[0:1], v[72:73], 0, v[0:1]
	s_mov_b32 m0, s9
	v_readfirstlane_b32 s9, v135
	global_load_lds_dwordx4 v[0:1], off
	v_add_u32_e32 v0, s22, v113
	v_ashrrev_i32_e32 v1, 31, v0
	v_lshlrev_b64 v[0:1], 11, v[0:1]
	v_lshl_add_u64 v[0:1], v[70:71], 0, v[0:1]
	s_mov_b32 m0, s9
	s_lshl_b32 s28, s8, 7
	global_load_lds_dwordx4 v[0:1], off
	v_add_u32_e32 v0, v2, v113
	v_ashrrev_i32_e32 v1, 31, v0
	v_add_u32_e32 v2, 0xc00, v108
	v_lshlrev_b64 v[0:1], 11, v[0:1]
	v_readfirstlane_b32 s9, v2
	v_lshl_add_u64 v[0:1], v[76:77], 0, v[0:1]
	s_mov_b32 m0, s9
	s_mul_i32 s9, s8, 0x380
	global_load_lds_dwordx4 v[0:1], off
	v_subrev_u32_e32 v0, s9, v123
	v_ashrrev_i32_e32 v1, 31, v0
	v_lshlrev_b64 v[0:1], 11, v[0:1]
	v_lshl_add_u64 v[90:91], v[78:79], 0, v[0:1]
	v_add_u32_e32 v0, s28, v124
	v_ashrrev_i32_e32 v1, 31, v0
	v_lshlrev_b64 v[0:1], 11, v[0:1]
	v_lshl_add_u64 v[92:93], v[80:81], 0, v[0:1]
	v_subrev_u32_e32 v0, s9, v125
	v_ashrrev_i32_e32 v1, 31, v0
	v_lshlrev_b64 v[0:1], 11, v[0:1]
	v_lshl_add_u64 v[94:95], v[82:83], 0, v[0:1]
	v_add_u32_e32 v0, s28, v126
	v_ashrrev_i32_e32 v1, 31, v0
	v_lshlrev_b64 v[0:1], 11, v[0:1]
	v_lshl_add_u64 v[96:97], v[84:85], 0, v[0:1]
	v_subrev_u32_e32 v0, s9, v127
	v_ashrrev_i32_e32 v1, 31, v0
	v_lshlrev_b64 v[0:1], 11, v[0:1]
	v_lshl_add_u64 v[98:99], v[78:79], 0, v[0:1]
	v_add_u32_e32 v0, s28, v128
	v_ashrrev_i32_e32 v1, 31, v0
	v_lshlrev_b64 v[0:1], 11, v[0:1]
	v_lshl_add_u64 v[100:101], v[80:81], 0, v[0:1]
	v_subrev_u32_e32 v0, s9, v129
	v_ashrrev_i32_e32 v1, 31, v0
	v_lshlrev_b64 v[0:1], 11, v[0:1]
	v_lshl_add_u64 v[102:103], v[86:87], 0, v[0:1]
	v_add_u32_e32 v0, s28, v130
	v_ashrrev_i32_e32 v1, 31, v0
	v_lshlrev_b64 v[0:1], 11, v[0:1]
	v_lshl_add_u64 v[104:105], v[88:89], 0, v[0:1]
	v_mov_b32_e32 v0, 0
	s_mov_b64 s[8:9], 0
	s_mov_b32 s23, 0
	v_mov_b32_e32 v1, v0
	v_mov_b32_e32 v2, v0
	v_mov_b32_e32 v3, v0
	v_mov_b32_e32 v4, v0
	v_mov_b32_e32 v5, v0
	v_mov_b32_e32 v6, v0
	v_mov_b32_e32 v7, v0
	v_mov_b32_e32 v8, v0
	v_mov_b32_e32 v9, v0
	v_mov_b32_e32 v10, v0
	v_mov_b32_e32 v11, v0
	v_mov_b32_e32 v12, v0
	v_mov_b32_e32 v13, v0
	v_mov_b32_e32 v14, v0
	v_mov_b32_e32 v15, v0
	v_mov_b32_e32 v16, v0
	v_mov_b32_e32 v17, v0
	v_mov_b32_e32 v18, v0
	v_mov_b32_e32 v19, v0
	v_mov_b32_e32 v20, v0
	v_mov_b32_e32 v21, v0
	v_mov_b32_e32 v22, v0
	v_mov_b32_e32 v23, v0
	v_mov_b32_e32 v24, v0
	v_mov_b32_e32 v25, v0
	v_mov_b32_e32 v26, v0
	v_mov_b32_e32 v27, v0
	v_mov_b32_e32 v28, v0
	v_mov_b32_e32 v29, v0
	v_mov_b32_e32 v30, v0
	v_mov_b32_e32 v31, v0
	s_waitcnt vmcnt(0)
	v_mov_b32_e32 v32, v0
	v_mov_b32_e32 v33, v0
	v_mov_b32_e32 v34, v0
	v_mov_b32_e32 v35, v0
	v_mov_b32_e32 v36, v0
	v_mov_b32_e32 v37, v0
	v_mov_b32_e32 v38, v0
	v_mov_b32_e32 v39, v0
	v_mov_b32_e32 v40, v0
	v_mov_b32_e32 v41, v0
	v_mov_b32_e32 v42, v0
	v_mov_b32_e32 v43, v0
	v_mov_b32_e32 v44, v0
	v_mov_b32_e32 v45, v0
	v_mov_b32_e32 v46, v0
	v_mov_b32_e32 v47, v0
	v_mov_b32_e32 v48, v0
	v_mov_b32_e32 v49, v0
	v_mov_b32_e32 v50, v0
	v_mov_b32_e32 v51, v0
	v_mov_b32_e32 v52, v0
	v_mov_b32_e32 v53, v0
	v_mov_b32_e32 v54, v0
	v_mov_b32_e32 v55, v0
	v_mov_b32_e32 v56, v0
	v_mov_b32_e32 v57, v0
	v_mov_b32_e32 v58, v0
	v_mov_b32_e32 v59, v0
	v_mov_b32_e32 v60, v0
	v_mov_b32_e32 v61, v0
	v_mov_b32_e32 v62, v0
	v_mov_b32_e32 v63, v0
	s_waitcnt lgkmcnt(0)
	s_barrier
	v_add3_u32 v182, 0, v136, v137
	v_add_u32_e32 v183, 0x4000, v182
	s_nop 0
	v_readfirstlane_b32 s82, v183
	s_nop 0
	v_readfirstlane_b32 s83, v182
	v_subrev_u32_e32 v184, s52, v90
	v_subrev_u32_e32 v185, s52, v92
	v_subrev_u32_e32 v186, s52, v94
	v_subrev_u32_e32 v187, s52, v96
	v_subrev_u32_e32 v188, s52, v98
	v_subrev_u32_e32 v189, s52, v100
	v_subrev_u32_e32 v190, s52, v102
	v_subrev_u32_e32 v191, s52, v104
	v_subrev_u32_e32 v187, 0x400, v187
	v_subrev_u32_e32 v186, 0x400, v186
	v_subrev_u32_e32 v189, 0x800, v189
	v_subrev_u32_e32 v188, 0x800, v188
	v_subrev_u32_e32 v191, 0xc00, v191
	v_subrev_u32_e32 v190, 0xc00, v190
	s_and_b32 s25, s23, 0x4000
	s_xor_b32 s24, s25, 0x4000
	s_lshl_b32 s24, s24, 1
	s_add_i32 s24, s24, 32
	s_lshl_b32 s25, s25, 1
	s_add_i32 s25, s25, 32

.LBB0_2975:
	s_mul_hi_i32 s4, s43, 0x51eb851f
	s_lshr_b32 s5, s4, 31
	s_ashr_i32 s4, s4, 3
	s_add_i32 s4, s4, s5
	s_mul_i32 s5, s4, 0xffffffe7
	s_add_i32 s5, s5, s43
	s_lshl_b32 s6, s5, 7
	v_add_u32_e32 v0, s6, v106
	v_ashrrev_i32_e32 v1, 31, v0
	v_add_u32_e32 v2, 0x4000, v107
	v_lshlrev_b64 v[0:1], 11, v[0:1]
	v_readfirstlane_b32 s5, v2
	s_lshl_b32 s36, s4, 7
	v_lshl_add_u64 v[0:1], v[66:67], 0, v[0:1]
	s_mov_b32 m0, s5
	v_readfirstlane_b32 s5, v107
	global_load_lds_dwordx4 v[0:1], off
	v_add_u32_e32 v0, s36, v106
	v_ashrrev_i32_e32 v1, 31, v0
	v_lshlrev_b64 v[0:1], 11, v[0:1]
	v_lshl_add_u64 v[2:3], v[72:73], 0, v[0:1]
	s_mov_b32 m0, s5
	v_readfirstlane_b32 s5, v131
	global_load_lds_dwordx4 v[2:3], off
	v_add_u32_e32 v2, s6, v108
	v_ashrrev_i32_e32 v3, 31, v2
	v_lshlrev_b64 v[2:3], 11, v[2:3]
	v_lshl_add_u64 v[2:3], v[68:69], 0, v[2:3]
	s_mov_b32 m0, s5
	v_add_u32_e32 v4, 0x400, v107
	global_load_lds_dwordx4 v[2:3], off
	v_add_u32_e32 v2, s36, v108
	v_ashrrev_i32_e32 v3, 31, v2
	v_lshlrev_b64 v[2:3], 11, v[2:3]
	v_readfirstlane_b32 s5, v4
	v_lshl_add_u64 v[2:3], v[74:75], 0, v[2:3]
	s_mov_b32 m0, s5
	v_readfirstlane_b32 s5, v132
	global_load_lds_dwordx4 v[2:3], off
	v_add_u32_e32 v2, s6, v110
	v_ashrrev_i32_e32 v3, 31, v2
	v_lshlrev_b64 v[2:3], 11, v[2:3]
	v_lshl_add_u64 v[2:3], v[66:67], 0, v[2:3]
	s_mov_b32 m0, s5
	v_add_u32_e32 v4, 0x800, v107
	global_load_lds_dwordx4 v[2:3], off
	v_add_u32_e32 v2, s36, v110
	v_ashrrev_i32_e32 v3, 31, v2
	v_lshlrev_b64 v[2:3], 11, v[2:3]
	v_readfirstlane_b32 s5, v4
	v_lshl_add_u64 v[2:3], v[72:73], 0, v[2:3]
	s_mov_b32 m0, s5
	v_readfirstlane_b32 s5, v133
	global_load_lds_dwordx4 v[2:3], off
	v_add_u32_e32 v2, s6, v112
	v_ashrrev_i32_e32 v3, 31, v2
	v_lshlrev_b64 v[2:3], 11, v[2:3]
	v_lshl_add_u64 v[2:3], v[70:71], 0, v[2:3]
	s_mov_b32 m0, s5
	v_add_u32_e32 v4, 0xc00, v107
	global_load_lds_dwordx4 v[2:3], off
	v_add_u32_e32 v2, s36, v112
	v_ashrrev_i32_e32 v3, 31, v2
	v_lshlrev_b64 v[2:3], 11, v[2:3]
	v_readfirstlane_b32 s5, v4
	v_lshl_add_u64 v[2:3], v[76:77], 0, v[2:3]
	s_mov_b32 m0, s5
	s_mulk_i32 s4, 0xc80
	global_load_lds_dwordx4 v[2:3], off
	v_lshl_add_u64 v[92:93], v[80:81], 0, v[0:1]
	v_subrev_u32_e32 v0, s4, v123
	v_ashrrev_i32_e32 v1, 31, v0
	v_lshlrev_b64 v[0:1], 11, v[0:1]
	v_lshl_add_u64 v[94:95], v[82:83], 0, v[0:1]
	v_add_u32_e32 v0, s36, v124
	v_ashrrev_i32_e32 v1, 31, v0
	v_lshlrev_b64 v[0:1], 11, v[0:1]
	v_lshl_add_u64 v[96:97], v[84:85], 0, v[0:1]
	v_subrev_u32_e32 v0, s4, v125
	v_ashrrev_i32_e32 v1, 31, v0
	v_lshlrev_b64 v[0:1], 11, v[0:1]
	v_lshl_add_u64 v[98:99], v[78:79], 0, v[0:1]
	v_add_u32_e32 v0, s36, v126
	v_ashrrev_i32_e32 v1, 31, v0
	v_lshlrev_b64 v[0:1], 11, v[0:1]
	v_lshl_add_u64 v[100:101], v[80:81], 0, v[0:1]
	v_subrev_u32_e32 v0, s4, v127
	v_ashrrev_i32_e32 v1, 31, v0
	v_lshlrev_b64 v[0:1], 11, v[0:1]
	v_subrev_u32_e32 v2, s4, v122
	v_lshl_add_u64 v[102:103], v[86:87], 0, v[0:1]
	v_add_u32_e32 v0, s36, v128
	v_ashrrev_i32_e32 v3, 31, v2
	v_ashrrev_i32_e32 v1, 31, v0
	v_lshlrev_b64 v[2:3], 11, v[2:3]
	v_lshlrev_b64 v[0:1], 11, v[0:1]
	v_lshl_add_u64 v[90:91], v[78:79], 0, v[2:3]
	v_lshl_add_u64 v[104:105], v[88:89], 0, v[0:1]
	s_mov_b32 s7, 0
	s_mov_b64 s[4:5], 0
	v_mov_b32_e32 v0, 0
	v_mov_b32_e32 v1, v65
	v_mov_b32_e32 v2, v65
	v_mov_b32_e32 v3, v65
	v_mov_b32_e32 v4, 0
	v_mov_b32_e32 v5, v65
	v_mov_b32_e32 v6, v65
	v_mov_b32_e32 v7, v65
	v_mov_b32_e32 v8, 0
	v_mov_b32_e32 v9, v65
	v_mov_b32_e32 v10, v65
	v_mov_b32_e32 v11, v65
	v_mov_b32_e32 v12, 0
	v_mov_b32_e32 v13, v65
	v_mov_b32_e32 v14, v65
	v_mov_b32_e32 v15, v65
	v_mov_b32_e32 v16, 0
	v_mov_b32_e32 v17, v65
	v_mov_b32_e32 v18, v65
	v_mov_b32_e32 v19, v65
	v_mov_b32_e32 v20, 0
	v_mov_b32_e32 v21, v65
	v_mov_b32_e32 v22, v65
	v_mov_b32_e32 v23, v65
	v_mov_b32_e32 v24, 0
	v_mov_b32_e32 v25, v65
	v_mov_b32_e32 v26, v65
	v_mov_b32_e32 v27, v65
	v_mov_b32_e32 v28, 0
	v_mov_b32_e32 v29, v65
	v_mov_b32_e32 v30, v65
	v_mov_b32_e32 v31, v65
	v_mov_b32_e32 v32, 0
	v_mov_b32_e32 v33, v65
	v_mov_b32_e32 v34, v65
	v_mov_b32_e32 v35, v65
	v_mov_b32_e32 v36, 0
	v_mov_b32_e32 v37, v65
	v_mov_b32_e32 v38, v65
	v_mov_b32_e32 v39, v65
	v_mov_b32_e32 v40, 0
	v_mov_b32_e32 v41, v65
	v_mov_b32_e32 v42, v65
	v_mov_b32_e32 v43, v65
	v_mov_b32_e32 v44, 0
	v_mov_b32_e32 v45, v65
	v_mov_b32_e32 v46, v65
	v_mov_b32_e32 v47, v65
	v_mov_b32_e32 v48, 0
	v_mov_b32_e32 v49, v65
	v_mov_b32_e32 v50, v65
	v_mov_b32_e32 v51, v65
	v_mov_b32_e32 v52, 0
	v_mov_b32_e32 v53, v65
	v_mov_b32_e32 v54, v65
	v_mov_b32_e32 v55, v65
	v_mov_b32_e32 v56, 0
	v_mov_b32_e32 v57, v65
	v_mov_b32_e32 v58, v65
	v_mov_b32_e32 v59, v65
	v_mov_b32_e32 v60, 0
	v_mov_b32_e32 v61, v65
	v_mov_b32_e32 v62, v65
	v_mov_b32_e32 v63, v65
	s_waitcnt vmcnt(0) lgkmcnt(0)
	s_barrier
	v_add3_u32 v182, 0, v134, v135
	v_add_u32_e32 v183, 0x4000, v182
	s_nop 0
	v_readfirstlane_b32 s82, v183
	s_nop 0
	v_readfirstlane_b32 s83, v182
	v_subrev_u32_e32 v184, s52, v90
	v_subrev_u32_e32 v185, s52, v92
	v_subrev_u32_e32 v186, s52, v94
	v_subrev_u32_e32 v187, s52, v96
	v_subrev_u32_e32 v188, s52, v98
	v_subrev_u32_e32 v189, s52, v100
	v_subrev_u32_e32 v190, s52, v102
	v_subrev_u32_e32 v191, s52, v104
	v_subrev_u32_e32 v187, 0x400, v187
	v_subrev_u32_e32 v186, 0x400, v186
	v_subrev_u32_e32 v189, 0x800, v189
	v_subrev_u32_e32 v188, 0x800, v188
	v_subrev_u32_e32 v191, 0xc00, v191
	v_subrev_u32_e32 v190, 0xc00, v190
	s_and_b32 s29, s7, 0x4000
	s_xor_b32 s28, s29, 0x4000
	s_lshl_b32 s28, s28, 1
	s_add_i32 s28, s28, 32
	s_lshl_b32 s29, s29, 1
	s_add_i32 s29, s29, 32

.LBB0_3007:
	v_cvt_f32_ubyte0_e32 v0, s6
	v_rcp_iflag_f32_e32 v0, v0
	s_sub_i32 s24, 0, s6
	s_abs_i32 s23, s4
	s_ashr_i32 s22, s4, 31
	v_mul_f32_e32 v0, 0x4f7ffffe, v0
	v_cvt_u32_f32_e32 v0, v0
	v_add_u32_e32 v2, 0x4000, v108
	v_add_u32_e32 v4, 0x400, v108
	v_readfirstlane_b32 s25, v0
	s_mul_i32 s24, s24, s25
	s_mul_hi_u32 s24, s25, s24
	s_add_i32 s25, s25, s24
	s_mul_hi_u32 s24, s23, s25
	s_mul_i32 s25, s24, s6
	s_sub_i32 s23, s23, s25
	s_add_i32 s26, s24, 1
	s_sub_i32 s25, s23, s6
	s_cmp_ge_u32 s23, s6
	s_cselect_b32 s24, s26, s24
	s_cselect_b32 s23, s25, s23
	s_add_i32 s25, s24, 1
	s_cmp_ge_u32 s23, s6
	s_cselect_b32 s23, s25, s24
	s_xor_b32 s23, s23, s22
	s_sub_i32 s22, s23, s22
	s_mul_i32 s23, s22, s6
	s_sub_i32 s6, s4, s23
	s_lshl_b32 s6, s6, 7
	v_add_u32_e32 v0, s22, v106
	s_add_i32 s6, s6, s5
	v_lshlrev_b32_e32 v135, 7, v0
	v_add_u32_e32 v0, s6, v107
	v_ashrrev_i32_e32 v1, 31, v0
	v_lshlrev_b64 v[0:1], 11, v[0:1]
	v_readfirstlane_b32 s22, v2
	v_lshl_add_u64 v[0:1], v[66:67], 0, v[0:1]
	s_mov_b32 m0, s22
	v_readfirstlane_b32 s22, v108
	global_load_lds_dwordx4 v[0:1], off
	v_add_u32_e32 v0, v135, v107
	v_ashrrev_i32_e32 v1, 31, v0
	v_lshlrev_b64 v[0:1], 11, v[0:1]
	v_lshl_add_u64 v[2:3], v[72:73], 0, v[0:1]
	s_mov_b32 m0, s22
	v_readfirstlane_b32 s22, v128
	global_load_lds_dwordx4 v[2:3], off
	v_add_u32_e32 v2, s6, v109
	v_ashrrev_i32_e32 v3, 31, v2
	v_lshlrev_b64 v[2:3], 11, v[2:3]
	v_lshl_add_u64 v[2:3], v[68:69], 0, v[2:3]
	s_mov_b32 m0, s22
	v_readfirstlane_b32 s22, v4
	global_load_lds_dwordx4 v[2:3], off
	v_add_u32_e32 v2, v135, v109
	v_ashrrev_i32_e32 v3, 31, v2
	v_lshlrev_b64 v[2:3], 11, v[2:3]
	v_lshl_add_u64 v[2:3], v[74:75], 0, v[2:3]
	s_mov_b32 m0, s22
	v_readfirstlane_b32 s22, v129
	global_load_lds_dwordx4 v[2:3], off
	v_add_u32_e32 v2, s6, v111
	v_ashrrev_i32_e32 v3, 31, v2
	v_lshlrev_b64 v[2:3], 11, v[2:3]
	v_lshl_add_u64 v[2:3], v[66:67], 0, v[2:3]
	s_mov_b32 m0, s22
	v_add_u32_e32 v4, 0x800, v108
	global_load_lds_dwordx4 v[2:3], off
	v_add_u32_e32 v2, v135, v111
	v_ashrrev_i32_e32 v3, 31, v2
	v_lshlrev_b64 v[2:3], 11, v[2:3]
	v_readfirstlane_b32 s22, v4
	v_lshl_add_u64 v[2:3], v[72:73], 0, v[2:3]
	s_mov_b32 m0, s22
	v_readfirstlane_b32 s22, v130
	global_load_lds_dwordx4 v[2:3], off
	v_add_u32_e32 v2, s6, v113
	v_ashrrev_i32_e32 v3, 31, v2
	v_lshlrev_b64 v[2:3], 11, v[2:3]
	v_lshl_add_u64 v[2:3], v[70:71], 0, v[2:3]
	s_mov_b32 m0, s22
	v_add_u32_e32 v4, 0xc00, v108
	global_load_lds_dwordx4 v[2:3], off
	v_add_u32_e32 v2, v135, v113
	v_ashrrev_i32_e32 v3, 31, v2
	v_lshlrev_b64 v[2:3], 11, v[2:3]
	v_readfirstlane_b32 s22, v4
	v_lshl_add_u64 v[2:3], v[76:77], 0, v[2:3]
	s_mov_b32 m0, s22
	s_lshl_b32 s4, s4, 7
	global_load_lds_dwordx4 v[2:3], off
	s_add_i32 s4, s4, s5
	s_lshl_b32 s5, s23, 7
	v_lshl_add_u64 v[92:93], v[80:81], 0, v[0:1]
	v_add_u32_e32 v0, s4, v123
	v_subrev_u32_e32 v0, s5, v0
	v_ashrrev_i32_e32 v1, 31, v0
	v_lshlrev_b64 v[0:1], 11, v[0:1]
	v_lshl_add_u64 v[94:95], v[82:83], 0, v[0:1]
	v_add_u32_e32 v0, v123, v135
	v_ashrrev_i32_e32 v1, 31, v0
	v_lshlrev_b64 v[0:1], 11, v[0:1]
	v_lshl_add_u64 v[96:97], v[84:85], 0, v[0:1]
	v_add_u32_e32 v0, s4, v124
	v_subrev_u32_e32 v0, s5, v0
	v_ashrrev_i32_e32 v1, 31, v0
	v_lshlrev_b64 v[0:1], 11, v[0:1]
	v_lshl_add_u64 v[98:99], v[78:79], 0, v[0:1]
	v_add_u32_e32 v0, v124, v135
	v_ashrrev_i32_e32 v1, 31, v0
	v_lshlrev_b64 v[0:1], 11, v[0:1]
	v_lshl_add_u64 v[100:101], v[80:81], 0, v[0:1]
	v_add_u32_e32 v0, s4, v125
	v_subrev_u32_e32 v0, s5, v0
	v_ashrrev_i32_e32 v1, 31, v0
	v_lshlrev_b64 v[0:1], 11, v[0:1]
	v_add_u32_e32 v2, s4, v107
	v_lshl_add_u64 v[102:103], v[86:87], 0, v[0:1]
	v_add_u32_e32 v0, v125, v135
	v_subrev_u32_e32 v2, s5, v2
	v_ashrrev_i32_e32 v1, 31, v0
	v_ashrrev_i32_e32 v3, 31, v2
	v_lshlrev_b64 v[0:1], 11, v[0:1]
	v_lshlrev_b64 v[2:3], 11, v[2:3]
	v_lshl_add_u64 v[104:105], v[88:89], 0, v[0:1]
	v_mov_b32_e32 v0, 0
	v_lshl_add_u64 v[90:91], v[78:79], 0, v[2:3]
	s_mov_b64 s[4:5], 0
	v_mov_b32_e32 v1, v0
	v_mov_b32_e32 v2, v0
	v_mov_b32_e32 v3, v0
	v_mov_b32_e32 v4, v0
	v_mov_b32_e32 v5, v0
	v_mov_b32_e32 v6, v0
	v_mov_b32_e32 v7, v0
	v_mov_b32_e32 v8, v0
	v_mov_b32_e32 v9, v0
	v_mov_b32_e32 v10, v0
	v_mov_b32_e32 v11, v0
	v_mov_b32_e32 v12, v0
	v_mov_b32_e32 v13, v0
	v_mov_b32_e32 v14, v0
	v_mov_b32_e32 v15, v0
	v_mov_b32_e32 v16, v0
	v_mov_b32_e32 v17, v0
	v_mov_b32_e32 v18, v0
	v_mov_b32_e32 v19, v0
	v_mov_b32_e32 v20, v0
	v_mov_b32_e32 v21, v0
	v_mov_b32_e32 v22, v0
	v_mov_b32_e32 v23, v0
	v_mov_b32_e32 v24, v0
	v_mov_b32_e32 v25, v0
	v_mov_b32_e32 v26, v0
	v_mov_b32_e32 v27, v0
	v_mov_b32_e32 v28, v0
	v_mov_b32_e32 v29, v0
	v_mov_b32_e32 v30, v0
	v_mov_b32_e32 v31, v0
	v_mov_b32_e32 v32, v0
	v_mov_b32_e32 v33, v0
	v_mov_b32_e32 v34, v0
	v_mov_b32_e32 v35, v0
	v_mov_b32_e32 v36, v0
	v_mov_b32_e32 v37, v0
	v_mov_b32_e32 v38, v0
	v_mov_b32_e32 v39, v0
	v_mov_b32_e32 v40, v0
	v_mov_b32_e32 v41, v0
	v_mov_b32_e32 v42, v0
	v_mov_b32_e32 v43, v0
	v_mov_b32_e32 v44, v0
	v_mov_b32_e32 v45, v0
	v_mov_b32_e32 v46, v0
	v_mov_b32_e32 v47, v0
	v_mov_b32_e32 v48, v0
	v_mov_b32_e32 v49, v0
	v_mov_b32_e32 v50, v0
	v_mov_b32_e32 v51, v0
	v_mov_b32_e32 v52, v0
	v_mov_b32_e32 v53, v0
	v_mov_b32_e32 v54, v0
	v_mov_b32_e32 v55, v0
	v_mov_b32_e32 v56, v0
	v_mov_b32_e32 v57, v0
	v_mov_b32_e32 v58, v0
	v_mov_b32_e32 v59, v0
	v_mov_b32_e32 v60, v0
	v_mov_b32_e32 v61, v0
	v_mov_b32_e32 v62, v0
	v_mov_b32_e32 v63, v0
	s_waitcnt vmcnt(0) lgkmcnt(0)
	s_barrier
	v_add3_u32 v182, 0, v131, v132
	v_add_u32_e32 v183, 0x4000, v182
	s_nop 0
	v_readfirstlane_b32 s82, v183
	s_nop 0
	v_readfirstlane_b32 s83, v182
	v_subrev_u32_e32 v184, s52, v90
	v_subrev_u32_e32 v185, s52, v92
	v_subrev_u32_e32 v186, s52, v94
	v_subrev_u32_e32 v187, s52, v96
	v_subrev_u32_e32 v188, s52, v98
	v_subrev_u32_e32 v189, s52, v100
	v_subrev_u32_e32 v190, s52, v102
	v_subrev_u32_e32 v191, s52, v104
	v_subrev_u32_e32 v187, 0x400, v187
	v_subrev_u32_e32 v186, 0x400, v186
	v_subrev_u32_e32 v189, 0x800, v189
	v_subrev_u32_e32 v188, 0x800, v188
	v_subrev_u32_e32 v191, 0xc00, v191
	v_subrev_u32_e32 v190, 0xc00, v190
	s_and_b32 s23, s7, 0x4000
	s_xor_b32 s22, s23, 0x4000
	s_lshl_b32 s22, s22, 1
	s_add_i32 s22, s22, 32
	s_lshl_b32 s23, s23, 1
	s_add_i32 s23, s23, 32

.LBB0_3221:
	s_ashr_i32 s16, s23, 31
	s_lshr_b32 s16, s16, 29
	s_add_i32 s16, s23, s16
	s_ashr_i32 s16, s16, 3
	s_lshr_b32 s17, s16, 4
	s_lshl_b32 s24, s16, 7
	s_lshl_b32 s16, s16, 10
	s_lshl_b32 s25, s23, 7
	s_sub_i32 s25, s25, s16
	v_add_u32_e32 v0, s25, v106
	s_mulk_i32 s17, 0x900
	s_and_b32 s24, s24, 0x780
	v_ashrrev_i32_e32 v1, 31, v0
	v_add_u32_e32 v2, 0x4000, v107
	s_add_i32 s24, s24, s17
	v_lshlrev_b64 v[0:1], 11, v[0:1]
	v_readfirstlane_b32 s26, v2
	s_add_i32 s17, s24, 0x100
	v_lshl_add_u64 v[0:1], v[66:67], 0, v[0:1]
	s_mov_b32 m0, s26
	v_readfirstlane_b32 s26, v107
	global_load_lds_dwordx4 v[0:1], off
	v_add_u32_e32 v0, s17, v106
	v_ashrrev_i32_e32 v1, 31, v0
	v_lshlrev_b64 v[0:1], 11, v[0:1]
	v_lshl_add_u64 v[0:1], v[72:73], 0, v[0:1]
	s_mov_b32 m0, s26
	v_readfirstlane_b32 s26, v131
	global_load_lds_dwordx4 v[0:1], off
	v_add_u32_e32 v0, s25, v108
	v_ashrrev_i32_e32 v1, 31, v0
	v_lshlrev_b64 v[0:1], 11, v[0:1]
	v_lshl_add_u64 v[0:1], v[68:69], 0, v[0:1]
	s_mov_b32 m0, s26
	v_add_u32_e32 v2, 0x400, v107
	global_load_lds_dwordx4 v[0:1], off
	v_add_u32_e32 v0, s17, v108
	v_ashrrev_i32_e32 v1, 31, v0
	v_lshlrev_b64 v[0:1], 11, v[0:1]
	v_readfirstlane_b32 s26, v2
	v_lshl_add_u64 v[0:1], v[74:75], 0, v[0:1]
	s_mov_b32 m0, s26
	v_readfirstlane_b32 s26, v132
	global_load_lds_dwordx4 v[0:1], off
	v_add_u32_e32 v0, s25, v110
	v_ashrrev_i32_e32 v1, 31, v0
	v_lshlrev_b64 v[0:1], 11, v[0:1]
	v_lshl_add_u64 v[0:1], v[66:67], 0, v[0:1]
	s_mov_b32 m0, s26
	v_add_u32_e32 v2, 0x800, v107
	global_load_lds_dwordx4 v[0:1], off
	v_add_u32_e32 v0, s17, v110
	v_ashrrev_i32_e32 v1, 31, v0
	v_lshlrev_b64 v[0:1], 11, v[0:1]
	v_readfirstlane_b32 s26, v2
	v_lshl_add_u64 v[0:1], v[72:73], 0, v[0:1]
	s_mov_b32 m0, s26
	v_readfirstlane_b32 s26, v133
	global_load_lds_dwordx4 v[0:1], off
	v_add_u32_e32 v0, s25, v112
	v_ashrrev_i32_e32 v1, 31, v0
	v_lshlrev_b64 v[0:1], 11, v[0:1]
	v_lshl_add_u64 v[0:1], v[70:71], 0, v[0:1]
	s_mov_b32 m0, s26
	v_add_u32_e32 v2, 0xc00, v107
	global_load_lds_dwordx4 v[0:1], off
	v_add_u32_e32 v0, s17, v112
	v_ashrrev_i32_e32 v1, 31, v0
	v_lshlrev_b64 v[0:1], 11, v[0:1]
	v_readfirstlane_b32 s17, v2
	v_lshl_add_u64 v[0:1], v[76:77], 0, v[0:1]
	s_mov_b32 m0, s17
	s_mov_b32 s26, 0
	global_load_lds_dwordx4 v[0:1], off
	v_subrev_u32_e32 v0, s16, v122
	v_ashrrev_i32_e32 v1, 31, v0
	v_lshlrev_b64 v[0:1], 11, v[0:1]
	v_lshl_add_u64 v[90:91], v[78:79], 0, v[0:1]
	v_add_u32_e32 v0, s24, v123
	v_ashrrev_i32_e32 v1, 31, v0
	v_lshlrev_b64 v[0:1], 11, v[0:1]
	v_lshl_add_u64 v[92:93], v[80:81], 0, v[0:1]
	v_subrev_u32_e32 v0, s16, v124
	v_ashrrev_i32_e32 v1, 31, v0
	v_lshlrev_b64 v[0:1], 11, v[0:1]
	v_lshl_add_u64 v[94:95], v[82:83], 0, v[0:1]
	v_add_u32_e32 v0, s24, v125
	v_ashrrev_i32_e32 v1, 31, v0
	v_lshlrev_b64 v[0:1], 11, v[0:1]
	v_lshl_add_u64 v[96:97], v[84:85], 0, v[0:1]
	v_subrev_u32_e32 v0, s16, v126
	v_ashrrev_i32_e32 v1, 31, v0
	v_lshlrev_b64 v[0:1], 11, v[0:1]
	v_lshl_add_u64 v[98:99], v[78:79], 0, v[0:1]
	v_add_u32_e32 v0, s24, v127
	v_ashrrev_i32_e32 v1, 31, v0
	v_lshlrev_b64 v[0:1], 11, v[0:1]
	v_lshl_add_u64 v[100:101], v[80:81], 0, v[0:1]
	v_subrev_u32_e32 v0, s16, v64
	v_ashrrev_i32_e32 v1, 31, v0
	v_lshlrev_b64 v[0:1], 11, v[0:1]
	v_lshl_add_u64 v[102:103], v[86:87], 0, v[0:1]
	v_add_u32_e32 v0, s24, v128
	v_ashrrev_i32_e32 v1, 31, v0
	v_lshlrev_b64 v[0:1], 11, v[0:1]
	v_lshl_add_u64 v[104:105], v[88:89], 0, v[0:1]
	s_mov_b64 s[16:17], 0
	v_mov_b32_e32 v0, 0
	v_mov_b32_e32 v1, v65
	v_mov_b32_e32 v2, v65
	v_mov_b32_e32 v3, v65
	v_mov_b32_e32 v4, 0
	v_mov_b32_e32 v5, v65
	v_mov_b32_e32 v6, v65
	v_mov_b32_e32 v7, v65
	v_mov_b32_e32 v8, 0
	v_mov_b32_e32 v9, v65
	v_mov_b32_e32 v10, v65
	v_mov_b32_e32 v11, v65
	v_mov_b32_e32 v12, 0
	v_mov_b32_e32 v13, v65
	v_mov_b32_e32 v14, v65
	v_mov_b32_e32 v15, v65
	v_mov_b32_e32 v16, 0
	v_mov_b32_e32 v17, v65
	v_mov_b32_e32 v18, v65
	v_mov_b32_e32 v19, v65
	v_mov_b32_e32 v20, 0
	v_mov_b32_e32 v21, v65
	v_mov_b32_e32 v22, v65
	v_mov_b32_e32 v23, v65
	s_waitcnt vmcnt(0)
	v_mov_b32_e32 v24, 0
	v_mov_b32_e32 v25, v65
	v_mov_b32_e32 v26, v65
	v_mov_b32_e32 v27, v65
	v_mov_b32_e32 v28, 0
	v_mov_b32_e32 v29, v65
	v_mov_b32_e32 v30, v65
	v_mov_b32_e32 v31, v65
	v_mov_b32_e32 v32, 0
	v_mov_b32_e32 v33, v65
	v_mov_b32_e32 v34, v65
	v_mov_b32_e32 v35, v65
	v_mov_b32_e32 v36, 0
	v_mov_b32_e32 v37, v65
	v_mov_b32_e32 v38, v65
	v_mov_b32_e32 v39, v65
	v_mov_b32_e32 v40, 0
	v_mov_b32_e32 v41, v65
	v_mov_b32_e32 v42, v65
	v_mov_b32_e32 v43, v65
	v_mov_b32_e32 v44, 0
	v_mov_b32_e32 v45, v65
	v_mov_b32_e32 v46, v65
	v_mov_b32_e32 v47, v65
	v_mov_b32_e32 v48, 0
	v_mov_b32_e32 v49, v65
	v_mov_b32_e32 v50, v65
	v_mov_b32_e32 v51, v65
	v_mov_b32_e32 v52, 0
	v_mov_b32_e32 v53, v65
	v_mov_b32_e32 v54, v65
	v_mov_b32_e32 v55, v65
	v_mov_b32_e32 v56, 0
	v_mov_b32_e32 v57, v65
	v_mov_b32_e32 v58, v65
	v_mov_b32_e32 v59, v65
	v_mov_b32_e32 v60, 0
	v_mov_b32_e32 v61, v65
	v_mov_b32_e32 v62, v65
	v_mov_b32_e32 v63, v65
	s_waitcnt lgkmcnt(0)
	s_barrier
	v_add3_u32 v182, 0, v134, v135
	v_add_u32_e32 v183, 0x4000, v182
	s_nop 0
	v_readfirstlane_b32 s82, v183
	s_nop 0
	v_readfirstlane_b32 s83, v182
	v_subrev_u32_e32 v184, s52, v90
	v_subrev_u32_e32 v185, s52, v92
	v_subrev_u32_e32 v186, s52, v94
	v_subrev_u32_e32 v187, s52, v96
	v_subrev_u32_e32 v188, s52, v98
	v_subrev_u32_e32 v189, s52, v100
	v_subrev_u32_e32 v190, s52, v102
	v_subrev_u32_e32 v191, s52, v104
	v_subrev_u32_e32 v187, 0x400, v187
	v_subrev_u32_e32 v186, 0x400, v186
	v_subrev_u32_e32 v189, 0x800, v189
	v_subrev_u32_e32 v188, 0x800, v188
	v_subrev_u32_e32 v191, 0xc00, v191
	v_subrev_u32_e32 v190, 0xc00, v190
	s_and_b32 s28, s26, 0x4000
	s_xor_b32 s27, s28, 0x4000
	s_lshl_b32 s27, s27, 1
	s_add_i32 s27, s27, 32
	s_lshl_b32 s28, s28, 1
	s_add_i32 s28, s28, 32

.LBB0_3230:
	s_ashr_i32 s8, s14, 31
	s_lshr_b32 s8, s8, 29
	s_add_i32 s8, s14, s8
	s_ashr_i32 s8, s8, 3
	s_add_i32 s9, s8, s16
	s_lshl_b32 s20, s8, 7
	s_lshl_b32 s8, s8, 10
	s_lshl_b32 s21, s14, 7
	s_sub_i32 s21, s21, s8
	s_lshr_b32 s9, s9, 4
	v_add_u32_e32 v0, s21, v104
	s_mulk_i32 s9, 0x900
	s_and_b32 s20, s20, 0x780
	v_ashrrev_i32_e32 v1, 31, v0
	v_add_u32_e32 v2, 0x4000, v105
	s_add_i32 s20, s20, s9
	v_lshlrev_b64 v[0:1], 11, v[0:1]
	v_readfirstlane_b32 s22, v2
	s_add_i32 s9, s20, 0x100
	v_lshl_add_u64 v[0:1], v[64:65], 0, v[0:1]
	s_mov_b32 m0, s22
	v_readfirstlane_b32 s22, v105
	global_load_lds_dwordx4 v[0:1], off
	v_add_u32_e32 v0, s9, v104
	v_ashrrev_i32_e32 v1, 31, v0
	v_lshlrev_b64 v[0:1], 11, v[0:1]
	v_lshl_add_u64 v[0:1], v[70:71], 0, v[0:1]
	s_mov_b32 m0, s22
	v_readfirstlane_b32 s22, v130
	global_load_lds_dwordx4 v[0:1], off
	v_add_u32_e32 v0, s21, v106
	v_ashrrev_i32_e32 v1, 31, v0
	v_lshlrev_b64 v[0:1], 11, v[0:1]
	v_lshl_add_u64 v[0:1], v[66:67], 0, v[0:1]
	s_mov_b32 m0, s22
	v_add_u32_e32 v2, 0x400, v105
	global_load_lds_dwordx4 v[0:1], off
	v_add_u32_e32 v0, s9, v106
	v_ashrrev_i32_e32 v1, 31, v0
	v_lshlrev_b64 v[0:1], 11, v[0:1]
	v_readfirstlane_b32 s22, v2
	v_lshl_add_u64 v[0:1], v[72:73], 0, v[0:1]
	s_mov_b32 m0, s22
	v_readfirstlane_b32 s22, v131
	global_load_lds_dwordx4 v[0:1], off
	v_add_u32_e32 v0, s21, v108
	v_ashrrev_i32_e32 v1, 31, v0
	v_lshlrev_b64 v[0:1], 11, v[0:1]
	v_lshl_add_u64 v[0:1], v[64:65], 0, v[0:1]
	s_mov_b32 m0, s22
	v_add_u32_e32 v2, 0x800, v105
	global_load_lds_dwordx4 v[0:1], off
	v_add_u32_e32 v0, s9, v108
	v_ashrrev_i32_e32 v1, 31, v0
	v_lshlrev_b64 v[0:1], 11, v[0:1]
	v_readfirstlane_b32 s22, v2
	v_lshl_add_u64 v[0:1], v[70:71], 0, v[0:1]
	s_mov_b32 m0, s22
	v_readfirstlane_b32 s22, v132
	global_load_lds_dwordx4 v[0:1], off
	v_add_u32_e32 v0, s21, v110
	v_ashrrev_i32_e32 v1, 31, v0
	v_lshlrev_b64 v[0:1], 11, v[0:1]
	v_lshl_add_u64 v[0:1], v[68:69], 0, v[0:1]
	s_mov_b32 m0, s22
	v_add_u32_e32 v2, 0xc00, v105
	global_load_lds_dwordx4 v[0:1], off
	v_add_u32_e32 v0, s9, v110
	v_ashrrev_i32_e32 v1, 31, v0
	v_lshlrev_b64 v[0:1], 11, v[0:1]
	v_readfirstlane_b32 s9, v2
	v_lshl_add_u64 v[0:1], v[74:75], 0, v[0:1]
	s_mov_b32 m0, s9
	s_mov_b32 s22, 0
	global_load_lds_dwordx4 v[0:1], off
	v_subrev_u32_e32 v0, s8, v120
	v_ashrrev_i32_e32 v1, 31, v0
	v_lshlrev_b64 v[0:1], 11, v[0:1]
	v_lshl_add_u64 v[88:89], v[76:77], 0, v[0:1]
	v_add_u32_e32 v0, s20, v121
	v_ashrrev_i32_e32 v1, 31, v0
	v_lshlrev_b64 v[0:1], 11, v[0:1]
	v_lshl_add_u64 v[90:91], v[78:79], 0, v[0:1]
	v_subrev_u32_e32 v0, s8, v122
	v_ashrrev_i32_e32 v1, 31, v0
	v_lshlrev_b64 v[0:1], 11, v[0:1]
	v_lshl_add_u64 v[92:93], v[80:81], 0, v[0:1]
	v_add_u32_e32 v0, s20, v123
	v_ashrrev_i32_e32 v1, 31, v0
	v_lshlrev_b64 v[0:1], 11, v[0:1]
	v_lshl_add_u64 v[94:95], v[82:83], 0, v[0:1]
	v_subrev_u32_e32 v0, s8, v124
	v_ashrrev_i32_e32 v1, 31, v0
	v_lshlrev_b64 v[0:1], 11, v[0:1]
	v_lshl_add_u64 v[96:97], v[76:77], 0, v[0:1]
	v_add_u32_e32 v0, s20, v125
	v_ashrrev_i32_e32 v1, 31, v0
	v_lshlrev_b64 v[0:1], 11, v[0:1]
	v_lshl_add_u64 v[98:99], v[78:79], 0, v[0:1]
	v_subrev_u32_e32 v0, s8, v126
	v_ashrrev_i32_e32 v1, 31, v0
	v_lshlrev_b64 v[0:1], 11, v[0:1]
	v_lshl_add_u64 v[100:101], v[84:85], 0, v[0:1]
	v_add_u32_e32 v0, s20, v127
	v_ashrrev_i32_e32 v1, 31, v0
	v_lshlrev_b64 v[0:1], 11, v[0:1]
	v_lshl_add_u64 v[102:103], v[86:87], 0, v[0:1]
	v_mov_b32_e32 v0, 0
	s_mov_b64 s[8:9], 0
	v_mov_b32_e32 v1, v0
	v_mov_b32_e32 v2, v0
	v_mov_b32_e32 v3, v0
	v_mov_b32_e32 v4, v0
	v_mov_b32_e32 v5, v0
	v_mov_b32_e32 v6, v0
	v_mov_b32_e32 v7, v0
	v_mov_b32_e32 v8, v0
	v_mov_b32_e32 v9, v0
	v_mov_b32_e32 v10, v0
	v_mov_b32_e32 v11, v0
	v_mov_b32_e32 v12, v0
	v_mov_b32_e32 v13, v0
	v_mov_b32_e32 v14, v0
	v_mov_b32_e32 v15, v0
	v_mov_b32_e32 v16, v0
	v_mov_b32_e32 v17, v0
	v_mov_b32_e32 v18, v0
	v_mov_b32_e32 v19, v0
	v_mov_b32_e32 v20, v0
	v_mov_b32_e32 v21, v0
	v_mov_b32_e32 v22, v0
	v_mov_b32_e32 v23, v0
	v_mov_b32_e32 v24, v0
	v_mov_b32_e32 v25, v0
	v_mov_b32_e32 v26, v0
	v_mov_b32_e32 v27, v0
	s_waitcnt vmcnt(0)
	v_mov_b32_e32 v28, v0
	v_mov_b32_e32 v29, v0
	v_mov_b32_e32 v30, v0
	v_mov_b32_e32 v31, v0
	v_mov_b32_e32 v32, v0
	v_mov_b32_e32 v33, v0
	v_mov_b32_e32 v34, v0
	v_mov_b32_e32 v35, v0
	v_mov_b32_e32 v36, v0
	v_mov_b32_e32 v37, v0
	v_mov_b32_e32 v38, v0
	v_mov_b32_e32 v39, v0
	v_mov_b32_e32 v40, v0
	v_mov_b32_e32 v41, v0
	v_mov_b32_e32 v42, v0
	v_mov_b32_e32 v43, v0
	v_mov_b32_e32 v44, v0
	v_mov_b32_e32 v45, v0
	v_mov_b32_e32 v46, v0
	v_mov_b32_e32 v47, v0
	v_mov_b32_e32 v48, v0
	v_mov_b32_e32 v49, v0
	v_mov_b32_e32 v50, v0
	v_mov_b32_e32 v51, v0
	v_mov_b32_e32 v52, v0
	v_mov_b32_e32 v53, v0
	v_mov_b32_e32 v54, v0
	v_mov_b32_e32 v55, v0
	v_mov_b32_e32 v56, v0
	v_mov_b32_e32 v57, v0
	v_mov_b32_e32 v58, v0
	v_mov_b32_e32 v59, v0
	v_mov_b32_e32 v60, v0
	v_mov_b32_e32 v61, v0
	v_mov_b32_e32 v62, v0
	v_mov_b32_e32 v63, v0
	s_waitcnt lgkmcnt(0)
	s_barrier
	v_add3_u32 v182, 0, v133, v134
	v_add_u32_e32 v183, 0x4000, v182
	s_nop 0
	v_readfirstlane_b32 s82, v183
	s_nop 0
	v_readfirstlane_b32 s83, v182
	v_subrev_u32_e32 v184, s52, v88
	v_subrev_u32_e32 v185, s52, v90
	v_subrev_u32_e32 v186, s52, v92
	v_subrev_u32_e32 v187, s52, v94
	v_subrev_u32_e32 v188, s52, v96
	v_subrev_u32_e32 v189, s52, v98
	v_subrev_u32_e32 v190, s52, v100
	v_subrev_u32_e32 v191, s52, v102
	v_subrev_u32_e32 v187, 0x400, v187
	v_subrev_u32_e32 v186, 0x400, v186
	v_subrev_u32_e32 v189, 0x800, v189
	v_subrev_u32_e32 v188, 0x800, v188
	v_subrev_u32_e32 v191, 0xc00, v191
	v_subrev_u32_e32 v190, 0xc00, v190
	s_and_b32 s24, s22, 0x4000
	s_xor_b32 s23, s24, 0x4000
	s_lshl_b32 s23, s23, 1
	s_add_i32 s23, s23, 32
	s_lshl_b32 s24, s24, 1
	s_add_i32 s24, s24, 32

.LBB0_3387:
	s_ashr_i32 s12, s16, 31
	s_lshr_b32 s12, s12, 27
	s_add_i32 s12, s16, s12
	s_ashr_i32 s12, s12, 5
	s_lshr_b32 s13, s12, 4
	s_lshl_b32 s17, s12, 7
	s_lshl_b32 s12, s12, 12
	s_lshl_b32 s18, s16, 7
	s_sub_i32 s18, s18, s12
	v_add_u32_e32 v0, s18, v106
	s_mulk_i32 s13, 0x900
	s_and_b32 s17, s17, 0x780
	v_ashrrev_i32_e32 v1, 31, v0
	v_add_u32_e32 v2, 0x4000, v107
	s_add_i32 s17, s17, s13
	v_lshlrev_b64 v[0:1], 11, v[0:1]
	v_readfirstlane_b32 s19, v2
	s_add_i32 s13, s17, 0x100
	v_lshl_add_u64 v[0:1], v[66:67], 0, v[0:1]
	s_mov_b32 m0, s19
	v_readfirstlane_b32 s19, v107
	global_load_lds_dwordx4 v[0:1], off
	v_add_u32_e32 v0, s13, v106
	v_ashrrev_i32_e32 v1, 31, v0
	v_lshlrev_b64 v[0:1], 11, v[0:1]
	v_lshl_add_u64 v[0:1], v[72:73], 0, v[0:1]
	s_mov_b32 m0, s19
	v_readfirstlane_b32 s19, v131
	global_load_lds_dwordx4 v[0:1], off
	v_add_u32_e32 v0, s18, v108
	v_ashrrev_i32_e32 v1, 31, v0
	v_lshlrev_b64 v[0:1], 11, v[0:1]
	v_lshl_add_u64 v[0:1], v[68:69], 0, v[0:1]
	s_mov_b32 m0, s19
	v_add_u32_e32 v2, 0x400, v107
	global_load_lds_dwordx4 v[0:1], off
	v_add_u32_e32 v0, s13, v108
	v_ashrrev_i32_e32 v1, 31, v0
	v_lshlrev_b64 v[0:1], 11, v[0:1]
	v_readfirstlane_b32 s19, v2
	v_lshl_add_u64 v[0:1], v[74:75], 0, v[0:1]
	s_mov_b32 m0, s19
	v_readfirstlane_b32 s19, v132
	global_load_lds_dwordx4 v[0:1], off
	v_add_u32_e32 v0, s18, v110
	v_ashrrev_i32_e32 v1, 31, v0
	v_lshlrev_b64 v[0:1], 11, v[0:1]
	v_lshl_add_u64 v[0:1], v[66:67], 0, v[0:1]
	s_mov_b32 m0, s19
	v_add_u32_e32 v2, 0x800, v107
	global_load_lds_dwordx4 v[0:1], off
	v_add_u32_e32 v0, s13, v110
	v_ashrrev_i32_e32 v1, 31, v0
	v_lshlrev_b64 v[0:1], 11, v[0:1]
	v_readfirstlane_b32 s19, v2
	v_lshl_add_u64 v[0:1], v[72:73], 0, v[0:1]
	s_mov_b32 m0, s19
	v_readfirstlane_b32 s19, v133
	global_load_lds_dwordx4 v[0:1], off
	v_add_u32_e32 v0, s18, v112
	v_ashrrev_i32_e32 v1, 31, v0
	v_lshlrev_b64 v[0:1], 11, v[0:1]
	v_lshl_add_u64 v[0:1], v[70:71], 0, v[0:1]
	s_mov_b32 m0, s19
	v_add_u32_e32 v2, 0xc00, v107
	global_load_lds_dwordx4 v[0:1], off
	v_add_u32_e32 v0, s13, v112
	v_ashrrev_i32_e32 v1, 31, v0
	v_lshlrev_b64 v[0:1], 11, v[0:1]
	v_readfirstlane_b32 s13, v2
	v_lshl_add_u64 v[0:1], v[76:77], 0, v[0:1]
	s_mov_b32 m0, s13
	s_mov_b32 s19, 0
	global_load_lds_dwordx4 v[0:1], off
	v_subrev_u32_e32 v0, s12, v122
	v_ashrrev_i32_e32 v1, 31, v0
	v_lshlrev_b64 v[0:1], 11, v[0:1]
	v_lshl_add_u64 v[90:91], v[78:79], 0, v[0:1]
	v_add_u32_e32 v0, s17, v123
	v_ashrrev_i32_e32 v1, 31, v0
	v_lshlrev_b64 v[0:1], 11, v[0:1]
	v_lshl_add_u64 v[92:93], v[80:81], 0, v[0:1]
	v_subrev_u32_e32 v0, s12, v124
	v_ashrrev_i32_e32 v1, 31, v0
	v_lshlrev_b64 v[0:1], 11, v[0:1]
	v_lshl_add_u64 v[94:95], v[82:83], 0, v[0:1]
	v_add_u32_e32 v0, s17, v125
	v_ashrrev_i32_e32 v1, 31, v0
	v_lshlrev_b64 v[0:1], 11, v[0:1]
	v_lshl_add_u64 v[96:97], v[84:85], 0, v[0:1]
	v_subrev_u32_e32 v0, s12, v126
	v_ashrrev_i32_e32 v1, 31, v0
	v_lshlrev_b64 v[0:1], 11, v[0:1]
	v_lshl_add_u64 v[98:99], v[78:79], 0, v[0:1]
	v_add_u32_e32 v0, s17, v127
	v_ashrrev_i32_e32 v1, 31, v0
	v_lshlrev_b64 v[0:1], 11, v[0:1]
	v_lshl_add_u64 v[100:101], v[80:81], 0, v[0:1]
	v_subrev_u32_e32 v0, s12, v64
	v_ashrrev_i32_e32 v1, 31, v0
	v_lshlrev_b64 v[0:1], 11, v[0:1]
	v_lshl_add_u64 v[102:103], v[86:87], 0, v[0:1]
	v_add_u32_e32 v0, s17, v128
	v_ashrrev_i32_e32 v1, 31, v0
	v_lshlrev_b64 v[0:1], 11, v[0:1]
	v_lshl_add_u64 v[104:105], v[88:89], 0, v[0:1]
	s_mov_b64 s[12:13], 0
	v_mov_b32_e32 v0, 0
	v_mov_b32_e32 v1, v65
	v_mov_b32_e32 v2, v65
	v_mov_b32_e32 v3, v65
	v_mov_b32_e32 v4, 0
	v_mov_b32_e32 v5, v65
	v_mov_b32_e32 v6, v65
	v_mov_b32_e32 v7, v65
	v_mov_b32_e32 v8, 0
	v_mov_b32_e32 v9, v65
	v_mov_b32_e32 v10, v65
	v_mov_b32_e32 v11, v65
	v_mov_b32_e32 v12, 0
	v_mov_b32_e32 v13, v65
	v_mov_b32_e32 v14, v65
	v_mov_b32_e32 v15, v65
	v_mov_b32_e32 v16, 0
	v_mov_b32_e32 v17, v65
	v_mov_b32_e32 v18, v65
	v_mov_b32_e32 v19, v65
	v_mov_b32_e32 v20, 0
	v_mov_b32_e32 v21, v65
	v_mov_b32_e32 v22, v65
	v_mov_b32_e32 v23, v65
	v_mov_b32_e32 v24, 0
	v_mov_b32_e32 v25, v65
	v_mov_b32_e32 v26, v65
	v_mov_b32_e32 v27, v65
	v_mov_b32_e32 v28, 0
	v_mov_b32_e32 v29, v65
	v_mov_b32_e32 v30, v65
	v_mov_b32_e32 v31, v65
	v_mov_b32_e32 v32, 0
	v_mov_b32_e32 v33, v65
	v_mov_b32_e32 v34, v65
	v_mov_b32_e32 v35, v65
	v_mov_b32_e32 v36, 0
	v_mov_b32_e32 v37, v65
	v_mov_b32_e32 v38, v65
	v_mov_b32_e32 v39, v65
	v_mov_b32_e32 v40, 0
	v_mov_b32_e32 v41, v65
	v_mov_b32_e32 v42, v65
	v_mov_b32_e32 v43, v65
	v_mov_b32_e32 v44, 0
	v_mov_b32_e32 v45, v65
	v_mov_b32_e32 v46, v65
	v_mov_b32_e32 v47, v65
	v_mov_b32_e32 v48, 0
	v_mov_b32_e32 v49, v65
	v_mov_b32_e32 v50, v65
	v_mov_b32_e32 v51, v65
	v_mov_b32_e32 v52, 0
	v_mov_b32_e32 v53, v65
	v_mov_b32_e32 v54, v65
	v_mov_b32_e32 v55, v65
	v_mov_b32_e32 v56, 0
	v_mov_b32_e32 v57, v65
	v_mov_b32_e32 v58, v65
	v_mov_b32_e32 v59, v65
	v_mov_b32_e32 v60, 0
	v_mov_b32_e32 v61, v65
	v_mov_b32_e32 v62, v65
	v_mov_b32_e32 v63, v65
	s_waitcnt vmcnt(0) lgkmcnt(0)
	s_barrier
	v_add3_u32 v182, 0, v134, v135
	v_add_u32_e32 v183, 0x4000, v182
	s_nop 0
	v_readfirstlane_b32 s82, v183
	s_nop 0
	v_readfirstlane_b32 s83, v182
	v_subrev_u32_e32 v184, s52, v90
	v_subrev_u32_e32 v185, s52, v92
	v_subrev_u32_e32 v186, s52, v94
	v_subrev_u32_e32 v187, s52, v96
	v_subrev_u32_e32 v188, s52, v98
	v_subrev_u32_e32 v189, s52, v100
	v_subrev_u32_e32 v190, s52, v102
	v_subrev_u32_e32 v191, s52, v104
	v_subrev_u32_e32 v187, 0x400, v187
	v_subrev_u32_e32 v186, 0x400, v186
	v_subrev_u32_e32 v189, 0x800, v189
	v_subrev_u32_e32 v188, 0x800, v188
	v_subrev_u32_e32 v191, 0xc00, v191
	v_subrev_u32_e32 v190, 0xc00, v190
	s_and_b32 s21, s19, 0x4000
	s_xor_b32 s20, s21, 0x4000
	s_lshl_b32 s20, s20, 1
	s_add_i32 s20, s20, 32
	s_lshl_b32 s21, s21, 1
	s_add_i32 s21, s21, 32

.LBB0_3398:
	s_ashr_i32 s15, s9, 31
	s_lshr_b32 s15, s15, 29
	s_add_i32 s15, s9, s15
	s_ashr_i32 s16, s15, 3
	s_lshl_b32 s18, s16, 10
	s_lshl_b32 s9, s9, 7
	s_add_i32 s15, s16, s14
	s_lshl_b32 s17, s16, 7
	s_sub_i32 s16, s9, s18
	s_add_i32 s16, s16, s8
	s_lshr_b32 s15, s15, 4
	v_add_u32_e32 v0, s16, v104
	s_mulk_i32 s15, 0x900
	s_and_b32 s17, s17, 0x780
	v_ashrrev_i32_e32 v1, 31, v0
	v_add_u32_e32 v2, 0x4000, v105
	s_add_i32 s15, s17, s15
	v_lshlrev_b64 v[0:1], 11, v[0:1]
	v_readfirstlane_b32 s19, v2
	s_add_i32 s17, s15, 0x100
	v_lshl_add_u64 v[0:1], v[64:65], 0, v[0:1]
	s_mov_b32 m0, s19
	v_readfirstlane_b32 s19, v105
	global_load_lds_dwordx4 v[0:1], off
	v_add_u32_e32 v0, s17, v104
	v_ashrrev_i32_e32 v1, 31, v0
	v_lshlrev_b64 v[0:1], 11, v[0:1]
	v_lshl_add_u64 v[0:1], v[70:71], 0, v[0:1]
	s_mov_b32 m0, s19
	v_readfirstlane_b32 s19, v129
	global_load_lds_dwordx4 v[0:1], off
	v_add_u32_e32 v0, s16, v106
	v_ashrrev_i32_e32 v1, 31, v0
	v_lshlrev_b64 v[0:1], 11, v[0:1]
	v_lshl_add_u64 v[0:1], v[66:67], 0, v[0:1]
	s_mov_b32 m0, s19
	v_add_u32_e32 v2, 0x400, v105
	global_load_lds_dwordx4 v[0:1], off
	v_add_u32_e32 v0, s17, v106
	v_ashrrev_i32_e32 v1, 31, v0
	v_lshlrev_b64 v[0:1], 11, v[0:1]
	v_readfirstlane_b32 s19, v2
	v_lshl_add_u64 v[0:1], v[72:73], 0, v[0:1]
	s_mov_b32 m0, s19
	v_readfirstlane_b32 s19, v130
	global_load_lds_dwordx4 v[0:1], off
	v_add_u32_e32 v0, s16, v108
	v_ashrrev_i32_e32 v1, 31, v0
	v_lshlrev_b64 v[0:1], 11, v[0:1]
	v_lshl_add_u64 v[0:1], v[64:65], 0, v[0:1]
	s_mov_b32 m0, s19
	v_add_u32_e32 v2, 0x800, v105
	global_load_lds_dwordx4 v[0:1], off
	v_add_u32_e32 v0, s17, v108
	v_ashrrev_i32_e32 v1, 31, v0
	v_lshlrev_b64 v[0:1], 11, v[0:1]
	v_readfirstlane_b32 s19, v2
	v_lshl_add_u64 v[0:1], v[70:71], 0, v[0:1]
	s_mov_b32 m0, s19
	v_readfirstlane_b32 s19, v131
	global_load_lds_dwordx4 v[0:1], off
	v_add_u32_e32 v0, s16, v110
	v_ashrrev_i32_e32 v1, 31, v0
	v_lshlrev_b64 v[0:1], 11, v[0:1]
	v_lshl_add_u64 v[0:1], v[68:69], 0, v[0:1]
	s_mov_b32 m0, s19
	v_add_u32_e32 v2, 0xc00, v105
	global_load_lds_dwordx4 v[0:1], off
	v_add_u32_e32 v0, s17, v110
	v_ashrrev_i32_e32 v1, 31, v0
	v_lshlrev_b64 v[0:1], 11, v[0:1]
	v_readfirstlane_b32 s17, v2
	v_lshl_add_u64 v[0:1], v[74:75], 0, v[0:1]
	s_mov_b32 m0, s17
	s_add_i32 s9, s9, s8
	global_load_lds_dwordx4 v[0:1], off
	v_add_u32_e32 v0, s9, v104
	v_subrev_u32_e32 v0, s18, v0
	v_ashrrev_i32_e32 v1, 31, v0
	v_lshlrev_b64 v[0:1], 11, v[0:1]
	v_lshl_add_u64 v[88:89], v[76:77], 0, v[0:1]
	v_add_u32_e32 v0, s15, v120
	v_ashrrev_i32_e32 v1, 31, v0
	v_lshlrev_b64 v[0:1], 11, v[0:1]
	v_lshl_add_u64 v[90:91], v[78:79], 0, v[0:1]
	v_add_u32_e32 v0, s9, v121
	v_subrev_u32_e32 v0, s18, v0
	v_ashrrev_i32_e32 v1, 31, v0
	v_lshlrev_b64 v[0:1], 11, v[0:1]
	v_lshl_add_u64 v[92:93], v[80:81], 0, v[0:1]
	v_add_u32_e32 v0, s15, v122
	v_ashrrev_i32_e32 v1, 31, v0
	v_lshlrev_b64 v[0:1], 11, v[0:1]
	v_lshl_add_u64 v[94:95], v[82:83], 0, v[0:1]
	v_add_u32_e32 v0, s9, v123
	v_subrev_u32_e32 v0, s18, v0
	v_ashrrev_i32_e32 v1, 31, v0
	v_lshlrev_b64 v[0:1], 11, v[0:1]
	v_lshl_add_u64 v[96:97], v[76:77], 0, v[0:1]
	v_add_u32_e32 v0, s15, v124
	v_ashrrev_i32_e32 v1, 31, v0
	v_lshlrev_b64 v[0:1], 11, v[0:1]
	v_lshl_add_u64 v[98:99], v[78:79], 0, v[0:1]
	v_add_u32_e32 v0, s9, v125
	v_subrev_u32_e32 v0, s18, v0
	v_ashrrev_i32_e32 v1, 31, v0
	v_lshlrev_b64 v[0:1], 11, v[0:1]
	v_lshl_add_u64 v[100:101], v[84:85], 0, v[0:1]
	v_add_u32_e32 v0, s15, v126
	v_ashrrev_i32_e32 v1, 31, v0
	v_lshlrev_b64 v[0:1], 11, v[0:1]
	v_lshl_add_u64 v[102:103], v[86:87], 0, v[0:1]
	v_mov_b32_e32 v0, 0
	s_mov_b32 s17, 0
	s_mov_b64 s[8:9], 0
	v_mov_b32_e32 v1, v0
	v_mov_b32_e32 v2, v0
	v_mov_b32_e32 v3, v0
	v_mov_b32_e32 v4, v0
	v_mov_b32_e32 v5, v0
	v_mov_b32_e32 v6, v0
	v_mov_b32_e32 v7, v0
	v_mov_b32_e32 v8, v0
	v_mov_b32_e32 v9, v0
	v_mov_b32_e32 v10, v0
	v_mov_b32_e32 v11, v0
	v_mov_b32_e32 v12, v0
	v_mov_b32_e32 v13, v0
	v_mov_b32_e32 v14, v0
	v_mov_b32_e32 v15, v0
	v_mov_b32_e32 v16, v0
	v_mov_b32_e32 v17, v0
	v_mov_b32_e32 v18, v0
	v_mov_b32_e32 v19, v0
	v_mov_b32_e32 v20, v0
	v_mov_b32_e32 v21, v0
	v_mov_b32_e32 v22, v0
	v_mov_b32_e32 v23, v0
	v_mov_b32_e32 v24, v0
	v_mov_b32_e32 v25, v0
	v_mov_b32_e32 v26, v0
	v_mov_b32_e32 v27, v0
	v_mov_b32_e32 v28, v0
	v_mov_b32_e32 v29, v0
	v_mov_b32_e32 v30, v0
	v_mov_b32_e32 v31, v0
	v_mov_b32_e32 v32, v0
	v_mov_b32_e32 v33, v0
	v_mov_b32_e32 v34, v0
	v_mov_b32_e32 v35, v0
	v_mov_b32_e32 v36, v0
	v_mov_b32_e32 v37, v0
	v_mov_b32_e32 v38, v0
	v_mov_b32_e32 v39, v0
	v_mov_b32_e32 v40, v0
	v_mov_b32_e32 v41, v0
	v_mov_b32_e32 v42, v0
	v_mov_b32_e32 v43, v0
	v_mov_b32_e32 v44, v0
	v_mov_b32_e32 v45, v0
	v_mov_b32_e32 v46, v0
	v_mov_b32_e32 v47, v0
	v_mov_b32_e32 v48, v0
	v_mov_b32_e32 v49, v0
	v_mov_b32_e32 v50, v0
	v_mov_b32_e32 v51, v0
	v_mov_b32_e32 v52, v0
	v_mov_b32_e32 v53, v0
	v_mov_b32_e32 v54, v0
	v_mov_b32_e32 v55, v0
	v_mov_b32_e32 v56, v0
	v_mov_b32_e32 v57, v0
	v_mov_b32_e32 v58, v0
	v_mov_b32_e32 v59, v0
	v_mov_b32_e32 v60, v0
	v_mov_b32_e32 v61, v0
	v_mov_b32_e32 v62, v0
	v_mov_b32_e32 v63, v0
	s_waitcnt vmcnt(0) lgkmcnt(0)
	s_barrier
	v_add3_u32 v182, 0, v132, v133
	v_add_u32_e32 v183, 0x4000, v182
	s_nop 0
	v_readfirstlane_b32 s82, v183
	s_nop 0
	v_readfirstlane_b32 s83, v182
	v_subrev_u32_e32 v184, s52, v88
	v_subrev_u32_e32 v185, s52, v90
	v_subrev_u32_e32 v186, s52, v92
	v_subrev_u32_e32 v187, s52, v94
	v_subrev_u32_e32 v188, s52, v96
	v_subrev_u32_e32 v189, s52, v98
	v_subrev_u32_e32 v190, s52, v100
	v_subrev_u32_e32 v191, s52, v102
	v_subrev_u32_e32 v187, 0x400, v187
	v_subrev_u32_e32 v186, 0x400, v186
	v_subrev_u32_e32 v189, 0x800, v189
	v_subrev_u32_e32 v188, 0x800, v188
	v_subrev_u32_e32 v191, 0xc00, v191
	v_subrev_u32_e32 v190, 0xc00, v190
	s_and_b32 s19, s17, 0x4000
	s_xor_b32 s18, s19, 0x4000
	s_lshl_b32 s18, s18, 1
	s_add_i32 s18, s18, 32
	s_lshl_b32 s19, s19, 1
	s_add_i32 s19, s19, 32

.LBB0_3462:
	s_ashr_i32 s16, s23, 31
	s_lshr_b32 s16, s16, 29
	s_add_i32 s16, s23, s16
	s_ashr_i32 s16, s16, 3
	s_lshr_b32 s17, s16, 4
	s_lshl_b32 s24, s16, 7
	s_lshl_b32 s16, s16, 10
	s_lshl_b32 s25, s23, 7
	s_sub_i32 s25, s25, s16
	v_add_u32_e32 v0, s25, v106
	s_mulk_i32 s17, 0x900
	s_and_b32 s24, s24, 0x780
	v_ashrrev_i32_e32 v1, 31, v0
	v_add_u32_e32 v2, 0x4000, v107
	s_add_i32 s24, s24, s17
	v_lshlrev_b64 v[0:1], 13, v[0:1]
	v_readfirstlane_b32 s26, v2
	s_add_i32 s17, s24, 0x100
	v_lshl_add_u64 v[0:1], v[66:67], 0, v[0:1]
	s_mov_b32 m0, s26
	v_readfirstlane_b32 s26, v107
	global_load_lds_dwordx4 v[0:1], off
	v_add_u32_e32 v0, s17, v106
	v_ashrrev_i32_e32 v1, 31, v0
	v_lshlrev_b64 v[0:1], 13, v[0:1]
	v_lshl_add_u64 v[0:1], v[72:73], 0, v[0:1]
	s_mov_b32 m0, s26
	v_readfirstlane_b32 s26, v131
	global_load_lds_dwordx4 v[0:1], off
	v_add_u32_e32 v0, s25, v108
	v_ashrrev_i32_e32 v1, 31, v0
	v_lshlrev_b64 v[0:1], 13, v[0:1]
	v_lshl_add_u64 v[0:1], v[68:69], 0, v[0:1]
	s_mov_b32 m0, s26
	v_add_u32_e32 v2, 0x400, v107
	global_load_lds_dwordx4 v[0:1], off
	v_add_u32_e32 v0, s17, v108
	v_ashrrev_i32_e32 v1, 31, v0
	v_lshlrev_b64 v[0:1], 13, v[0:1]
	v_readfirstlane_b32 s26, v2
	v_lshl_add_u64 v[0:1], v[74:75], 0, v[0:1]
	s_mov_b32 m0, s26
	v_readfirstlane_b32 s26, v132
	global_load_lds_dwordx4 v[0:1], off
	v_add_u32_e32 v0, s25, v110
	v_ashrrev_i32_e32 v1, 31, v0
	v_lshlrev_b64 v[0:1], 13, v[0:1]
	v_lshl_add_u64 v[0:1], v[66:67], 0, v[0:1]
	s_mov_b32 m0, s26
	v_add_u32_e32 v2, 0x800, v107
	global_load_lds_dwordx4 v[0:1], off
	v_add_u32_e32 v0, s17, v110
	v_ashrrev_i32_e32 v1, 31, v0
	v_lshlrev_b64 v[0:1], 13, v[0:1]
	v_readfirstlane_b32 s26, v2
	v_lshl_add_u64 v[0:1], v[72:73], 0, v[0:1]
	s_mov_b32 m0, s26
	v_readfirstlane_b32 s26, v133
	global_load_lds_dwordx4 v[0:1], off
	v_add_u32_e32 v0, s25, v112
	v_ashrrev_i32_e32 v1, 31, v0
	v_lshlrev_b64 v[0:1], 13, v[0:1]
	v_lshl_add_u64 v[0:1], v[70:71], 0, v[0:1]
	s_mov_b32 m0, s26
	v_add_u32_e32 v2, 0xc00, v107
	global_load_lds_dwordx4 v[0:1], off
	v_add_u32_e32 v0, s17, v112
	v_ashrrev_i32_e32 v1, 31, v0
	v_lshlrev_b64 v[0:1], 13, v[0:1]
	v_readfirstlane_b32 s17, v2
	v_lshl_add_u64 v[0:1], v[76:77], 0, v[0:1]
	s_mov_b32 m0, s17
	s_mov_b32 s26, 0
	global_load_lds_dwordx4 v[0:1], off
	v_subrev_u32_e32 v0, s16, v122
	v_ashrrev_i32_e32 v1, 31, v0
	v_lshlrev_b64 v[0:1], 13, v[0:1]
	v_lshl_add_u64 v[90:91], v[78:79], 0, v[0:1]
	v_add_u32_e32 v0, s24, v123
	v_ashrrev_i32_e32 v1, 31, v0
	v_lshlrev_b64 v[0:1], 13, v[0:1]
	v_lshl_add_u64 v[92:93], v[80:81], 0, v[0:1]
	v_subrev_u32_e32 v0, s16, v124
	v_ashrrev_i32_e32 v1, 31, v0
	v_lshlrev_b64 v[0:1], 13, v[0:1]
	v_lshl_add_u64 v[94:95], v[82:83], 0, v[0:1]
	v_add_u32_e32 v0, s24, v125
	v_ashrrev_i32_e32 v1, 31, v0
	v_lshlrev_b64 v[0:1], 13, v[0:1]
	v_lshl_add_u64 v[96:97], v[84:85], 0, v[0:1]
	v_subrev_u32_e32 v0, s16, v126
	v_ashrrev_i32_e32 v1, 31, v0
	v_lshlrev_b64 v[0:1], 13, v[0:1]
	v_lshl_add_u64 v[98:99], v[78:79], 0, v[0:1]
	v_add_u32_e32 v0, s24, v127
	v_ashrrev_i32_e32 v1, 31, v0
	v_lshlrev_b64 v[0:1], 13, v[0:1]
	v_lshl_add_u64 v[100:101], v[80:81], 0, v[0:1]
	v_subrev_u32_e32 v0, s16, v64
	v_ashrrev_i32_e32 v1, 31, v0
	v_lshlrev_b64 v[0:1], 13, v[0:1]
	v_lshl_add_u64 v[102:103], v[86:87], 0, v[0:1]
	v_add_u32_e32 v0, s24, v128
	v_ashrrev_i32_e32 v1, 31, v0
	v_lshlrev_b64 v[0:1], 13, v[0:1]
	v_lshl_add_u64 v[104:105], v[88:89], 0, v[0:1]
	s_mov_b64 s[16:17], 0
	v_mov_b32_e32 v0, 0
	v_mov_b32_e32 v1, v65
	v_mov_b32_e32 v2, v65
	v_mov_b32_e32 v3, v65
	v_mov_b32_e32 v4, 0
	v_mov_b32_e32 v5, v65
	v_mov_b32_e32 v6, v65
	v_mov_b32_e32 v7, v65
	v_mov_b32_e32 v8, 0
	v_mov_b32_e32 v9, v65
	v_mov_b32_e32 v10, v65
	v_mov_b32_e32 v11, v65
	v_mov_b32_e32 v12, 0
	v_mov_b32_e32 v13, v65
	v_mov_b32_e32 v14, v65
	v_mov_b32_e32 v15, v65
	v_mov_b32_e32 v16, 0
	v_mov_b32_e32 v17, v65
	v_mov_b32_e32 v18, v65
	v_mov_b32_e32 v19, v65
	v_mov_b32_e32 v20, 0
	v_mov_b32_e32 v21, v65
	v_mov_b32_e32 v22, v65
	v_mov_b32_e32 v23, v65
	s_waitcnt vmcnt(0)
	v_mov_b32_e32 v24, 0
	v_mov_b32_e32 v25, v65
	v_mov_b32_e32 v26, v65
	v_mov_b32_e32 v27, v65
	v_mov_b32_e32 v28, 0
	v_mov_b32_e32 v29, v65
	v_mov_b32_e32 v30, v65
	v_mov_b32_e32 v31, v65
	v_mov_b32_e32 v32, 0
	v_mov_b32_e32 v33, v65
	v_mov_b32_e32 v34, v65
	v_mov_b32_e32 v35, v65
	v_mov_b32_e32 v36, 0
	v_mov_b32_e32 v37, v65
	v_mov_b32_e32 v38, v65
	v_mov_b32_e32 v39, v65
	v_mov_b32_e32 v40, 0
	v_mov_b32_e32 v41, v65
	v_mov_b32_e32 v42, v65
	v_mov_b32_e32 v43, v65
	v_mov_b32_e32 v44, 0
	v_mov_b32_e32 v45, v65
	v_mov_b32_e32 v46, v65
	v_mov_b32_e32 v47, v65
	v_mov_b32_e32 v48, 0
	v_mov_b32_e32 v49, v65
	v_mov_b32_e32 v50, v65
	v_mov_b32_e32 v51, v65
	v_mov_b32_e32 v52, 0
	v_mov_b32_e32 v53, v65
	v_mov_b32_e32 v54, v65
	v_mov_b32_e32 v55, v65
	v_mov_b32_e32 v56, 0
	v_mov_b32_e32 v57, v65
	v_mov_b32_e32 v58, v65
	v_mov_b32_e32 v59, v65
	v_mov_b32_e32 v60, 0
	v_mov_b32_e32 v61, v65
	v_mov_b32_e32 v62, v65
	v_mov_b32_e32 v63, v65
	s_waitcnt lgkmcnt(0)
	s_barrier
	v_add3_u32 v182, 0, v134, v135
	v_add_u32_e32 v183, 0x4000, v182
	s_nop 0
	v_readfirstlane_b32 s82, v183
	s_nop 0
	v_readfirstlane_b32 s83, v182
	v_subrev_u32_e32 v184, s52, v90
	v_subrev_u32_e32 v185, s52, v92
	v_subrev_u32_e32 v186, s52, v94
	v_subrev_u32_e32 v187, s52, v96
	v_subrev_u32_e32 v188, s52, v98
	v_subrev_u32_e32 v189, s52, v100
	v_subrev_u32_e32 v190, s52, v102
	v_subrev_u32_e32 v191, s52, v104
	v_subrev_u32_e32 v187, 0x400, v187
	v_subrev_u32_e32 v186, 0x400, v186
	v_subrev_u32_e32 v189, 0x800, v189
	v_subrev_u32_e32 v188, 0x800, v188
	v_subrev_u32_e32 v191, 0xc00, v191
	v_subrev_u32_e32 v190, 0xc00, v190
	s_and_b32 s28, s26, 0x4000
	s_xor_b32 s27, s28, 0x4000
	s_lshl_b32 s27, s27, 1
	s_add_i32 s27, s27, 32
	s_lshl_b32 s28, s28, 1
	s_add_i32 s28, s28, 32

.LBB0_3471:
	s_ashr_i32 s8, s14, 31
	s_lshr_b32 s8, s8, 29
	s_add_i32 s8, s14, s8
	s_ashr_i32 s8, s8, 3
	s_add_i32 s9, s8, s16
	s_lshl_b32 s20, s8, 7
	s_lshl_b32 s8, s8, 10
	s_lshl_b32 s21, s14, 7
	s_sub_i32 s21, s21, s8
	s_lshr_b32 s9, s9, 4
	v_add_u32_e32 v0, s21, v104
	s_mulk_i32 s9, 0x900
	s_and_b32 s20, s20, 0x780
	v_ashrrev_i32_e32 v1, 31, v0
	v_add_u32_e32 v2, 0x4000, v105
	s_add_i32 s20, s20, s9
	v_lshlrev_b64 v[0:1], 13, v[0:1]
	v_readfirstlane_b32 s22, v2
	s_add_i32 s9, s20, 0x100
	v_lshl_add_u64 v[0:1], v[64:65], 0, v[0:1]
	s_mov_b32 m0, s22
	v_readfirstlane_b32 s22, v105
	global_load_lds_dwordx4 v[0:1], off
	v_add_u32_e32 v0, s9, v104
	v_ashrrev_i32_e32 v1, 31, v0
	v_lshlrev_b64 v[0:1], 13, v[0:1]
	v_lshl_add_u64 v[0:1], v[70:71], 0, v[0:1]
	s_mov_b32 m0, s22
	v_readfirstlane_b32 s22, v130
	global_load_lds_dwordx4 v[0:1], off
	v_add_u32_e32 v0, s21, v106
	v_ashrrev_i32_e32 v1, 31, v0
	v_lshlrev_b64 v[0:1], 13, v[0:1]
	v_lshl_add_u64 v[0:1], v[66:67], 0, v[0:1]
	s_mov_b32 m0, s22
	v_add_u32_e32 v2, 0x400, v105
	global_load_lds_dwordx4 v[0:1], off
	v_add_u32_e32 v0, s9, v106
	v_ashrrev_i32_e32 v1, 31, v0
	v_lshlrev_b64 v[0:1], 13, v[0:1]
	v_readfirstlane_b32 s22, v2
	v_lshl_add_u64 v[0:1], v[72:73], 0, v[0:1]
	s_mov_b32 m0, s22
	v_readfirstlane_b32 s22, v131
	global_load_lds_dwordx4 v[0:1], off
	v_add_u32_e32 v0, s21, v108
	v_ashrrev_i32_e32 v1, 31, v0
	v_lshlrev_b64 v[0:1], 13, v[0:1]
	v_lshl_add_u64 v[0:1], v[64:65], 0, v[0:1]
	s_mov_b32 m0, s22
	v_add_u32_e32 v2, 0x800, v105
	global_load_lds_dwordx4 v[0:1], off
	v_add_u32_e32 v0, s9, v108
	v_ashrrev_i32_e32 v1, 31, v0
	v_lshlrev_b64 v[0:1], 13, v[0:1]
	v_readfirstlane_b32 s22, v2
	v_lshl_add_u64 v[0:1], v[70:71], 0, v[0:1]
	s_mov_b32 m0, s22
	v_readfirstlane_b32 s22, v132
	global_load_lds_dwordx4 v[0:1], off
	v_add_u32_e32 v0, s21, v110
	v_ashrrev_i32_e32 v1, 31, v0
	v_lshlrev_b64 v[0:1], 13, v[0:1]
	v_lshl_add_u64 v[0:1], v[68:69], 0, v[0:1]
	s_mov_b32 m0, s22
	v_add_u32_e32 v2, 0xc00, v105
	global_load_lds_dwordx4 v[0:1], off
	v_add_u32_e32 v0, s9, v110
	v_ashrrev_i32_e32 v1, 31, v0
	v_lshlrev_b64 v[0:1], 13, v[0:1]
	v_readfirstlane_b32 s9, v2
	v_lshl_add_u64 v[0:1], v[74:75], 0, v[0:1]
	s_mov_b32 m0, s9
	s_mov_b32 s22, 0
	global_load_lds_dwordx4 v[0:1], off
	v_subrev_u32_e32 v0, s8, v120
	v_ashrrev_i32_e32 v1, 31, v0
	v_lshlrev_b64 v[0:1], 13, v[0:1]
	v_lshl_add_u64 v[88:89], v[76:77], 0, v[0:1]
	v_add_u32_e32 v0, s20, v121
	v_ashrrev_i32_e32 v1, 31, v0
	v_lshlrev_b64 v[0:1], 13, v[0:1]
	v_lshl_add_u64 v[90:91], v[78:79], 0, v[0:1]
	v_subrev_u32_e32 v0, s8, v122
	v_ashrrev_i32_e32 v1, 31, v0
	v_lshlrev_b64 v[0:1], 13, v[0:1]
	v_lshl_add_u64 v[92:93], v[80:81], 0, v[0:1]
	v_add_u32_e32 v0, s20, v123
	v_ashrrev_i32_e32 v1, 31, v0
	v_lshlrev_b64 v[0:1], 13, v[0:1]
	v_lshl_add_u64 v[94:95], v[82:83], 0, v[0:1]
	v_subrev_u32_e32 v0, s8, v124
	v_ashrrev_i32_e32 v1, 31, v0
	v_lshlrev_b64 v[0:1], 13, v[0:1]
	v_lshl_add_u64 v[96:97], v[76:77], 0, v[0:1]
	v_add_u32_e32 v0, s20, v125
	v_ashrrev_i32_e32 v1, 31, v0
	v_lshlrev_b64 v[0:1], 13, v[0:1]
	v_lshl_add_u64 v[98:99], v[78:79], 0, v[0:1]
	v_subrev_u32_e32 v0, s8, v126
	v_ashrrev_i32_e32 v1, 31, v0
	v_lshlrev_b64 v[0:1], 13, v[0:1]
	v_lshl_add_u64 v[100:101], v[84:85], 0, v[0:1]
	v_add_u32_e32 v0, s20, v127
	v_ashrrev_i32_e32 v1, 31, v0
	v_lshlrev_b64 v[0:1], 13, v[0:1]
	v_lshl_add_u64 v[102:103], v[86:87], 0, v[0:1]
	v_mov_b32_e32 v0, 0
	s_mov_b64 s[8:9], 0
	v_mov_b32_e32 v1, v0
	v_mov_b32_e32 v2, v0
	v_mov_b32_e32 v3, v0
	v_mov_b32_e32 v4, v0
	v_mov_b32_e32 v5, v0
	v_mov_b32_e32 v6, v0
	v_mov_b32_e32 v7, v0
	v_mov_b32_e32 v8, v0
	v_mov_b32_e32 v9, v0
	v_mov_b32_e32 v10, v0
	v_mov_b32_e32 v11, v0
	v_mov_b32_e32 v12, v0
	v_mov_b32_e32 v13, v0
	v_mov_b32_e32 v14, v0
	v_mov_b32_e32 v15, v0
	v_mov_b32_e32 v16, v0
	v_mov_b32_e32 v17, v0
	v_mov_b32_e32 v18, v0
	v_mov_b32_e32 v19, v0
	v_mov_b32_e32 v20, v0
	v_mov_b32_e32 v21, v0
	v_mov_b32_e32 v22, v0
	v_mov_b32_e32 v23, v0
	v_mov_b32_e32 v24, v0
	v_mov_b32_e32 v25, v0
	v_mov_b32_e32 v26, v0
	v_mov_b32_e32 v27, v0
	s_waitcnt vmcnt(0)
	v_mov_b32_e32 v28, v0
	v_mov_b32_e32 v29, v0
	v_mov_b32_e32 v30, v0
	v_mov_b32_e32 v31, v0
	v_mov_b32_e32 v32, v0
	v_mov_b32_e32 v33, v0
	v_mov_b32_e32 v34, v0
	v_mov_b32_e32 v35, v0
	v_mov_b32_e32 v36, v0
	v_mov_b32_e32 v37, v0
	v_mov_b32_e32 v38, v0
	v_mov_b32_e32 v39, v0
	v_mov_b32_e32 v40, v0
	v_mov_b32_e32 v41, v0
	v_mov_b32_e32 v42, v0
	v_mov_b32_e32 v43, v0
	v_mov_b32_e32 v44, v0
	v_mov_b32_e32 v45, v0
	v_mov_b32_e32 v46, v0
	v_mov_b32_e32 v47, v0
	v_mov_b32_e32 v48, v0
	v_mov_b32_e32 v49, v0
	v_mov_b32_e32 v50, v0
	v_mov_b32_e32 v51, v0
	v_mov_b32_e32 v52, v0
	v_mov_b32_e32 v53, v0
	v_mov_b32_e32 v54, v0
	v_mov_b32_e32 v55, v0
	v_mov_b32_e32 v56, v0
	v_mov_b32_e32 v57, v0
	v_mov_b32_e32 v58, v0
	v_mov_b32_e32 v59, v0
	v_mov_b32_e32 v60, v0
	v_mov_b32_e32 v61, v0
	v_mov_b32_e32 v62, v0
	v_mov_b32_e32 v63, v0
	s_waitcnt lgkmcnt(0)
	s_barrier
	v_add3_u32 v182, 0, v133, v134
	v_add_u32_e32 v183, 0x4000, v182
	s_nop 0
	v_readfirstlane_b32 s82, v183
	s_nop 0
	v_readfirstlane_b32 s83, v182
	v_subrev_u32_e32 v184, s52, v88
	v_subrev_u32_e32 v185, s52, v90
	v_subrev_u32_e32 v186, s52, v92
	v_subrev_u32_e32 v187, s52, v94
	v_subrev_u32_e32 v188, s52, v96
	v_subrev_u32_e32 v189, s52, v98
	v_subrev_u32_e32 v190, s52, v100
	v_subrev_u32_e32 v191, s52, v102
	v_subrev_u32_e32 v187, 0x400, v187
	v_subrev_u32_e32 v186, 0x400, v186
	v_subrev_u32_e32 v189, 0x800, v189
	v_subrev_u32_e32 v188, 0x800, v188
	v_subrev_u32_e32 v191, 0xc00, v191
	v_subrev_u32_e32 v190, 0xc00, v190
	s_and_b32 s24, s22, 0x4000
	s_xor_b32 s23, s24, 0x4000
	s_lshl_b32 s23, s23, 1
	s_add_i32 s23, s23, 32
	s_lshl_b32 s24, s24, 1
	s_add_i32 s24, s24, 32
